# GEMM K-loop micro edits: drop mid-block setprio pair, setprio before barrier, merged waits, drop s_nop between DMA blocks
# speedup vs baseline: 1.0042x; 1.0042x over previous
; #define PG8_STAGE(bufoff, gbase, voff) do { _Pragma("unroll") for (int _i = 0; _i < 2; ++_i) \
;         asm volatile("s_mov_b32 m0, %0\n\ts_nop 0\n\tglobal_load_lds_dwordx4 %1, %2" :: "s"(ldsb + (unsigned)((bufoff) + _i * 8192)), "v"((voff)[_i]), "s"(gbase) : "m0", "memory"); } while (0)
; #define PG8_LDA(dst, b, h) do { _Pragma("unroll") for (int m = 0; m < 4; ++m) _Pragma("unroll") for (int k = 0; k < 2; ++k) dst[m][k] = *(const PG8_LAS bf16x8*)(lds + PG8_SA(b, h) + aoff + m * 2048 + k * 1024); } while (0)
; #define PG8_WAIT_V(n) asm volatile("s_waitcnt vmcnt(" #n ")" ::: "memory")
; #define PG8_WAIT_L(n) asm volatile("s_waitcnt lgkmcnt(" #n ")" ::: "memory")
; template <class Epi, class Sched, bool ALIGN_EPI = false, bool SP2 = false>
; __device__ __forceinline__ void gemm_phase(PG8_LAS unsigned char* lds, const Gemm g, const Sched& S, const Epi& E, const int wv) {
;     ...
;         for (int t = 0; t < nt; t += 2) {
;             const bool last = (t == nt - 2);
;             const char* a1 = cA + (size_t)(t + 1) * kstep;
;             const char* a2 = last ? nA : cA + (size_t)(t + 2) * kstep; const char* b2 = last ? nB : cB + (size_t)(t + 2) * kstep;
;             const char* a3 = a2 + kstep; const char* b3 = b2 + kstep;
;             if (last && has_next) S.a_ready(nxt);
;             if constexpr (SP2) {
;             PG8_LDB(B0, 0, 0); PG8_LDB(B1, 0, 1); PG8_SCHED; PG8_LDA(At, 0, 0); PG8_STAGE(PG8_SA(1, 1), a1 + hstepA, voffA);
;             PG8_WAIT_V(8); PG8_WAIT_L(0); PG8_BAR; PG8_MMA(0, 0, At, B0); PG8_MMA(0, 1, At, B1); PG8_BAR; PG8_SCHED;
;             PG8_LDA(At, 0, 1); PG8_STAGE(PG8_SB(0, 0), b2, voffB); PG8_STAGE(PG8_SB(0, 1), b2 + hstepB, voffB); PG8_STAGE(PG8_SA(0, 0), a2, voffA);
;             PG8_WAIT_V(8); PG8_WAIT_L(0); PG8_BAR; PG8_MMA(1, 0, At, B0); PG8_MMA(1, 1, At, B1); PG8_BAR; PG8_SCHED;
;             PG8_LDB(B0, 1, 0); PG8_LDB(B1, 1, 1); PG8_SCHED; PG8_LDA(At, 1, 0); PG8_STAGE(PG8_SA(0, 1), a2 + hstepA, voffA);
;             PG8_WAIT_V(8); PG8_WAIT_L(0); PG8_BAR; PG8_MMA(0, 0, At, B0); PG8_MMA(0, 1, At, B1); PG8_BAR; PG8_SCHED;
;             PG8_LDA(At, 1, 1); PG8_STAGE(PG8_SB(1, 0), b3, voffB); PG8_STAGE(PG8_SB(1, 1), b3 + hstepB, voffB); PG8_STAGE(PG8_SA(1, 0), a3, voffA);
;             PG8_WAIT_V(8); PG8_WAIT_L(0); PG8_BAR; PG8_MMA(1, 0, At, B0); PG8_MMA(1, 1, At, B1); PG8_BAR; PG8_SCHED;
.LBB0_268:
	ds_read_b128 v[80:83], v161
	ds_read_b128 v[84:87], v161 offset:1024
	ds_read_b128 v[88:91], v161 offset:2048
	ds_read_b128 v[92:95], v161 offset:3072
	ds_read_b128 v[166:169], v162
	ds_read_b128 v[170:173], v162 offset:1024
	ds_read_b128 v[174:177], v162 offset:2048
	ds_read_b128 v[178:181], v162 offset:3072
	s_add_i32 s84, s18, 2
	s_cmp_eq_u32 s71, s18
	s_cselect_b32 s22, s12, s72
	s_cselect_b32 s23, s13, s77
	s_cselect_b32 s20, s65, s79
	s_cselect_b32 s21, s62, s83
	s_add_u32 s18, s22, 0x80
	s_addc_u32 s19, s23, 0
	ds_read_b128 v[182:185], v163
	ds_read_b128 v[186:189], v163 offset:1024
	ds_read_b128 v[194:197], v163 offset:2048
	ds_read_b128 v[198:201], v163 offset:3072
	ds_read_b128 v[202:205], v163 offset:4096
	ds_read_b128 v[206:209], v163 offset:5120
	ds_read_b128 v[210:213], v163 offset:6144
	ds_read_b128 v[214:217], v163 offset:7168
	s_add_u32 s86, s72, 0x83f80
	s_addc_u32 s87, s77, 0
	s_mov_b32 m0, s51
	s_nop 0
	global_load_lds_dwordx4 v147, s[86:87]
	s_mov_b32 m0, s52
	s_nop 0
	global_load_lds_dwordx4 v151, s[86:87]
	s_waitcnt vmcnt(8) lgkmcnt(0)
	s_setprio 1
	s_barrier
	v_mfma_f32_16x16x32_bf16 v[140:143], v[80:83], v[182:185], v[140:143]
	v_mfma_f32_16x16x32_bf16 v[136:139], v[88:91], v[182:185], v[136:139]
	v_mfma_f32_16x16x32_bf16 v[124:127], v[80:83], v[194:197], v[124:127]
	v_mfma_f32_16x16x32_bf16 v[120:123], v[88:91], v[194:197], v[120:123]
	v_mfma_f32_16x16x32_bf16 v[108:111], v[80:83], v[202:205], v[108:111]
	v_mfma_f32_16x16x32_bf16 v[104:107], v[88:91], v[202:205], v[104:107]
	v_mfma_f32_16x16x32_bf16 v[76:79], v[80:83], v[210:213], v[76:79]
	v_mfma_f32_16x16x32_bf16 v[72:75], v[88:91], v[210:213], v[72:75]
	v_mfma_f32_16x16x32_bf16 v[140:143], v[84:87], v[186:189], v[140:143]
	v_mfma_f32_16x16x32_bf16 v[136:139], v[92:95], v[186:189], v[136:139]
	v_mfma_f32_16x16x32_bf16 v[124:127], v[84:87], v[198:201], v[124:127]
	v_mfma_f32_16x16x32_bf16 v[120:123], v[92:95], v[198:201], v[120:123]
	v_mfma_f32_16x16x32_bf16 v[108:111], v[84:87], v[206:209], v[108:111]
	v_mfma_f32_16x16x32_bf16 v[104:107], v[92:95], v[206:209], v[104:107]
	v_mfma_f32_16x16x32_bf16 v[76:79], v[84:87], v[214:217], v[76:79]
	v_mfma_f32_16x16x32_bf16 v[72:75], v[92:95], v[214:217], v[72:75]
	v_mfma_f32_16x16x32_bf16 v[132:135], v[166:169], v[182:185], v[132:135]
	v_mfma_f32_16x16x32_bf16 v[128:131], v[174:177], v[182:185], v[128:131]
	v_mfma_f32_16x16x32_bf16 v[116:119], v[166:169], v[194:197], v[116:119]
	v_mfma_f32_16x16x32_bf16 v[112:115], v[174:177], v[194:197], v[112:115]
	v_mfma_f32_16x16x32_bf16 v[100:103], v[166:169], v[202:205], v[100:103]
	v_mfma_f32_16x16x32_bf16 v[96:99], v[174:177], v[202:205], v[96:99]
	v_mfma_f32_16x16x32_bf16 v[68:71], v[166:169], v[210:213], v[68:71]
	v_mfma_f32_16x16x32_bf16 v[64:67], v[174:177], v[210:213], v[64:67]
	v_mfma_f32_16x16x32_bf16 v[132:135], v[170:173], v[186:189], v[132:135]
	v_mfma_f32_16x16x32_bf16 v[128:131], v[178:181], v[186:189], v[128:131]
	v_mfma_f32_16x16x32_bf16 v[116:119], v[170:173], v[198:201], v[116:119]
	v_mfma_f32_16x16x32_bf16 v[112:115], v[178:181], v[198:201], v[112:115]
	v_mfma_f32_16x16x32_bf16 v[100:103], v[170:173], v[206:209], v[100:103]
	v_mfma_f32_16x16x32_bf16 v[96:99], v[178:181], v[206:209], v[96:99]
	v_mfma_f32_16x16x32_bf16 v[68:71], v[170:173], v[214:217], v[68:71]
	v_mfma_f32_16x16x32_bf16 v[64:67], v[178:181], v[214:217], v[64:67]
	s_setprio 0
	s_barrier
	ds_read_b128 v[182:185], v163 offset:16384
	ds_read_b128 v[186:189], v163 offset:17408
	ds_read_b128 v[194:197], v163 offset:18432
	ds_read_b128 v[198:201], v163 offset:19456
	ds_read_b128 v[202:205], v163 offset:20480
	ds_read_b128 v[206:209], v163 offset:21504
	ds_read_b128 v[210:213], v163 offset:22528
	ds_read_b128 v[214:217], v163 offset:23552
	s_mov_b32 m0, s29
	s_nop 0
	global_load_lds_dwordx4 v149, s[20:21]
	s_add_u32 s86, s20, 0x80000
	s_mov_b32 m0, s30
	s_nop 0
	global_load_lds_dwordx4 v153, s[20:21]
	s_addc_u32 s87, s21, 0
	s_mov_b32 m0, s31
	s_nop 0
	global_load_lds_dwordx4 v149, s[86:87]
	s_mov_b32 m0, s33
	s_nop 0
	global_load_lds_dwordx4 v153, s[86:87]
	s_mov_b32 m0, s28
	s_nop 0
	global_load_lds_dwordx4 v147, s[22:23]
	s_mov_b32 m0, s34
	s_nop 0
	global_load_lds_dwordx4 v151, s[22:23]
	s_waitcnt vmcnt(8) lgkmcnt(0)
	s_setprio 1
	s_barrier
	v_mfma_f32_16x16x32_bf16 v[60:63], v[80:83], v[182:185], v[60:63]
	v_mfma_f32_16x16x32_bf16 v[56:59], v[88:91], v[182:185], v[56:59]
	v_mfma_f32_16x16x32_bf16 v[44:47], v[80:83], v[194:197], v[44:47]
	v_mfma_f32_16x16x32_bf16 v[40:43], v[88:91], v[194:197], v[40:43]
	v_mfma_f32_16x16x32_bf16 v[28:31], v[80:83], v[202:205], v[28:31]
	v_mfma_f32_16x16x32_bf16 v[24:27], v[88:91], v[202:205], v[24:27]
	v_mfma_f32_16x16x32_bf16 v[12:15], v[80:83], v[210:213], v[12:15]
	v_mfma_f32_16x16x32_bf16 v[8:11], v[88:91], v[210:213], v[8:11]
	v_mfma_f32_16x16x32_bf16 v[60:63], v[84:87], v[186:189], v[60:63]
	v_mfma_f32_16x16x32_bf16 v[56:59], v[92:95], v[186:189], v[56:59]
	v_mfma_f32_16x16x32_bf16 v[44:47], v[84:87], v[198:201], v[44:47]
	v_mfma_f32_16x16x32_bf16 v[40:43], v[92:95], v[198:201], v[40:43]
	v_mfma_f32_16x16x32_bf16 v[28:31], v[84:87], v[206:209], v[28:31]
	v_mfma_f32_16x16x32_bf16 v[24:27], v[92:95], v[206:209], v[24:27]
	v_mfma_f32_16x16x32_bf16 v[12:15], v[84:87], v[214:217], v[12:15]
	v_mfma_f32_16x16x32_bf16 v[8:11], v[92:95], v[214:217], v[8:11]
	v_mfma_f32_16x16x32_bf16 v[52:55], v[166:169], v[182:185], v[52:55]
	v_mfma_f32_16x16x32_bf16 v[48:51], v[174:177], v[182:185], v[48:51]
	v_mfma_f32_16x16x32_bf16 v[36:39], v[166:169], v[194:197], v[36:39]
	v_mfma_f32_16x16x32_bf16 v[32:35], v[174:177], v[194:197], v[32:35]
	v_mfma_f32_16x16x32_bf16 v[20:23], v[166:169], v[202:205], v[20:23]
	v_mfma_f32_16x16x32_bf16 v[16:19], v[174:177], v[202:205], v[16:19]
	v_mfma_f32_16x16x32_bf16 v[4:7], v[166:169], v[210:213], v[4:7]
	v_mfma_f32_16x16x32_bf16 v[0:3], v[174:177], v[210:213], v[0:3]
	v_mfma_f32_16x16x32_bf16 v[52:55], v[170:173], v[186:189], v[52:55]
	v_mfma_f32_16x16x32_bf16 v[48:51], v[178:181], v[186:189], v[48:51]
	v_mfma_f32_16x16x32_bf16 v[36:39], v[170:173], v[198:201], v[36:39]
	v_mfma_f32_16x16x32_bf16 v[32:35], v[178:181], v[198:201], v[32:35]
	v_mfma_f32_16x16x32_bf16 v[20:23], v[170:173], v[206:209], v[20:23]
	v_mfma_f32_16x16x32_bf16 v[16:19], v[178:181], v[206:209], v[16:19]
	v_mfma_f32_16x16x32_bf16 v[4:7], v[170:173], v[214:217], v[4:7]
	v_mfma_f32_16x16x32_bf16 v[0:3], v[178:181], v[214:217], v[0:3]
	s_setprio 0
	s_barrier
; #define PG8_STAGE(bufoff, gbase, voff) do { _Pragma("unroll") for (int _i = 0; _i < 2; ++_i) \
;         asm volatile("s_mov_b32 m0, %0\n\ts_nop 0\n\tglobal_load_lds_dwordx4 %1, %2" :: "s"(ldsb + (unsigned)((bufoff) + _i * 8192)), "v"((voff)[_i]), "s"(gbase) : "m0", "memory"); } while (0)
; #define PG8_LDA(dst, b, h) do { _Pragma("unroll") for (int m = 0; m < 4; ++m) _Pragma("unroll") for (int k = 0; k < 2; ++k) dst[m][k] = *(const PG8_LAS bf16x8*)(lds + PG8_SA(b, h) + aoff + m * 2048 + k * 1024); } while (0)
; #define PG8_LDB(dst, b, h) do { _Pragma("unroll") for (int n = 0; n < 2; ++n) _Pragma("unroll") for (int k = 0; k < 2; ++k) dst[n][k] = *(const PG8_LAS bf16x8*)(lds + PG8_SB(b, h) + boff + n * 2048 + k * 1024); } while (0)
; #define PG8_MMA(ai, bj, At, Bt) do { __builtin_amdgcn_s_setprio(1); _Pragma("unroll") for (int m = 0; m < 4; ++m) _Pragma("unroll") for (int n = 0; n < 2; ++n) _Pragma("unroll") for (int k = 0; k < 2; ++k) \
;         acc[ai][bj][m][n] = __builtin_amdgcn_mfma_f32_16x16x32_bf16(Bt[n][k], At[m][k], acc[ai][bj][m][n], 0, 0, 0); __builtin_amdgcn_s_setprio(0); } while (0)
; #define PG8_WAIT_V(n) asm volatile("s_waitcnt vmcnt(" #n ")" ::: "memory")
; #define PG8_WAIT_L(n) asm volatile("s_waitcnt lgkmcnt(" #n ")" ::: "memory")
; #define PG8_BAR __builtin_amdgcn_s_barrier()
; #define PG8_SCHED __builtin_amdgcn_sched_barrier(0)
; template <class Epi, class Sched, bool ALIGN_EPI = false, bool SP2 = false>
; __device__ __forceinline__ void gemm_phase(PG8_LAS unsigned char* lds, const Gemm g, const Sched& S, const Epi& E, const int wv) {
;     ...
;         for (int t = 0; t < nt; t += 2) {
;     ...
;             PG8_LDB(B0, 1, 0); PG8_LDB(B1, 1, 1); PG8_SCHED; PG8_LDA(At, 1, 0); PG8_STAGE(PG8_SA(0, 1), a2 + hstepA, voffA);
;             PG8_WAIT_V(8); PG8_WAIT_L(0); PG8_BAR; PG8_MMA(0, 0, At, B0); PG8_MMA(0, 1, At, B1); PG8_BAR; PG8_SCHED;
;             PG8_LDA(At, 1, 1); PG8_STAGE(PG8_SB(1, 0), b3, voffB); PG8_STAGE(PG8_SB(1, 1), b3 + hstepB, voffB); PG8_STAGE(PG8_SA(1, 0), a3, voffA);
;             PG8_WAIT_V(8); PG8_WAIT_L(0); PG8_BAR; PG8_MMA(1, 0, At, B0); PG8_MMA(1, 1, At, B1); PG8_BAR; PG8_SCHED;
	v_add_u32_e32 v92, 0x18000, v160
	v_add_u32_e32 v144, 0x1c000, v160
	ds_read_b128 v[80:83], v92
	ds_read_b128 v[84:87], v92 offset:1024
	ds_read_b128 v[88:91], v92 offset:2048
	ds_read_b128 v[92:95], v92 offset:3072
	ds_read_b128 v[166:169], v144
	ds_read_b128 v[170:173], v144 offset:1024
	ds_read_b128 v[174:177], v144 offset:2048
	ds_read_b128 v[178:181], v144 offset:3072
	ds_read_b128 v[182:185], v163 offset:32768
	ds_read_b128 v[186:189], v163 offset:33792
	ds_read_b128 v[194:197], v163 offset:34816
	ds_read_b128 v[198:201], v163 offset:35840
	ds_read_b128 v[202:205], v163 offset:36864
	ds_read_b128 v[206:209], v163 offset:37888
	ds_read_b128 v[210:213], v163 offset:38912
	ds_read_b128 v[214:217], v163 offset:39936
	s_add_u32 s22, s22, 0x84000
	s_addc_u32 s23, s23, 0
	s_mov_b32 m0, s35
	s_nop 0
	global_load_lds_dwordx4 v147, s[22:23]
	s_mov_b32 m0, s36
	s_nop 0
	global_load_lds_dwordx4 v151, s[22:23]
	s_waitcnt vmcnt(8) lgkmcnt(0)
	s_setprio 1
	s_barrier
	v_mfma_f32_16x16x32_bf16 v[140:143], v[80:83], v[182:185], v[140:143]
	v_mfma_f32_16x16x32_bf16 v[136:139], v[88:91], v[182:185], v[136:139]
	v_mfma_f32_16x16x32_bf16 v[124:127], v[80:83], v[194:197], v[124:127]
	v_mfma_f32_16x16x32_bf16 v[120:123], v[88:91], v[194:197], v[120:123]
	v_mfma_f32_16x16x32_bf16 v[108:111], v[80:83], v[202:205], v[108:111]
	v_mfma_f32_16x16x32_bf16 v[104:107], v[88:91], v[202:205], v[104:107]
	v_mfma_f32_16x16x32_bf16 v[76:79], v[80:83], v[210:213], v[76:79]
	v_mfma_f32_16x16x32_bf16 v[72:75], v[88:91], v[210:213], v[72:75]
	v_mfma_f32_16x16x32_bf16 v[140:143], v[84:87], v[186:189], v[140:143]
	v_mfma_f32_16x16x32_bf16 v[136:139], v[92:95], v[186:189], v[136:139]
	v_mfma_f32_16x16x32_bf16 v[124:127], v[84:87], v[198:201], v[124:127]
	v_mfma_f32_16x16x32_bf16 v[120:123], v[92:95], v[198:201], v[120:123]
	v_mfma_f32_16x16x32_bf16 v[108:111], v[84:87], v[206:209], v[108:111]
	v_mfma_f32_16x16x32_bf16 v[104:107], v[92:95], v[206:209], v[104:107]
	v_mfma_f32_16x16x32_bf16 v[76:79], v[84:87], v[214:217], v[76:79]
	v_mfma_f32_16x16x32_bf16 v[72:75], v[92:95], v[214:217], v[72:75]
	v_mfma_f32_16x16x32_bf16 v[132:135], v[166:169], v[182:185], v[132:135]
	v_mfma_f32_16x16x32_bf16 v[128:131], v[174:177], v[182:185], v[128:131]
	v_mfma_f32_16x16x32_bf16 v[116:119], v[166:169], v[194:197], v[116:119]
	v_mfma_f32_16x16x32_bf16 v[112:115], v[174:177], v[194:197], v[112:115]
	v_mfma_f32_16x16x32_bf16 v[100:103], v[166:169], v[202:205], v[100:103]
	v_mfma_f32_16x16x32_bf16 v[96:99], v[174:177], v[202:205], v[96:99]
	v_mfma_f32_16x16x32_bf16 v[68:71], v[166:169], v[210:213], v[68:71]
	v_mfma_f32_16x16x32_bf16 v[64:67], v[174:177], v[210:213], v[64:67]
	v_mfma_f32_16x16x32_bf16 v[132:135], v[170:173], v[186:189], v[132:135]
	v_mfma_f32_16x16x32_bf16 v[128:131], v[178:181], v[186:189], v[128:131]
	v_mfma_f32_16x16x32_bf16 v[116:119], v[170:173], v[198:201], v[116:119]
	v_mfma_f32_16x16x32_bf16 v[112:115], v[178:181], v[198:201], v[112:115]
	v_mfma_f32_16x16x32_bf16 v[100:103], v[170:173], v[206:209], v[100:103]
	v_mfma_f32_16x16x32_bf16 v[96:99], v[178:181], v[206:209], v[96:99]
	v_mfma_f32_16x16x32_bf16 v[68:71], v[170:173], v[214:217], v[68:71]
	v_mfma_f32_16x16x32_bf16 v[64:67], v[178:181], v[214:217], v[64:67]
	s_setprio 0
	s_barrier
	ds_read_b128 v[182:185], v163 offset:49152
	ds_read_b128 v[186:189], v163 offset:50176
	ds_read_b128 v[194:197], v163 offset:51200
	ds_read_b128 v[198:201], v163 offset:52224
	ds_read_b128 v[202:205], v163 offset:53248
	ds_read_b128 v[206:209], v163 offset:54272
	ds_read_b128 v[210:213], v163 offset:55296
	ds_read_b128 v[214:217], v163 offset:56320
	s_add_u32 s22, s20, 0x80
	s_addc_u32 s23, s21, 0
	s_mov_b32 m0, s45
	s_nop 0
	global_load_lds_dwordx4 v149, s[22:23]
	s_add_u32 s20, s20, 0x80080
	s_mov_b32 m0, s46
	s_nop 0
	global_load_lds_dwordx4 v153, s[22:23]
	s_addc_u32 s21, s21, 0
	s_mov_b32 m0, s49
	s_nop 0
	global_load_lds_dwordx4 v149, s[20:21]
	s_mov_b32 m0, s50
	s_nop 0
	global_load_lds_dwordx4 v153, s[20:21]
	s_mov_b32 m0, s47
	s_nop 0
	global_load_lds_dwordx4 v147, s[18:19]
	s_mov_b32 m0, s48
	s_nop 0
	global_load_lds_dwordx4 v151, s[18:19]
	s_waitcnt vmcnt(8) lgkmcnt(0)
	s_setprio 1
	s_barrier
	v_mfma_f32_16x16x32_bf16 v[60:63], v[80:83], v[182:185], v[60:63]
	v_mfma_f32_16x16x32_bf16 v[56:59], v[88:91], v[182:185], v[56:59]
	v_mfma_f32_16x16x32_bf16 v[44:47], v[80:83], v[194:197], v[44:47]
	v_mfma_f32_16x16x32_bf16 v[40:43], v[88:91], v[194:197], v[40:43]
	v_mfma_f32_16x16x32_bf16 v[28:31], v[80:83], v[202:205], v[28:31]
	v_mfma_f32_16x16x32_bf16 v[24:27], v[88:91], v[202:205], v[24:27]
	v_mfma_f32_16x16x32_bf16 v[12:15], v[80:83], v[210:213], v[12:15]
	v_mfma_f32_16x16x32_bf16 v[8:11], v[88:91], v[210:213], v[8:11]
	v_mfma_f32_16x16x32_bf16 v[60:63], v[84:87], v[186:189], v[60:63]
	v_mfma_f32_16x16x32_bf16 v[56:59], v[92:95], v[186:189], v[56:59]
	v_mfma_f32_16x16x32_bf16 v[44:47], v[84:87], v[198:201], v[44:47]
	v_mfma_f32_16x16x32_bf16 v[40:43], v[92:95], v[198:201], v[40:43]
	v_mfma_f32_16x16x32_bf16 v[28:31], v[84:87], v[206:209], v[28:31]
	v_mfma_f32_16x16x32_bf16 v[24:27], v[92:95], v[206:209], v[24:27]
	v_mfma_f32_16x16x32_bf16 v[12:15], v[84:87], v[214:217], v[12:15]
	v_mfma_f32_16x16x32_bf16 v[8:11], v[92:95], v[214:217], v[8:11]
	v_mfma_f32_16x16x32_bf16 v[52:55], v[166:169], v[182:185], v[52:55]
	v_mfma_f32_16x16x32_bf16 v[48:51], v[174:177], v[182:185], v[48:51]
	v_mfma_f32_16x16x32_bf16 v[36:39], v[166:169], v[194:197], v[36:39]
	v_mfma_f32_16x16x32_bf16 v[32:35], v[174:177], v[194:197], v[32:35]
	v_mfma_f32_16x16x32_bf16 v[20:23], v[166:169], v[202:205], v[20:23]
	v_mfma_f32_16x16x32_bf16 v[16:19], v[174:177], v[202:205], v[16:19]
	v_mfma_f32_16x16x32_bf16 v[4:7], v[166:169], v[210:213], v[4:7]
	v_mfma_f32_16x16x32_bf16 v[0:3], v[174:177], v[210:213], v[0:3]
	v_mfma_f32_16x16x32_bf16 v[52:55], v[170:173], v[186:189], v[52:55]
	v_mfma_f32_16x16x32_bf16 v[48:51], v[178:181], v[186:189], v[48:51]
	v_mfma_f32_16x16x32_bf16 v[36:39], v[170:173], v[198:201], v[36:39]
	v_mfma_f32_16x16x32_bf16 v[32:35], v[178:181], v[198:201], v[32:35]
	v_mfma_f32_16x16x32_bf16 v[20:23], v[170:173], v[206:209], v[20:23]
	v_mfma_f32_16x16x32_bf16 v[16:19], v[178:181], v[206:209], v[16:19]
	v_mfma_f32_16x16x32_bf16 v[4:7], v[170:173], v[214:217], v[4:7]
	v_mfma_f32_16x16x32_bf16 v[0:3], v[178:181], v[214:217], v[0:3]
	s_setprio 0
	s_barrier
	s_add_u32 s72, s72, 0x100
	s_addc_u32 s77, s77, 0
	s_add_u32 s79, s79, 0x100
	s_addc_u32 s83, s83, 0
	s_cmp_ge_i32 s84, s40
	s_mov_b32 s18, s84
	s_cbranch_scc0 .LBB0_268
	s_mov_b32 s79, 0xc00000
	s_and_b64 vcc, exec, s[10:11]
	s_cbranch_vccz .LBB0_271

; #define PG8_STAGE(bufoff, gbase, voff) do { _Pragma("unroll") for (int _i = 0; _i < 2; ++_i) \
;         asm volatile("s_mov_b32 m0, %0\n\ts_nop 0\n\tglobal_load_lds_dwordx4 %1, %2" :: "s"(ldsb + (unsigned)((bufoff) + _i * 8192)), "v"((voff)[_i]), "s"(gbase) : "m0", "memory"); } while (0)
; #define PG8_LDA(dst, b, h) do { _Pragma("unroll") for (int m = 0; m < 4; ++m) _Pragma("unroll") for (int k = 0; k < 2; ++k) dst[m][k] = *(const PG8_LAS bf16x8*)(lds + PG8_SA(b, h) + aoff + m * 2048 + k * 1024); } while (0)
; #define PG8_WAIT_V(n) asm volatile("s_waitcnt vmcnt(" #n ")" ::: "memory")
; #define PG8_WAIT_L(n) asm volatile("s_waitcnt lgkmcnt(" #n ")" ::: "memory")
; template <class Epi, class Sched, bool ALIGN_EPI = false, bool SP2 = false>
; __device__ __forceinline__ void gemm_phase(PG8_LAS unsigned char* lds, const Gemm g, const Sched& S, const Epi& E, const int wv) {
;     ...
;         for (int t = 0; t < nt; t += 2) {
;             const bool last = (t == nt - 2);
;             const char* a1 = cA + (size_t)(t + 1) * kstep;
;             const char* a2 = last ? nA : cA + (size_t)(t + 2) * kstep; const char* b2 = last ? nB : cB + (size_t)(t + 2) * kstep;
;             const char* a3 = a2 + kstep; const char* b3 = b2 + kstep;
;             if (last && has_next) S.a_ready(nxt);
;             if constexpr (SP2) {
;             PG8_LDB(B0, 0, 0); PG8_LDB(B1, 0, 1); PG8_SCHED; PG8_LDA(At, 0, 0); PG8_STAGE(PG8_SA(1, 1), a1 + hstepA, voffA);
;             PG8_WAIT_V(8); PG8_WAIT_L(0); PG8_BAR; PG8_MMA(0, 0, At, B0); PG8_MMA(0, 1, At, B1); PG8_BAR; PG8_SCHED;
;             PG8_LDA(At, 0, 1); PG8_STAGE(PG8_SB(0, 0), b2, voffB); PG8_STAGE(PG8_SB(0, 1), b2 + hstepB, voffB); PG8_STAGE(PG8_SA(0, 0), a2, voffA);
;             PG8_WAIT_V(8); PG8_WAIT_L(0); PG8_BAR; PG8_MMA(1, 0, At, B0); PG8_MMA(1, 1, At, B1); PG8_BAR; PG8_SCHED;
;             PG8_LDB(B0, 1, 0); PG8_LDB(B1, 1, 1); PG8_SCHED; PG8_LDA(At, 1, 0); PG8_STAGE(PG8_SA(0, 1), a2 + hstepA, voffA);
;             PG8_WAIT_V(8); PG8_WAIT_L(0); PG8_BAR; PG8_MMA(0, 0, At, B0); PG8_MMA(0, 1, At, B1); PG8_BAR; PG8_SCHED;
;             PG8_LDA(At, 1, 1); PG8_STAGE(PG8_SB(1, 0), b3, voffB); PG8_STAGE(PG8_SB(1, 1), b3 + hstepB, voffB); PG8_STAGE(PG8_SA(1, 0), a3, voffA);
;             PG8_WAIT_V(8); PG8_WAIT_L(0); PG8_BAR; PG8_MMA(1, 0, At, B0); PG8_MMA(1, 1, At, B1); PG8_BAR; PG8_SCHED;
.LBB0_343:
	v_add_u32_e32 v140, 0x10000, v220
	v_add_u32_e32 v159, 0x14000, v220
	ds_read_b128 v[128:131], v140
	ds_read_b128 v[132:135], v140 offset:1024
	ds_read_b128 v[136:139], v140 offset:2048
	ds_read_b128 v[140:143], v140 offset:3072
	ds_read_b128 v[144:147], v159
	ds_read_b128 v[148:151], v159 offset:1024
	ds_read_b128 v[152:155], v159 offset:2048
	ds_read_b128 v[160:163], v159 offset:3072
	s_add_i32 s62, s30, 2
	s_cmp_eq_u32 s23, s30
	s_cselect_b32 s36, s24, s85
	s_cselect_b32 s37, s25, vcc_lo
	s_cselect_b32 s34, s26, vcc_hi
	s_cselect_b32 s35, s27, s79
	s_add_u32 s30, s36, 0x80
	s_addc_u32 s31, s37, 0
	ds_read_b128 v[164:167], v221
	ds_read_b128 v[168:171], v221 offset:1024
	ds_read_b128 v[172:175], v221 offset:2048
	ds_read_b128 v[176:179], v221 offset:3072
	ds_read_b128 v[180:183], v221 offset:4096
	ds_read_b128 v[184:187], v221 offset:5120
	ds_read_b128 v[188:191], v221 offset:6144
	ds_read_b128 v[194:197], v221 offset:7168
	s_mov_b32 m0, s93
	s_nop 0
	global_load_lds_dwordx4 v208, s[28:29]
	s_mov_b32 m0, s58
	s_nop 0
	global_load_lds_dwordx4 v210, s[28:29]
	s_waitcnt vmcnt(8) lgkmcnt(0)
	s_setprio 1
	s_barrier
	v_mfma_f32_16x16x32_bf16 v[124:127], v[128:131], v[164:167], v[124:127]
	v_mfma_f32_16x16x32_bf16 v[120:123], v[136:139], v[164:167], v[120:123]
	v_mfma_f32_16x16x32_bf16 v[108:111], v[128:131], v[172:175], v[108:111]
	v_mfma_f32_16x16x32_bf16 v[104:107], v[136:139], v[172:175], v[104:107]
	v_mfma_f32_16x16x32_bf16 v[92:95], v[128:131], v[180:183], v[92:95]
	v_mfma_f32_16x16x32_bf16 v[88:91], v[136:139], v[180:183], v[88:91]
	v_mfma_f32_16x16x32_bf16 v[76:79], v[128:131], v[188:191], v[76:79]
	v_mfma_f32_16x16x32_bf16 v[72:75], v[136:139], v[188:191], v[72:75]
	v_mfma_f32_16x16x32_bf16 v[124:127], v[132:135], v[168:171], v[124:127]
	v_mfma_f32_16x16x32_bf16 v[120:123], v[140:143], v[168:171], v[120:123]
	v_mfma_f32_16x16x32_bf16 v[108:111], v[132:135], v[176:179], v[108:111]
	v_mfma_f32_16x16x32_bf16 v[104:107], v[140:143], v[176:179], v[104:107]
	v_mfma_f32_16x16x32_bf16 v[92:95], v[132:135], v[184:187], v[92:95]
	v_mfma_f32_16x16x32_bf16 v[88:91], v[140:143], v[184:187], v[88:91]
	v_mfma_f32_16x16x32_bf16 v[76:79], v[132:135], v[194:197], v[76:79]
	v_mfma_f32_16x16x32_bf16 v[72:75], v[140:143], v[194:197], v[72:75]
	v_mfma_f32_16x16x32_bf16 v[116:119], v[144:147], v[164:167], v[116:119]
	v_mfma_f32_16x16x32_bf16 v[112:115], v[152:155], v[164:167], v[112:115]
	v_mfma_f32_16x16x32_bf16 v[100:103], v[144:147], v[172:175], v[100:103]
	v_mfma_f32_16x16x32_bf16 v[96:99], v[152:155], v[172:175], v[96:99]
	v_mfma_f32_16x16x32_bf16 v[84:87], v[144:147], v[180:183], v[84:87]
	v_mfma_f32_16x16x32_bf16 v[80:83], v[152:155], v[180:183], v[80:83]
	v_mfma_f32_16x16x32_bf16 v[68:71], v[144:147], v[188:191], v[68:71]
	v_mfma_f32_16x16x32_bf16 v[64:67], v[152:155], v[188:191], v[64:67]
	v_mfma_f32_16x16x32_bf16 v[116:119], v[148:151], v[168:171], v[116:119]
	v_mfma_f32_16x16x32_bf16 v[112:115], v[160:163], v[168:171], v[112:115]
	v_mfma_f32_16x16x32_bf16 v[100:103], v[148:151], v[176:179], v[100:103]
	v_mfma_f32_16x16x32_bf16 v[96:99], v[160:163], v[176:179], v[96:99]
	v_mfma_f32_16x16x32_bf16 v[84:87], v[148:151], v[184:187], v[84:87]
	v_mfma_f32_16x16x32_bf16 v[80:83], v[160:163], v[184:187], v[80:83]
	v_mfma_f32_16x16x32_bf16 v[68:71], v[148:151], v[194:197], v[68:71]
	v_mfma_f32_16x16x32_bf16 v[64:67], v[160:163], v[194:197], v[64:67]
	s_setprio 0
	s_barrier
	ds_read_b128 v[164:167], v221 offset:16384
	ds_read_b128 v[168:171], v221 offset:17408
	ds_read_b128 v[172:175], v221 offset:18432
	ds_read_b128 v[176:179], v221 offset:19456
	ds_read_b128 v[180:183], v221 offset:20480
	ds_read_b128 v[184:187], v221 offset:21504
	ds_read_b128 v[188:191], v221 offset:22528
	ds_read_b128 v[194:197], v221 offset:23552
	s_mov_b32 m0, s47
	s_nop 0
	global_load_lds_dwordx4 v209, s[34:35]
	s_add_u32 s8, s34, 0x160000
	s_mov_b32 m0, s48
	s_nop 0
	global_load_lds_dwordx4 v211, s[34:35]
	s_addc_u32 s9, s35, 0
	s_mov_b32 m0, s49
	s_nop 0
	global_load_lds_dwordx4 v209, s[8:9]
	s_mov_b32 m0, s50
	s_nop 0
	global_load_lds_dwordx4 v211, s[8:9]
	s_mov_b32 m0, s46
	s_nop 0
	global_load_lds_dwordx4 v208, s[36:37]
	s_mov_b32 m0, s51
	s_nop 0
	global_load_lds_dwordx4 v210, s[36:37]
	s_waitcnt vmcnt(8) lgkmcnt(0)
	s_setprio 1
	s_barrier
	v_mfma_f32_16x16x32_bf16 v[60:63], v[128:131], v[164:167], v[60:63]
	v_mfma_f32_16x16x32_bf16 v[56:59], v[136:139], v[164:167], v[56:59]
	v_mfma_f32_16x16x32_bf16 v[44:47], v[128:131], v[172:175], v[44:47]
	v_mfma_f32_16x16x32_bf16 v[40:43], v[136:139], v[172:175], v[40:43]
	v_mfma_f32_16x16x32_bf16 v[28:31], v[128:131], v[180:183], v[28:31]
	v_mfma_f32_16x16x32_bf16 v[24:27], v[136:139], v[180:183], v[24:27]
	v_mfma_f32_16x16x32_bf16 v[12:15], v[128:131], v[188:191], v[12:15]
	v_mfma_f32_16x16x32_bf16 v[8:11], v[136:139], v[188:191], v[8:11]
	v_mfma_f32_16x16x32_bf16 v[60:63], v[132:135], v[168:171], v[60:63]
	v_mfma_f32_16x16x32_bf16 v[56:59], v[140:143], v[168:171], v[56:59]
	v_mfma_f32_16x16x32_bf16 v[44:47], v[132:135], v[176:179], v[44:47]
	v_mfma_f32_16x16x32_bf16 v[40:43], v[140:143], v[176:179], v[40:43]
	v_mfma_f32_16x16x32_bf16 v[28:31], v[132:135], v[184:187], v[28:31]
	v_mfma_f32_16x16x32_bf16 v[24:27], v[140:143], v[184:187], v[24:27]
	v_mfma_f32_16x16x32_bf16 v[12:15], v[132:135], v[194:197], v[12:15]
	v_mfma_f32_16x16x32_bf16 v[8:11], v[140:143], v[194:197], v[8:11]
	v_mfma_f32_16x16x32_bf16 v[52:55], v[144:147], v[164:167], v[52:55]
	v_mfma_f32_16x16x32_bf16 v[48:51], v[152:155], v[164:167], v[48:51]
	v_mfma_f32_16x16x32_bf16 v[36:39], v[144:147], v[172:175], v[36:39]
	v_mfma_f32_16x16x32_bf16 v[32:35], v[152:155], v[172:175], v[32:35]
	v_mfma_f32_16x16x32_bf16 v[20:23], v[144:147], v[180:183], v[20:23]
	v_mfma_f32_16x16x32_bf16 v[16:19], v[152:155], v[180:183], v[16:19]
	v_mfma_f32_16x16x32_bf16 v[4:7], v[144:147], v[188:191], v[4:7]
	v_mfma_f32_16x16x32_bf16 v[0:3], v[152:155], v[188:191], v[0:3]
	v_mfma_f32_16x16x32_bf16 v[52:55], v[148:151], v[168:171], v[52:55]
	v_mfma_f32_16x16x32_bf16 v[48:51], v[160:163], v[168:171], v[48:51]
	v_mfma_f32_16x16x32_bf16 v[36:39], v[148:151], v[176:179], v[36:39]
	v_mfma_f32_16x16x32_bf16 v[32:35], v[160:163], v[176:179], v[32:35]
	v_mfma_f32_16x16x32_bf16 v[20:23], v[148:151], v[184:187], v[20:23]
	v_mfma_f32_16x16x32_bf16 v[16:19], v[160:163], v[184:187], v[16:19]
	v_mfma_f32_16x16x32_bf16 v[4:7], v[148:151], v[194:197], v[4:7]
	v_mfma_f32_16x16x32_bf16 v[0:3], v[160:163], v[194:197], v[0:3]
	s_setprio 0
	s_barrier
; #define PG8_STAGE(bufoff, gbase, voff) do { _Pragma("unroll") for (int _i = 0; _i < 2; ++_i) \
;         asm volatile("s_mov_b32 m0, %0\n\ts_nop 0\n\tglobal_load_lds_dwordx4 %1, %2" :: "s"(ldsb + (unsigned)((bufoff) + _i * 8192)), "v"((voff)[_i]), "s"(gbase) : "m0", "memory"); } while (0)
; #define PG8_LDA(dst, b, h) do { _Pragma("unroll") for (int m = 0; m < 4; ++m) _Pragma("unroll") for (int k = 0; k < 2; ++k) dst[m][k] = *(const PG8_LAS bf16x8*)(lds + PG8_SA(b, h) + aoff + m * 2048 + k * 1024); } while (0)
; #define PG8_LDB(dst, b, h) do { _Pragma("unroll") for (int n = 0; n < 2; ++n) _Pragma("unroll") for (int k = 0; k < 2; ++k) dst[n][k] = *(const PG8_LAS bf16x8*)(lds + PG8_SB(b, h) + boff + n * 2048 + k * 1024); } while (0)
; #define PG8_MMA(ai, bj, At, Bt) do { __builtin_amdgcn_s_setprio(1); _Pragma("unroll") for (int m = 0; m < 4; ++m) _Pragma("unroll") for (int n = 0; n < 2; ++n) _Pragma("unroll") for (int k = 0; k < 2; ++k) \
;         acc[ai][bj][m][n] = __builtin_amdgcn_mfma_f32_16x16x32_bf16(Bt[n][k], At[m][k], acc[ai][bj][m][n], 0, 0, 0); __builtin_amdgcn_s_setprio(0); } while (0)
; #define PG8_WAIT_V(n) asm volatile("s_waitcnt vmcnt(" #n ")" ::: "memory")
; #define PG8_WAIT_L(n) asm volatile("s_waitcnt lgkmcnt(" #n ")" ::: "memory")
; #define PG8_BAR __builtin_amdgcn_s_barrier()
; #define PG8_SCHED __builtin_amdgcn_sched_barrier(0)
; template <class Epi, class Sched, bool ALIGN_EPI = false, bool SP2 = false>
; __device__ __forceinline__ void gemm_phase(PG8_LAS unsigned char* lds, const Gemm g, const Sched& S, const Epi& E, const int wv) {
;     ...
;         for (int t = 0; t < nt; t += 2) {
;     ...
;             PG8_LDB(B0, 1, 0); PG8_LDB(B1, 1, 1); PG8_SCHED; PG8_LDA(At, 1, 0); PG8_STAGE(PG8_SA(0, 1), a2 + hstepA, voffA);
;             PG8_WAIT_V(8); PG8_WAIT_L(0); PG8_BAR; PG8_MMA(0, 0, At, B0); PG8_MMA(0, 1, At, B1); PG8_BAR; PG8_SCHED;
;             PG8_LDA(At, 1, 1); PG8_STAGE(PG8_SB(1, 0), b3, voffB); PG8_STAGE(PG8_SB(1, 1), b3 + hstepB, voffB); PG8_STAGE(PG8_SA(1, 0), a3, voffA);
;             PG8_WAIT_V(8); PG8_WAIT_L(0); PG8_BAR; PG8_MMA(1, 0, At, B0); PG8_MMA(1, 1, At, B1); PG8_BAR; PG8_SCHED;
	v_add_u32_e32 v140, 0x18000, v220
	v_add_u32_e32 v159, 0x1c000, v220
	ds_read_b128 v[128:131], v140
	ds_read_b128 v[132:135], v140 offset:1024
	ds_read_b128 v[136:139], v140 offset:2048
	ds_read_b128 v[140:143], v140 offset:3072
	ds_read_b128 v[144:147], v159
	ds_read_b128 v[148:151], v159 offset:1024
	ds_read_b128 v[152:155], v159 offset:2048
	ds_read_b128 v[160:163], v159 offset:3072
	ds_read_b128 v[164:167], v221 offset:32768
	ds_read_b128 v[168:171], v221 offset:33792
	ds_read_b128 v[172:175], v221 offset:34816
	ds_read_b128 v[176:179], v221 offset:35840
	ds_read_b128 v[180:183], v221 offset:36864
	ds_read_b128 v[184:187], v221 offset:37888
	ds_read_b128 v[188:191], v221 offset:38912
	ds_read_b128 v[194:197], v221 offset:39936
	s_add_u32 s8, s36, 0x160000
	s_addc_u32 s9, s37, 0
	s_mov_b32 m0, s52
	s_nop 0
	global_load_lds_dwordx4 v208, s[8:9]
	s_mov_b32 m0, s53
	s_nop 0
	global_load_lds_dwordx4 v210, s[8:9]
	s_waitcnt vmcnt(8) lgkmcnt(0)
	s_setprio 1
	s_barrier
	v_mfma_f32_16x16x32_bf16 v[124:127], v[128:131], v[164:167], v[124:127]
	v_mfma_f32_16x16x32_bf16 v[120:123], v[136:139], v[164:167], v[120:123]
	v_mfma_f32_16x16x32_bf16 v[108:111], v[128:131], v[172:175], v[108:111]
	v_mfma_f32_16x16x32_bf16 v[104:107], v[136:139], v[172:175], v[104:107]
	v_mfma_f32_16x16x32_bf16 v[92:95], v[128:131], v[180:183], v[92:95]
	v_mfma_f32_16x16x32_bf16 v[88:91], v[136:139], v[180:183], v[88:91]
	v_mfma_f32_16x16x32_bf16 v[76:79], v[128:131], v[188:191], v[76:79]
	v_mfma_f32_16x16x32_bf16 v[72:75], v[136:139], v[188:191], v[72:75]
	v_mfma_f32_16x16x32_bf16 v[124:127], v[132:135], v[168:171], v[124:127]
	v_mfma_f32_16x16x32_bf16 v[120:123], v[140:143], v[168:171], v[120:123]
	v_mfma_f32_16x16x32_bf16 v[108:111], v[132:135], v[176:179], v[108:111]
	v_mfma_f32_16x16x32_bf16 v[104:107], v[140:143], v[176:179], v[104:107]
	v_mfma_f32_16x16x32_bf16 v[92:95], v[132:135], v[184:187], v[92:95]
	v_mfma_f32_16x16x32_bf16 v[88:91], v[140:143], v[184:187], v[88:91]
	v_mfma_f32_16x16x32_bf16 v[76:79], v[132:135], v[194:197], v[76:79]
	v_mfma_f32_16x16x32_bf16 v[72:75], v[140:143], v[194:197], v[72:75]
	v_mfma_f32_16x16x32_bf16 v[116:119], v[144:147], v[164:167], v[116:119]
	v_mfma_f32_16x16x32_bf16 v[112:115], v[152:155], v[164:167], v[112:115]
	v_mfma_f32_16x16x32_bf16 v[100:103], v[144:147], v[172:175], v[100:103]
	v_mfma_f32_16x16x32_bf16 v[96:99], v[152:155], v[172:175], v[96:99]
	v_mfma_f32_16x16x32_bf16 v[84:87], v[144:147], v[180:183], v[84:87]
	v_mfma_f32_16x16x32_bf16 v[80:83], v[152:155], v[180:183], v[80:83]
	v_mfma_f32_16x16x32_bf16 v[68:71], v[144:147], v[188:191], v[68:71]
	v_mfma_f32_16x16x32_bf16 v[64:67], v[152:155], v[188:191], v[64:67]
	v_mfma_f32_16x16x32_bf16 v[116:119], v[148:151], v[168:171], v[116:119]
	v_mfma_f32_16x16x32_bf16 v[112:115], v[160:163], v[168:171], v[112:115]
	v_mfma_f32_16x16x32_bf16 v[100:103], v[148:151], v[176:179], v[100:103]
	v_mfma_f32_16x16x32_bf16 v[96:99], v[160:163], v[176:179], v[96:99]
	v_mfma_f32_16x16x32_bf16 v[84:87], v[148:151], v[184:187], v[84:87]
	v_mfma_f32_16x16x32_bf16 v[80:83], v[160:163], v[184:187], v[80:83]
	v_mfma_f32_16x16x32_bf16 v[68:71], v[148:151], v[194:197], v[68:71]
	v_mfma_f32_16x16x32_bf16 v[64:67], v[160:163], v[194:197], v[64:67]
	s_setprio 0
	s_barrier
	ds_read_b128 v[164:167], v221 offset:49152
	ds_read_b128 v[168:171], v221 offset:50176
	ds_read_b128 v[172:175], v221 offset:51200
	ds_read_b128 v[176:179], v221 offset:52224
	ds_read_b128 v[180:183], v221 offset:53248
	ds_read_b128 v[184:187], v221 offset:54272
	ds_read_b128 v[188:191], v221 offset:55296
	ds_read_b128 v[194:197], v221 offset:56320
	s_add_u32 s8, s34, 0x80
	s_addc_u32 s9, s35, 0
	s_mov_b32 m0, s86
	s_nop 0
	global_load_lds_dwordx4 v209, s[8:9]
	s_mov_b32 m0, s87
	s_nop 0
	global_load_lds_dwordx4 v211, s[8:9]
	s_add_u32 s8, s34, 0x160080
	s_addc_u32 s9, s35, 0
	s_mov_b32 m0, s89
	s_nop 0
	global_load_lds_dwordx4 v209, s[8:9]
	s_mov_b32 m0, s92
	s_nop 0
	global_load_lds_dwordx4 v211, s[8:9]
	s_mov_b32 m0, s83
	s_nop 0
	global_load_lds_dwordx4 v208, s[30:31]
	s_mov_b32 m0, s60
	s_nop 0
	global_load_lds_dwordx4 v210, s[30:31]
	s_waitcnt vmcnt(8) lgkmcnt(0)
	s_setprio 1
	s_barrier
	v_mfma_f32_16x16x32_bf16 v[60:63], v[128:131], v[164:167], v[60:63]
	v_mfma_f32_16x16x32_bf16 v[56:59], v[136:139], v[164:167], v[56:59]
	v_mfma_f32_16x16x32_bf16 v[44:47], v[128:131], v[172:175], v[44:47]
	v_mfma_f32_16x16x32_bf16 v[40:43], v[136:139], v[172:175], v[40:43]
	v_mfma_f32_16x16x32_bf16 v[28:31], v[128:131], v[180:183], v[28:31]
	v_mfma_f32_16x16x32_bf16 v[24:27], v[136:139], v[180:183], v[24:27]
	v_mfma_f32_16x16x32_bf16 v[12:15], v[128:131], v[188:191], v[12:15]
	v_mfma_f32_16x16x32_bf16 v[8:11], v[136:139], v[188:191], v[8:11]
	v_mfma_f32_16x16x32_bf16 v[60:63], v[132:135], v[168:171], v[60:63]
	v_mfma_f32_16x16x32_bf16 v[56:59], v[140:143], v[168:171], v[56:59]
	v_mfma_f32_16x16x32_bf16 v[44:47], v[132:135], v[176:179], v[44:47]
	v_mfma_f32_16x16x32_bf16 v[40:43], v[140:143], v[176:179], v[40:43]
	v_mfma_f32_16x16x32_bf16 v[28:31], v[132:135], v[184:187], v[28:31]
	v_mfma_f32_16x16x32_bf16 v[24:27], v[140:143], v[184:187], v[24:27]
	v_mfma_f32_16x16x32_bf16 v[12:15], v[132:135], v[194:197], v[12:15]
	v_mfma_f32_16x16x32_bf16 v[8:11], v[140:143], v[194:197], v[8:11]
	v_mfma_f32_16x16x32_bf16 v[52:55], v[144:147], v[164:167], v[52:55]
	v_mfma_f32_16x16x32_bf16 v[48:51], v[152:155], v[164:167], v[48:51]
	v_mfma_f32_16x16x32_bf16 v[36:39], v[144:147], v[172:175], v[36:39]
	v_mfma_f32_16x16x32_bf16 v[32:35], v[152:155], v[172:175], v[32:35]
	v_mfma_f32_16x16x32_bf16 v[20:23], v[144:147], v[180:183], v[20:23]
	v_mfma_f32_16x16x32_bf16 v[16:19], v[152:155], v[180:183], v[16:19]
	v_mfma_f32_16x16x32_bf16 v[4:7], v[144:147], v[188:191], v[4:7]
	v_mfma_f32_16x16x32_bf16 v[0:3], v[152:155], v[188:191], v[0:3]
	v_mfma_f32_16x16x32_bf16 v[52:55], v[148:151], v[168:171], v[52:55]
	v_mfma_f32_16x16x32_bf16 v[48:51], v[160:163], v[168:171], v[48:51]
	v_mfma_f32_16x16x32_bf16 v[36:39], v[148:151], v[176:179], v[36:39]
	v_mfma_f32_16x16x32_bf16 v[32:35], v[160:163], v[176:179], v[32:35]
	v_mfma_f32_16x16x32_bf16 v[20:23], v[148:151], v[184:187], v[20:23]
	v_mfma_f32_16x16x32_bf16 v[16:19], v[160:163], v[184:187], v[16:19]
	v_mfma_f32_16x16x32_bf16 v[4:7], v[148:151], v[194:197], v[4:7]
	v_mfma_f32_16x16x32_bf16 v[0:3], v[160:163], v[194:197], v[0:3]
	s_setprio 0
	s_barrier
	s_add_u32 s85, s85, 0x100
	s_addc_u32 vcc_lo, vcc_lo, 0
	s_add_u32 vcc_hi, vcc_hi, 0x100
	s_addc_u32 s79, s79, 0
	s_add_u32 s28, s28, 0x100
	s_addc_u32 s29, s29, 0
	s_cmp_ge_i32 s62, s40
	s_mov_b32 s30, s62
	s_cbranch_scc0 .LBB0_343
	s_mov_b32 s79, 0xc00000
	s_and_b64 vcc, exec, s[18:19]
	s_cbranch_vccz .LBB0_346

; #define PG8_STAGE(bufoff, gbase, voff) do { _Pragma("unroll") for (int _i = 0; _i < 2; ++_i) \
;         asm volatile("s_mov_b32 m0, %0\n\ts_nop 0\n\tglobal_load_lds_dwordx4 %1, %2" :: "s"(ldsb + (unsigned)((bufoff) + _i * 8192)), "v"((voff)[_i]), "s"(gbase) : "m0", "memory"); } while (0)
; #define PG8_LDA(dst, b, h) do { _Pragma("unroll") for (int m = 0; m < 4; ++m) _Pragma("unroll") for (int k = 0; k < 2; ++k) dst[m][k] = *(const PG8_LAS bf16x8*)(lds + PG8_SA(b, h) + aoff + m * 2048 + k * 1024); } while (0)
; #define PG8_WAIT_V(n) asm volatile("s_waitcnt vmcnt(" #n ")" ::: "memory")
; #define PG8_WAIT_L(n) asm volatile("s_waitcnt lgkmcnt(" #n ")" ::: "memory")
; template <class Epi, class Sched, bool ALIGN_EPI = false, bool SP2 = false>
; __device__ __forceinline__ void gemm_phase(PG8_LAS unsigned char* lds, const Gemm g, const Sched& S, const Epi& E, const int wv) {
;     ...
;         for (int t = 0; t < nt; t += 2) {
;             const bool last = (t == nt - 2);
;             const char* a1 = cA + (size_t)(t + 1) * kstep;
;             const char* a2 = last ? nA : cA + (size_t)(t + 2) * kstep; const char* b2 = last ? nB : cB + (size_t)(t + 2) * kstep;
;             const char* a3 = a2 + kstep; const char* b3 = b2 + kstep;
;             if (last && has_next) S.a_ready(nxt);
;             if constexpr (SP2) {
;             PG8_LDB(B0, 0, 0); PG8_LDB(B1, 0, 1); PG8_SCHED; PG8_LDA(At, 0, 0); PG8_STAGE(PG8_SA(1, 1), a1 + hstepA, voffA);
;             PG8_WAIT_V(8); PG8_WAIT_L(0); PG8_BAR; PG8_MMA(0, 0, At, B0); PG8_MMA(0, 1, At, B1); PG8_BAR; PG8_SCHED;
;             PG8_LDA(At, 0, 1); PG8_STAGE(PG8_SB(0, 0), b2, voffB); PG8_STAGE(PG8_SB(0, 1), b2 + hstepB, voffB); PG8_STAGE(PG8_SA(0, 0), a2, voffA);
;             PG8_WAIT_V(8); PG8_WAIT_L(0); PG8_BAR; PG8_MMA(1, 0, At, B0); PG8_MMA(1, 1, At, B1); PG8_BAR; PG8_SCHED;
;             PG8_LDB(B0, 1, 0); PG8_LDB(B1, 1, 1); PG8_SCHED; PG8_LDA(At, 1, 0); PG8_STAGE(PG8_SA(0, 1), a2 + hstepA, voffA);
;             PG8_WAIT_V(8); PG8_WAIT_L(0); PG8_BAR; PG8_MMA(0, 0, At, B0); PG8_MMA(0, 1, At, B1); PG8_BAR; PG8_SCHED;
;             PG8_LDA(At, 1, 1); PG8_STAGE(PG8_SB(1, 0), b3, voffB); PG8_STAGE(PG8_SB(1, 1), b3 + hstepB, voffB); PG8_STAGE(PG8_SA(1, 0), a3, voffA);
;             PG8_WAIT_V(8); PG8_WAIT_L(0); PG8_BAR; PG8_MMA(1, 0, At, B0); PG8_MMA(1, 1, At, B1); PG8_BAR; PG8_SCHED;
.LBB0_396:
	v_add_u32_e32 v140, 0x10000, v240
	v_add_u32_e32 v156, 0x14000, v240
	ds_read_b128 v[128:131], v140
	ds_read_b128 v[132:135], v140 offset:1024
	ds_read_b128 v[136:139], v140 offset:2048
	ds_read_b128 v[140:143], v140 offset:3072
	ds_read_b128 v[144:147], v156
	ds_read_b128 v[148:151], v156 offset:1024
	ds_read_b128 v[152:155], v156 offset:2048
	ds_read_b128 v[156:159], v156 offset:3072
	s_add_i32 vcc_hi, s30, 2
	s_cmp_eq_u32 s25, s30
	s_cselect_b32 s36, s26, s62
	s_cselect_b32 s37, s27, s79
	s_cselect_b32 s34, s28, s97
	s_cselect_b32 s35, s29, vcc_lo
	s_add_u32 s30, s36, 0x80
	s_addc_u32 s31, s37, 0
	ds_read_b128 v[160:163], v194
	ds_read_b128 v[164:167], v194 offset:1024
	ds_read_b128 v[168:171], v194 offset:2048
	ds_read_b128 v[172:175], v194 offset:3072
	ds_read_b128 v[176:179], v194 offset:4096
	ds_read_b128 v[180:183], v194 offset:5120
	ds_read_b128 v[184:187], v194 offset:6144
	ds_read_b128 v[188:191], v194 offset:7168
	s_add_u32 s10, s62, 0x15ff80
	s_addc_u32 s11, s79, 0
	s_mov_b32 m0, s83
	s_nop 0
	global_load_lds_dwordx4 v244, s[10:11]
	s_mov_b32 m0, s86
	s_nop 0
	global_load_lds_dwordx4 v246, s[10:11]
	s_waitcnt vmcnt(8) lgkmcnt(0)
	s_setprio 1
	s_barrier
	v_mfma_f32_16x16x32_bf16 v[124:127], v[128:131], v[160:163], v[124:127]
	v_mfma_f32_16x16x32_bf16 v[120:123], v[136:139], v[160:163], v[120:123]
	v_mfma_f32_16x16x32_bf16 v[108:111], v[128:131], v[168:171], v[108:111]
	v_mfma_f32_16x16x32_bf16 v[104:107], v[136:139], v[168:171], v[104:107]
	v_mfma_f32_16x16x32_bf16 v[92:95], v[128:131], v[176:179], v[92:95]
	v_mfma_f32_16x16x32_bf16 v[88:91], v[136:139], v[176:179], v[88:91]
	v_mfma_f32_16x16x32_bf16 v[76:79], v[128:131], v[184:187], v[76:79]
	v_mfma_f32_16x16x32_bf16 v[72:75], v[136:139], v[184:187], v[72:75]
	v_mfma_f32_16x16x32_bf16 v[124:127], v[132:135], v[164:167], v[124:127]
	v_mfma_f32_16x16x32_bf16 v[120:123], v[140:143], v[164:167], v[120:123]
	v_mfma_f32_16x16x32_bf16 v[108:111], v[132:135], v[172:175], v[108:111]
	v_mfma_f32_16x16x32_bf16 v[104:107], v[140:143], v[172:175], v[104:107]
	v_mfma_f32_16x16x32_bf16 v[92:95], v[132:135], v[180:183], v[92:95]
	v_mfma_f32_16x16x32_bf16 v[88:91], v[140:143], v[180:183], v[88:91]
	v_mfma_f32_16x16x32_bf16 v[76:79], v[132:135], v[188:191], v[76:79]
	v_mfma_f32_16x16x32_bf16 v[72:75], v[140:143], v[188:191], v[72:75]
	v_mfma_f32_16x16x32_bf16 v[116:119], v[144:147], v[160:163], v[116:119]
	v_mfma_f32_16x16x32_bf16 v[112:115], v[152:155], v[160:163], v[112:115]
	v_mfma_f32_16x16x32_bf16 v[100:103], v[144:147], v[168:171], v[100:103]
	v_mfma_f32_16x16x32_bf16 v[96:99], v[152:155], v[168:171], v[96:99]
	v_mfma_f32_16x16x32_bf16 v[84:87], v[144:147], v[176:179], v[84:87]
	v_mfma_f32_16x16x32_bf16 v[80:83], v[152:155], v[176:179], v[80:83]
	v_mfma_f32_16x16x32_bf16 v[68:71], v[144:147], v[184:187], v[68:71]
	v_mfma_f32_16x16x32_bf16 v[64:67], v[152:155], v[184:187], v[64:67]
	v_mfma_f32_16x16x32_bf16 v[116:119], v[148:151], v[164:167], v[116:119]
	v_mfma_f32_16x16x32_bf16 v[112:115], v[156:159], v[164:167], v[112:115]
	v_mfma_f32_16x16x32_bf16 v[100:103], v[148:151], v[172:175], v[100:103]
	v_mfma_f32_16x16x32_bf16 v[96:99], v[156:159], v[172:175], v[96:99]
	v_mfma_f32_16x16x32_bf16 v[84:87], v[148:151], v[180:183], v[84:87]
	v_mfma_f32_16x16x32_bf16 v[80:83], v[156:159], v[180:183], v[80:83]
	v_mfma_f32_16x16x32_bf16 v[68:71], v[148:151], v[188:191], v[68:71]
	v_mfma_f32_16x16x32_bf16 v[64:67], v[156:159], v[188:191], v[64:67]
	s_setprio 0
	s_barrier
	ds_read_b128 v[160:163], v194 offset:16384
	ds_read_b128 v[164:167], v194 offset:17408
	ds_read_b128 v[168:171], v194 offset:18432
	ds_read_b128 v[172:175], v194 offset:19456
	ds_read_b128 v[176:179], v194 offset:20480
	ds_read_b128 v[180:183], v194 offset:21504
	ds_read_b128 v[184:187], v194 offset:22528
	ds_read_b128 v[188:191], v194 offset:23552
	s_mov_b32 m0, s46
	s_nop 0
	global_load_lds_dwordx4 v245, s[34:35]
	s_add_u32 s10, s34, 0x160000
	s_mov_b32 m0, s47
	s_nop 0
	global_load_lds_dwordx4 v247, s[34:35]
	s_addc_u32 s11, s35, 0
	s_mov_b32 m0, s48
	s_nop 0
	global_load_lds_dwordx4 v245, s[10:11]
	s_mov_b32 m0, s49
	s_nop 0
	global_load_lds_dwordx4 v247, s[10:11]
	s_mov_b32 m0, s33
	s_nop 0
	global_load_lds_dwordx4 v244, s[36:37]
	s_mov_b32 m0, s50
	s_nop 0
	global_load_lds_dwordx4 v246, s[36:37]
	s_waitcnt vmcnt(8) lgkmcnt(0)
	s_setprio 1
	s_barrier
	v_mfma_f32_16x16x32_bf16 v[60:63], v[128:131], v[160:163], v[60:63]
	v_mfma_f32_16x16x32_bf16 v[56:59], v[136:139], v[160:163], v[56:59]
	v_mfma_f32_16x16x32_bf16 v[44:47], v[128:131], v[168:171], v[44:47]
	v_mfma_f32_16x16x32_bf16 v[40:43], v[136:139], v[168:171], v[40:43]
	v_mfma_f32_16x16x32_bf16 v[28:31], v[128:131], v[176:179], v[28:31]
	v_mfma_f32_16x16x32_bf16 v[24:27], v[136:139], v[176:179], v[24:27]
	v_mfma_f32_16x16x32_bf16 v[12:15], v[128:131], v[184:187], v[12:15]
	v_mfma_f32_16x16x32_bf16 v[8:11], v[136:139], v[184:187], v[8:11]
	v_mfma_f32_16x16x32_bf16 v[60:63], v[132:135], v[164:167], v[60:63]
	v_mfma_f32_16x16x32_bf16 v[56:59], v[140:143], v[164:167], v[56:59]
	v_mfma_f32_16x16x32_bf16 v[44:47], v[132:135], v[172:175], v[44:47]
	v_mfma_f32_16x16x32_bf16 v[40:43], v[140:143], v[172:175], v[40:43]
	v_mfma_f32_16x16x32_bf16 v[28:31], v[132:135], v[180:183], v[28:31]
	v_mfma_f32_16x16x32_bf16 v[24:27], v[140:143], v[180:183], v[24:27]
	v_mfma_f32_16x16x32_bf16 v[12:15], v[132:135], v[188:191], v[12:15]
	v_mfma_f32_16x16x32_bf16 v[8:11], v[140:143], v[188:191], v[8:11]
	v_mfma_f32_16x16x32_bf16 v[52:55], v[144:147], v[160:163], v[52:55]
	v_mfma_f32_16x16x32_bf16 v[48:51], v[152:155], v[160:163], v[48:51]
	v_mfma_f32_16x16x32_bf16 v[36:39], v[144:147], v[168:171], v[36:39]
	v_mfma_f32_16x16x32_bf16 v[32:35], v[152:155], v[168:171], v[32:35]
	v_mfma_f32_16x16x32_bf16 v[20:23], v[144:147], v[176:179], v[20:23]
	v_mfma_f32_16x16x32_bf16 v[16:19], v[152:155], v[176:179], v[16:19]
	v_mfma_f32_16x16x32_bf16 v[4:7], v[144:147], v[184:187], v[4:7]
	v_mfma_f32_16x16x32_bf16 v[0:3], v[152:155], v[184:187], v[0:3]
	v_mfma_f32_16x16x32_bf16 v[52:55], v[148:151], v[164:167], v[52:55]
	v_mfma_f32_16x16x32_bf16 v[48:51], v[156:159], v[164:167], v[48:51]
	v_mfma_f32_16x16x32_bf16 v[36:39], v[148:151], v[172:175], v[36:39]
	v_mfma_f32_16x16x32_bf16 v[32:35], v[156:159], v[172:175], v[32:35]
	v_mfma_f32_16x16x32_bf16 v[20:23], v[148:151], v[180:183], v[20:23]
	v_mfma_f32_16x16x32_bf16 v[16:19], v[156:159], v[180:183], v[16:19]
	v_mfma_f32_16x16x32_bf16 v[4:7], v[148:151], v[188:191], v[4:7]
	v_mfma_f32_16x16x32_bf16 v[0:3], v[156:159], v[188:191], v[0:3]
	s_setprio 0
	s_barrier
; #define PG8_STAGE(bufoff, gbase, voff) do { _Pragma("unroll") for (int _i = 0; _i < 2; ++_i) \
;         asm volatile("s_mov_b32 m0, %0\n\ts_nop 0\n\tglobal_load_lds_dwordx4 %1, %2" :: "s"(ldsb + (unsigned)((bufoff) + _i * 8192)), "v"((voff)[_i]), "s"(gbase) : "m0", "memory"); } while (0)
; #define PG8_LDA(dst, b, h) do { _Pragma("unroll") for (int m = 0; m < 4; ++m) _Pragma("unroll") for (int k = 0; k < 2; ++k) dst[m][k] = *(const PG8_LAS bf16x8*)(lds + PG8_SA(b, h) + aoff + m * 2048 + k * 1024); } while (0)
; #define PG8_LDB(dst, b, h) do { _Pragma("unroll") for (int n = 0; n < 2; ++n) _Pragma("unroll") for (int k = 0; k < 2; ++k) dst[n][k] = *(const PG8_LAS bf16x8*)(lds + PG8_SB(b, h) + boff + n * 2048 + k * 1024); } while (0)
; #define PG8_MMA(ai, bj, At, Bt) do { __builtin_amdgcn_s_setprio(1); _Pragma("unroll") for (int m = 0; m < 4; ++m) _Pragma("unroll") for (int n = 0; n < 2; ++n) _Pragma("unroll") for (int k = 0; k < 2; ++k) \
;         acc[ai][bj][m][n] = __builtin_amdgcn_mfma_f32_16x16x32_bf16(Bt[n][k], At[m][k], acc[ai][bj][m][n], 0, 0, 0); __builtin_amdgcn_s_setprio(0); } while (0)
; #define PG8_WAIT_V(n) asm volatile("s_waitcnt vmcnt(" #n ")" ::: "memory")
; #define PG8_WAIT_L(n) asm volatile("s_waitcnt lgkmcnt(" #n ")" ::: "memory")
; #define PG8_BAR __builtin_amdgcn_s_barrier()
; #define PG8_SCHED __builtin_amdgcn_sched_barrier(0)
; template <class Epi, class Sched, bool ALIGN_EPI = false, bool SP2 = false>
; __device__ __forceinline__ void gemm_phase(PG8_LAS unsigned char* lds, const Gemm g, const Sched& S, const Epi& E, const int wv) {
;     ...
;         for (int t = 0; t < nt; t += 2) {
;     ...
;             PG8_LDB(B0, 1, 0); PG8_LDB(B1, 1, 1); PG8_SCHED; PG8_LDA(At, 1, 0); PG8_STAGE(PG8_SA(0, 1), a2 + hstepA, voffA);
;             PG8_WAIT_V(8); PG8_WAIT_L(0); PG8_BAR; PG8_MMA(0, 0, At, B0); PG8_MMA(0, 1, At, B1); PG8_BAR; PG8_SCHED;
;             PG8_LDA(At, 1, 1); PG8_STAGE(PG8_SB(1, 0), b3, voffB); PG8_STAGE(PG8_SB(1, 1), b3 + hstepB, voffB); PG8_STAGE(PG8_SA(1, 0), a3, voffA);
;             PG8_WAIT_V(8); PG8_WAIT_L(0); PG8_BAR; PG8_MMA(1, 0, At, B0); PG8_MMA(1, 1, At, B1); PG8_BAR; PG8_SCHED;
	v_add_u32_e32 v140, 0x18000, v240
	v_add_u32_e32 v156, 0x1c000, v240
	ds_read_b128 v[128:131], v140
	ds_read_b128 v[132:135], v140 offset:1024
	ds_read_b128 v[136:139], v140 offset:2048
	ds_read_b128 v[140:143], v140 offset:3072
	ds_read_b128 v[144:147], v156
	ds_read_b128 v[148:151], v156 offset:1024
	ds_read_b128 v[152:155], v156 offset:2048
	ds_read_b128 v[156:159], v156 offset:3072
	ds_read_b128 v[160:163], v194 offset:32768
	ds_read_b128 v[164:167], v194 offset:33792
	ds_read_b128 v[168:171], v194 offset:34816
	ds_read_b128 v[172:175], v194 offset:35840
	ds_read_b128 v[176:179], v194 offset:36864
	ds_read_b128 v[180:183], v194 offset:37888
	ds_read_b128 v[184:187], v194 offset:38912
	ds_read_b128 v[188:191], v194 offset:39936
	s_add_u32 s10, s36, 0x160000
	s_addc_u32 s11, s37, 0
	s_mov_b32 m0, s51
	s_nop 0
	global_load_lds_dwordx4 v244, s[10:11]
	s_mov_b32 m0, s52
	s_nop 0
	global_load_lds_dwordx4 v246, s[10:11]
	s_waitcnt vmcnt(8) lgkmcnt(0)
	s_setprio 1
	s_barrier
	v_mfma_f32_16x16x32_bf16 v[124:127], v[128:131], v[160:163], v[124:127]
	v_mfma_f32_16x16x32_bf16 v[120:123], v[136:139], v[160:163], v[120:123]
	v_mfma_f32_16x16x32_bf16 v[108:111], v[128:131], v[168:171], v[108:111]
	v_mfma_f32_16x16x32_bf16 v[104:107], v[136:139], v[168:171], v[104:107]
	v_mfma_f32_16x16x32_bf16 v[92:95], v[128:131], v[176:179], v[92:95]
	v_mfma_f32_16x16x32_bf16 v[88:91], v[136:139], v[176:179], v[88:91]
	v_mfma_f32_16x16x32_bf16 v[76:79], v[128:131], v[184:187], v[76:79]
	v_mfma_f32_16x16x32_bf16 v[72:75], v[136:139], v[184:187], v[72:75]
	v_mfma_f32_16x16x32_bf16 v[124:127], v[132:135], v[164:167], v[124:127]
	v_mfma_f32_16x16x32_bf16 v[120:123], v[140:143], v[164:167], v[120:123]
	v_mfma_f32_16x16x32_bf16 v[108:111], v[132:135], v[172:175], v[108:111]
	v_mfma_f32_16x16x32_bf16 v[104:107], v[140:143], v[172:175], v[104:107]
	v_mfma_f32_16x16x32_bf16 v[92:95], v[132:135], v[180:183], v[92:95]
	v_mfma_f32_16x16x32_bf16 v[88:91], v[140:143], v[180:183], v[88:91]
	v_mfma_f32_16x16x32_bf16 v[76:79], v[132:135], v[188:191], v[76:79]
	v_mfma_f32_16x16x32_bf16 v[72:75], v[140:143], v[188:191], v[72:75]
	v_mfma_f32_16x16x32_bf16 v[116:119], v[144:147], v[160:163], v[116:119]
	v_mfma_f32_16x16x32_bf16 v[112:115], v[152:155], v[160:163], v[112:115]
	v_mfma_f32_16x16x32_bf16 v[100:103], v[144:147], v[168:171], v[100:103]
	v_mfma_f32_16x16x32_bf16 v[96:99], v[152:155], v[168:171], v[96:99]
	v_mfma_f32_16x16x32_bf16 v[84:87], v[144:147], v[176:179], v[84:87]
	v_mfma_f32_16x16x32_bf16 v[80:83], v[152:155], v[176:179], v[80:83]
	v_mfma_f32_16x16x32_bf16 v[68:71], v[144:147], v[184:187], v[68:71]
	v_mfma_f32_16x16x32_bf16 v[64:67], v[152:155], v[184:187], v[64:67]
	v_mfma_f32_16x16x32_bf16 v[116:119], v[148:151], v[164:167], v[116:119]
	v_mfma_f32_16x16x32_bf16 v[112:115], v[156:159], v[164:167], v[112:115]
	v_mfma_f32_16x16x32_bf16 v[100:103], v[148:151], v[172:175], v[100:103]
	v_mfma_f32_16x16x32_bf16 v[96:99], v[156:159], v[172:175], v[96:99]
	v_mfma_f32_16x16x32_bf16 v[84:87], v[148:151], v[180:183], v[84:87]
	v_mfma_f32_16x16x32_bf16 v[80:83], v[156:159], v[180:183], v[80:83]
	v_mfma_f32_16x16x32_bf16 v[68:71], v[148:151], v[188:191], v[68:71]
	v_mfma_f32_16x16x32_bf16 v[64:67], v[156:159], v[188:191], v[64:67]
	s_setprio 0
	s_barrier
	ds_read_b128 v[160:163], v194 offset:49152
	ds_read_b128 v[164:167], v194 offset:50176
	ds_read_b128 v[168:171], v194 offset:51200
	ds_read_b128 v[172:175], v194 offset:52224
	ds_read_b128 v[176:179], v194 offset:53248
	ds_read_b128 v[180:183], v194 offset:54272
	ds_read_b128 v[184:187], v194 offset:55296
	ds_read_b128 v[188:191], v194 offset:56320
	s_add_u32 s10, s34, 0x80
	s_addc_u32 s11, s35, 0
	s_mov_b32 m0, s58
	s_nop 0
	global_load_lds_dwordx4 v245, s[10:11]
	s_mov_b32 m0, s60
	s_nop 0
	global_load_lds_dwordx4 v247, s[10:11]
	s_add_u32 s10, s34, 0x160080
	s_addc_u32 s11, s35, 0
	s_mov_b32 m0, s72
	s_nop 0
	global_load_lds_dwordx4 v245, s[10:11]
	s_mov_b32 m0, s77
	s_nop 0
	global_load_lds_dwordx4 v247, s[10:11]
	s_mov_b32 m0, s65
	s_nop 0
	global_load_lds_dwordx4 v244, s[30:31]
	s_mov_b32 m0, s71
	s_nop 0
	global_load_lds_dwordx4 v246, s[30:31]
	s_waitcnt vmcnt(8) lgkmcnt(0)
	s_setprio 1
	s_barrier
	v_mfma_f32_16x16x32_bf16 v[60:63], v[128:131], v[160:163], v[60:63]
	v_mfma_f32_16x16x32_bf16 v[56:59], v[136:139], v[160:163], v[56:59]
	v_mfma_f32_16x16x32_bf16 v[44:47], v[128:131], v[168:171], v[44:47]
	v_mfma_f32_16x16x32_bf16 v[40:43], v[136:139], v[168:171], v[40:43]
	v_mfma_f32_16x16x32_bf16 v[28:31], v[128:131], v[176:179], v[28:31]
	v_mfma_f32_16x16x32_bf16 v[24:27], v[136:139], v[176:179], v[24:27]
	v_mfma_f32_16x16x32_bf16 v[12:15], v[128:131], v[184:187], v[12:15]
	v_mfma_f32_16x16x32_bf16 v[8:11], v[136:139], v[184:187], v[8:11]
	v_mfma_f32_16x16x32_bf16 v[60:63], v[132:135], v[164:167], v[60:63]
	v_mfma_f32_16x16x32_bf16 v[56:59], v[140:143], v[164:167], v[56:59]
	v_mfma_f32_16x16x32_bf16 v[44:47], v[132:135], v[172:175], v[44:47]
	v_mfma_f32_16x16x32_bf16 v[40:43], v[140:143], v[172:175], v[40:43]
	v_mfma_f32_16x16x32_bf16 v[28:31], v[132:135], v[180:183], v[28:31]
	v_mfma_f32_16x16x32_bf16 v[24:27], v[140:143], v[180:183], v[24:27]
	v_mfma_f32_16x16x32_bf16 v[12:15], v[132:135], v[188:191], v[12:15]
	v_mfma_f32_16x16x32_bf16 v[8:11], v[140:143], v[188:191], v[8:11]
	v_mfma_f32_16x16x32_bf16 v[52:55], v[144:147], v[160:163], v[52:55]
	v_mfma_f32_16x16x32_bf16 v[48:51], v[152:155], v[160:163], v[48:51]
	v_mfma_f32_16x16x32_bf16 v[36:39], v[144:147], v[168:171], v[36:39]
	v_mfma_f32_16x16x32_bf16 v[32:35], v[152:155], v[168:171], v[32:35]
	v_mfma_f32_16x16x32_bf16 v[20:23], v[144:147], v[176:179], v[20:23]
	v_mfma_f32_16x16x32_bf16 v[16:19], v[152:155], v[176:179], v[16:19]
	v_mfma_f32_16x16x32_bf16 v[4:7], v[144:147], v[184:187], v[4:7]
	v_mfma_f32_16x16x32_bf16 v[0:3], v[152:155], v[184:187], v[0:3]
	v_mfma_f32_16x16x32_bf16 v[52:55], v[148:151], v[164:167], v[52:55]
	v_mfma_f32_16x16x32_bf16 v[48:51], v[156:159], v[164:167], v[48:51]
	v_mfma_f32_16x16x32_bf16 v[36:39], v[148:151], v[172:175], v[36:39]
	v_mfma_f32_16x16x32_bf16 v[32:35], v[156:159], v[172:175], v[32:35]
	v_mfma_f32_16x16x32_bf16 v[20:23], v[148:151], v[180:183], v[20:23]
	v_mfma_f32_16x16x32_bf16 v[16:19], v[156:159], v[180:183], v[16:19]
	v_mfma_f32_16x16x32_bf16 v[4:7], v[148:151], v[188:191], v[4:7]
	v_mfma_f32_16x16x32_bf16 v[0:3], v[156:159], v[188:191], v[0:3]
	s_setprio 0
	s_barrier
	s_add_u32 s62, s62, 0x100
	s_addc_u32 s79, s79, 0
	s_add_u32 s97, s97, 0x100
	s_addc_u32 vcc_lo, vcc_lo, 0
	s_cmp_ge_i32 vcc_hi, s40
	s_mov_b32 s30, vcc_hi
	s_cbranch_scc0 .LBB0_396
	s_mov_b32 s79, 0xc00000
	s_and_b64 vcc, exec, s[20:21]
	s_cbranch_vccz .LBB0_399

; #define PG8_STAGE(bufoff, gbase, voff) do { _Pragma("unroll") for (int _i = 0; _i < 2; ++_i) \
;         asm volatile("s_mov_b32 m0, %0\n\ts_nop 0\n\tglobal_load_lds_dwordx4 %1, %2" :: "s"(ldsb + (unsigned)((bufoff) + _i * 8192)), "v"((voff)[_i]), "s"(gbase) : "m0", "memory"); } while (0)
; #define PG8_LDA(dst, b, h) do { _Pragma("unroll") for (int m = 0; m < 4; ++m) _Pragma("unroll") for (int k = 0; k < 2; ++k) dst[m][k] = *(const PG8_LAS bf16x8*)(lds + PG8_SA(b, h) + aoff + m * 2048 + k * 1024); } while (0)
; #define PG8_WAIT_V(n) asm volatile("s_waitcnt vmcnt(" #n ")" ::: "memory")
; #define PG8_WAIT_L(n) asm volatile("s_waitcnt lgkmcnt(" #n ")" ::: "memory")
; template <class Epi, class Sched, bool ALIGN_EPI = false, bool SP2 = false>
; __device__ __forceinline__ void gemm_phase(PG8_LAS unsigned char* lds, const Gemm g, const Sched& S, const Epi& E, const int wv) {
;     ...
;         for (int t = 0; t < nt; t += 2) {
;             const bool last = (t == nt - 2);
;             const char* a1 = cA + (size_t)(t + 1) * kstep;
;             const char* a2 = last ? nA : cA + (size_t)(t + 2) * kstep; const char* b2 = last ? nB : cB + (size_t)(t + 2) * kstep;
;             const char* a3 = a2 + kstep; const char* b3 = b2 + kstep;
;             if (last && has_next) S.a_ready(nxt);
;             if constexpr (SP2) {
;             PG8_LDB(B0, 0, 0); PG8_LDB(B1, 0, 1); PG8_SCHED; PG8_LDA(At, 0, 0); PG8_STAGE(PG8_SA(1, 1), a1 + hstepA, voffA);
;             PG8_WAIT_V(8); PG8_WAIT_L(0); PG8_BAR; PG8_MMA(0, 0, At, B0); PG8_MMA(0, 1, At, B1); PG8_BAR; PG8_SCHED;
;             PG8_LDA(At, 0, 1); PG8_STAGE(PG8_SB(0, 0), b2, voffB); PG8_STAGE(PG8_SB(0, 1), b2 + hstepB, voffB); PG8_STAGE(PG8_SA(0, 0), a2, voffA);
;             PG8_WAIT_V(8); PG8_WAIT_L(0); PG8_BAR; PG8_MMA(1, 0, At, B0); PG8_MMA(1, 1, At, B1); PG8_BAR; PG8_SCHED;
;             PG8_LDB(B0, 1, 0); PG8_LDB(B1, 1, 1); PG8_SCHED; PG8_LDA(At, 1, 0); PG8_STAGE(PG8_SA(0, 1), a2 + hstepA, voffA);
;             PG8_WAIT_V(8); PG8_WAIT_L(0); PG8_BAR; PG8_MMA(0, 0, At, B0); PG8_MMA(0, 1, At, B1); PG8_BAR; PG8_SCHED;
;             PG8_LDA(At, 1, 1); PG8_STAGE(PG8_SB(1, 0), b3, voffB); PG8_STAGE(PG8_SB(1, 1), b3 + hstepB, voffB); PG8_STAGE(PG8_SA(1, 0), a3, voffA);
;             PG8_WAIT_V(8); PG8_WAIT_L(0); PG8_BAR; PG8_MMA(1, 0, At, B0); PG8_MMA(1, 1, At, B1); PG8_BAR; PG8_SCHED;
.LBB0_563:
	v_add_u32_e32 v140, 0x10000, v166
	v_add_u32_e32 v148, 0x14000, v166
	ds_read_b128 v[128:131], v140
	ds_read_b128 v[132:135], v140 offset:1024
	ds_read_b128 v[136:139], v140 offset:2048
	ds_read_b128 v[140:143], v140 offset:3072
	ds_read_b128 v[168:171], v148
	ds_read_b128 v[172:175], v148 offset:1024
	ds_read_b128 v[176:179], v148 offset:2048
	ds_read_b128 v[180:183], v148 offset:3072
	s_add_i32 s92, s24, 2
	s_cmp_eq_u32 s62, s24
	s_cselect_b32 s28, s20, s79
	s_cselect_b32 s29, s21, s88
	s_cselect_b32 s26, s87, s89
	s_cselect_b32 s27, s86, s90
	s_add_u32 s24, s28, 0x80
	s_addc_u32 s25, s29, 0
	ds_read_b128 v[184:187], v167
	ds_read_b128 v[188:191], v167 offset:1024
	ds_read_b128 v[194:197], v167 offset:2048
	ds_read_b128 v[198:201], v167 offset:3072
	ds_read_b128 v[202:205], v167 offset:4096
	ds_read_b128 v[206:209], v167 offset:5120
	ds_read_b128 v[210:213], v167 offset:6144
	ds_read_b128 v[214:217], v167 offset:7168
	s_add_u32 s96, s79, 0x83f80
	s_addc_u32 s97, s88, 0
	s_mov_b32 m0, s57
	s_nop 0
	global_load_lds_dwordx4 v147, s[96:97]
	s_mov_b32 m0, s58
	s_nop 0
	global_load_lds_dwordx4 v153, s[96:97]
	s_waitcnt vmcnt(8) lgkmcnt(0)
	s_setprio 1
	s_barrier
	v_mfma_f32_16x16x32_bf16 v[124:127], v[128:131], v[184:187], v[124:127]
	v_mfma_f32_16x16x32_bf16 v[120:123], v[136:139], v[184:187], v[120:123]
	v_mfma_f32_16x16x32_bf16 v[108:111], v[128:131], v[194:197], v[108:111]
	v_mfma_f32_16x16x32_bf16 v[104:107], v[136:139], v[194:197], v[104:107]
	v_mfma_f32_16x16x32_bf16 v[92:95], v[128:131], v[202:205], v[92:95]
	v_mfma_f32_16x16x32_bf16 v[88:91], v[136:139], v[202:205], v[88:91]
	v_mfma_f32_16x16x32_bf16 v[76:79], v[128:131], v[210:213], v[76:79]
	v_mfma_f32_16x16x32_bf16 v[72:75], v[136:139], v[210:213], v[72:75]
	v_mfma_f32_16x16x32_bf16 v[124:127], v[132:135], v[188:191], v[124:127]
	v_mfma_f32_16x16x32_bf16 v[120:123], v[140:143], v[188:191], v[120:123]
	v_mfma_f32_16x16x32_bf16 v[108:111], v[132:135], v[198:201], v[108:111]
	v_mfma_f32_16x16x32_bf16 v[104:107], v[140:143], v[198:201], v[104:107]
	v_mfma_f32_16x16x32_bf16 v[92:95], v[132:135], v[206:209], v[92:95]
	v_mfma_f32_16x16x32_bf16 v[88:91], v[140:143], v[206:209], v[88:91]
	v_mfma_f32_16x16x32_bf16 v[76:79], v[132:135], v[214:217], v[76:79]
	v_mfma_f32_16x16x32_bf16 v[72:75], v[140:143], v[214:217], v[72:75]
	v_mfma_f32_16x16x32_bf16 v[116:119], v[168:171], v[184:187], v[116:119]
	v_mfma_f32_16x16x32_bf16 v[112:115], v[176:179], v[184:187], v[112:115]
	v_mfma_f32_16x16x32_bf16 v[100:103], v[168:171], v[194:197], v[100:103]
	v_mfma_f32_16x16x32_bf16 v[96:99], v[176:179], v[194:197], v[96:99]
	v_mfma_f32_16x16x32_bf16 v[84:87], v[168:171], v[202:205], v[84:87]
	v_mfma_f32_16x16x32_bf16 v[80:83], v[176:179], v[202:205], v[80:83]
	v_mfma_f32_16x16x32_bf16 v[68:71], v[168:171], v[210:213], v[68:71]
	v_mfma_f32_16x16x32_bf16 v[64:67], v[176:179], v[210:213], v[64:67]
	v_mfma_f32_16x16x32_bf16 v[116:119], v[172:175], v[188:191], v[116:119]
	v_mfma_f32_16x16x32_bf16 v[112:115], v[180:183], v[188:191], v[112:115]
	v_mfma_f32_16x16x32_bf16 v[100:103], v[172:175], v[198:201], v[100:103]
	v_mfma_f32_16x16x32_bf16 v[96:99], v[180:183], v[198:201], v[96:99]
	v_mfma_f32_16x16x32_bf16 v[84:87], v[172:175], v[206:209], v[84:87]
	v_mfma_f32_16x16x32_bf16 v[80:83], v[180:183], v[206:209], v[80:83]
	v_mfma_f32_16x16x32_bf16 v[68:71], v[172:175], v[214:217], v[68:71]
	v_mfma_f32_16x16x32_bf16 v[64:67], v[180:183], v[214:217], v[64:67]
	s_setprio 0
	s_barrier
	ds_read_b128 v[184:187], v167 offset:16384
	ds_read_b128 v[188:191], v167 offset:17408
	ds_read_b128 v[194:197], v167 offset:18432
	ds_read_b128 v[198:201], v167 offset:19456
	ds_read_b128 v[202:205], v167 offset:20480
	ds_read_b128 v[206:209], v167 offset:21504
	ds_read_b128 v[210:213], v167 offset:22528
	ds_read_b128 v[214:217], v167 offset:23552
	s_mov_b32 m0, s34
	s_nop 0
	global_load_lds_dwordx4 v151, s[26:27]
	s_add_u32 s96, s26, 0x80000
	s_mov_b32 m0, s35
	s_nop 0
	global_load_lds_dwordx4 v155, s[26:27]
	s_addc_u32 s97, s27, 0
	s_mov_b32 m0, s36
	s_nop 0
	global_load_lds_dwordx4 v151, s[96:97]
	s_mov_b32 m0, s37
	s_nop 0
	global_load_lds_dwordx4 v155, s[96:97]
	s_mov_b32 m0, s33
	s_nop 0
	global_load_lds_dwordx4 v147, s[28:29]
	s_mov_b32 m0, s44
	s_nop 0
	global_load_lds_dwordx4 v153, s[28:29]
	s_waitcnt vmcnt(8) lgkmcnt(0)
	s_setprio 1
	s_barrier
	v_mfma_f32_16x16x32_bf16 v[60:63], v[128:131], v[184:187], v[60:63]
	v_mfma_f32_16x16x32_bf16 v[56:59], v[136:139], v[184:187], v[56:59]
	v_mfma_f32_16x16x32_bf16 v[44:47], v[128:131], v[194:197], v[44:47]
	v_mfma_f32_16x16x32_bf16 v[40:43], v[136:139], v[194:197], v[40:43]
	v_mfma_f32_16x16x32_bf16 v[28:31], v[128:131], v[202:205], v[28:31]
	v_mfma_f32_16x16x32_bf16 v[24:27], v[136:139], v[202:205], v[24:27]
	v_mfma_f32_16x16x32_bf16 v[12:15], v[128:131], v[210:213], v[12:15]
	v_mfma_f32_16x16x32_bf16 v[8:11], v[136:139], v[210:213], v[8:11]
	v_mfma_f32_16x16x32_bf16 v[60:63], v[132:135], v[188:191], v[60:63]
	v_mfma_f32_16x16x32_bf16 v[56:59], v[140:143], v[188:191], v[56:59]
	v_mfma_f32_16x16x32_bf16 v[44:47], v[132:135], v[198:201], v[44:47]
	v_mfma_f32_16x16x32_bf16 v[40:43], v[140:143], v[198:201], v[40:43]
	v_mfma_f32_16x16x32_bf16 v[28:31], v[132:135], v[206:209], v[28:31]
	v_mfma_f32_16x16x32_bf16 v[24:27], v[140:143], v[206:209], v[24:27]
	v_mfma_f32_16x16x32_bf16 v[12:15], v[132:135], v[214:217], v[12:15]
	v_mfma_f32_16x16x32_bf16 v[8:11], v[140:143], v[214:217], v[8:11]
	v_mfma_f32_16x16x32_bf16 v[52:55], v[168:171], v[184:187], v[52:55]
	v_mfma_f32_16x16x32_bf16 v[48:51], v[176:179], v[184:187], v[48:51]
	v_mfma_f32_16x16x32_bf16 v[36:39], v[168:171], v[194:197], v[36:39]
	v_mfma_f32_16x16x32_bf16 v[32:35], v[176:179], v[194:197], v[32:35]
	v_mfma_f32_16x16x32_bf16 v[20:23], v[168:171], v[202:205], v[20:23]
	v_mfma_f32_16x16x32_bf16 v[16:19], v[176:179], v[202:205], v[16:19]
	v_mfma_f32_16x16x32_bf16 v[4:7], v[168:171], v[210:213], v[4:7]
	v_mfma_f32_16x16x32_bf16 v[0:3], v[176:179], v[210:213], v[0:3]
	v_mfma_f32_16x16x32_bf16 v[52:55], v[172:175], v[188:191], v[52:55]
	v_mfma_f32_16x16x32_bf16 v[48:51], v[180:183], v[188:191], v[48:51]
	v_mfma_f32_16x16x32_bf16 v[36:39], v[172:175], v[198:201], v[36:39]
	v_mfma_f32_16x16x32_bf16 v[32:35], v[180:183], v[198:201], v[32:35]
	v_mfma_f32_16x16x32_bf16 v[20:23], v[172:175], v[206:209], v[20:23]
	v_mfma_f32_16x16x32_bf16 v[16:19], v[180:183], v[206:209], v[16:19]
	v_mfma_f32_16x16x32_bf16 v[4:7], v[172:175], v[214:217], v[4:7]
	v_mfma_f32_16x16x32_bf16 v[0:3], v[180:183], v[214:217], v[0:3]
	s_setprio 0
	s_barrier
; #define PG8_STAGE(bufoff, gbase, voff) do { _Pragma("unroll") for (int _i = 0; _i < 2; ++_i) \
;         asm volatile("s_mov_b32 m0, %0\n\ts_nop 0\n\tglobal_load_lds_dwordx4 %1, %2" :: "s"(ldsb + (unsigned)((bufoff) + _i * 8192)), "v"((voff)[_i]), "s"(gbase) : "m0", "memory"); } while (0)
; #define PG8_LDA(dst, b, h) do { _Pragma("unroll") for (int m = 0; m < 4; ++m) _Pragma("unroll") for (int k = 0; k < 2; ++k) dst[m][k] = *(const PG8_LAS bf16x8*)(lds + PG8_SA(b, h) + aoff + m * 2048 + k * 1024); } while (0)
; #define PG8_LDB(dst, b, h) do { _Pragma("unroll") for (int n = 0; n < 2; ++n) _Pragma("unroll") for (int k = 0; k < 2; ++k) dst[n][k] = *(const PG8_LAS bf16x8*)(lds + PG8_SB(b, h) + boff + n * 2048 + k * 1024); } while (0)
; #define PG8_MMA(ai, bj, At, Bt) do { __builtin_amdgcn_s_setprio(1); _Pragma("unroll") for (int m = 0; m < 4; ++m) _Pragma("unroll") for (int n = 0; n < 2; ++n) _Pragma("unroll") for (int k = 0; k < 2; ++k) \
;         acc[ai][bj][m][n] = __builtin_amdgcn_mfma_f32_16x16x32_bf16(Bt[n][k], At[m][k], acc[ai][bj][m][n], 0, 0, 0); __builtin_amdgcn_s_setprio(0); } while (0)
; #define PG8_WAIT_V(n) asm volatile("s_waitcnt vmcnt(" #n ")" ::: "memory")
; #define PG8_WAIT_L(n) asm volatile("s_waitcnt lgkmcnt(" #n ")" ::: "memory")
; #define PG8_BAR __builtin_amdgcn_s_barrier()
; #define PG8_SCHED __builtin_amdgcn_sched_barrier(0)
; template <class Epi, class Sched, bool ALIGN_EPI = false, bool SP2 = false>
; __device__ __forceinline__ void gemm_phase(PG8_LAS unsigned char* lds, const Gemm g, const Sched& S, const Epi& E, const int wv) {
;     ...
;         for (int t = 0; t < nt; t += 2) {
;     ...
;             PG8_LDB(B0, 1, 0); PG8_LDB(B1, 1, 1); PG8_SCHED; PG8_LDA(At, 1, 0); PG8_STAGE(PG8_SA(0, 1), a2 + hstepA, voffA);
;             PG8_WAIT_V(8); PG8_WAIT_L(0); PG8_BAR; PG8_MMA(0, 0, At, B0); PG8_MMA(0, 1, At, B1); PG8_BAR; PG8_SCHED;
;             PG8_LDA(At, 1, 1); PG8_STAGE(PG8_SB(1, 0), b3, voffB); PG8_STAGE(PG8_SB(1, 1), b3 + hstepB, voffB); PG8_STAGE(PG8_SA(1, 0), a3, voffA);
;             PG8_WAIT_V(8); PG8_WAIT_L(0); PG8_BAR; PG8_MMA(1, 0, At, B0); PG8_MMA(1, 1, At, B1); PG8_BAR; PG8_SCHED;
	v_add_u32_e32 v140, 0x18000, v166
	v_add_u32_e32 v148, 0x1c000, v166
	ds_read_b128 v[128:131], v140
	ds_read_b128 v[132:135], v140 offset:1024
	ds_read_b128 v[136:139], v140 offset:2048
	ds_read_b128 v[140:143], v140 offset:3072
	ds_read_b128 v[168:171], v148
	ds_read_b128 v[172:175], v148 offset:1024
	ds_read_b128 v[176:179], v148 offset:2048
	ds_read_b128 v[180:183], v148 offset:3072
	ds_read_b128 v[184:187], v167 offset:32768
	ds_read_b128 v[188:191], v167 offset:33792
	ds_read_b128 v[194:197], v167 offset:34816
	ds_read_b128 v[198:201], v167 offset:35840
	ds_read_b128 v[202:205], v167 offset:36864
	ds_read_b128 v[206:209], v167 offset:37888
	ds_read_b128 v[210:213], v167 offset:38912
	ds_read_b128 v[214:217], v167 offset:39936
	s_add_u32 s28, s28, 0x84000
	s_addc_u32 s29, s29, 0
	s_mov_b32 m0, s45
	s_nop 0
	global_load_lds_dwordx4 v147, s[28:29]
	s_mov_b32 m0, s46
	s_nop 0
	global_load_lds_dwordx4 v153, s[28:29]
	s_waitcnt vmcnt(8) lgkmcnt(0)
	s_setprio 1
	s_barrier
	v_mfma_f32_16x16x32_bf16 v[124:127], v[128:131], v[184:187], v[124:127]
	v_mfma_f32_16x16x32_bf16 v[120:123], v[136:139], v[184:187], v[120:123]
	v_mfma_f32_16x16x32_bf16 v[108:111], v[128:131], v[194:197], v[108:111]
	v_mfma_f32_16x16x32_bf16 v[104:107], v[136:139], v[194:197], v[104:107]
	v_mfma_f32_16x16x32_bf16 v[92:95], v[128:131], v[202:205], v[92:95]
	v_mfma_f32_16x16x32_bf16 v[88:91], v[136:139], v[202:205], v[88:91]
	v_mfma_f32_16x16x32_bf16 v[76:79], v[128:131], v[210:213], v[76:79]
	v_mfma_f32_16x16x32_bf16 v[72:75], v[136:139], v[210:213], v[72:75]
	v_mfma_f32_16x16x32_bf16 v[124:127], v[132:135], v[188:191], v[124:127]
	v_mfma_f32_16x16x32_bf16 v[120:123], v[140:143], v[188:191], v[120:123]
	v_mfma_f32_16x16x32_bf16 v[108:111], v[132:135], v[198:201], v[108:111]
	v_mfma_f32_16x16x32_bf16 v[104:107], v[140:143], v[198:201], v[104:107]
	v_mfma_f32_16x16x32_bf16 v[92:95], v[132:135], v[206:209], v[92:95]
	v_mfma_f32_16x16x32_bf16 v[88:91], v[140:143], v[206:209], v[88:91]
	v_mfma_f32_16x16x32_bf16 v[76:79], v[132:135], v[214:217], v[76:79]
	v_mfma_f32_16x16x32_bf16 v[72:75], v[140:143], v[214:217], v[72:75]
	v_mfma_f32_16x16x32_bf16 v[116:119], v[168:171], v[184:187], v[116:119]
	v_mfma_f32_16x16x32_bf16 v[112:115], v[176:179], v[184:187], v[112:115]
	v_mfma_f32_16x16x32_bf16 v[100:103], v[168:171], v[194:197], v[100:103]
	v_mfma_f32_16x16x32_bf16 v[96:99], v[176:179], v[194:197], v[96:99]
	v_mfma_f32_16x16x32_bf16 v[84:87], v[168:171], v[202:205], v[84:87]
	v_mfma_f32_16x16x32_bf16 v[80:83], v[176:179], v[202:205], v[80:83]
	v_mfma_f32_16x16x32_bf16 v[68:71], v[168:171], v[210:213], v[68:71]
	v_mfma_f32_16x16x32_bf16 v[64:67], v[176:179], v[210:213], v[64:67]
	v_mfma_f32_16x16x32_bf16 v[116:119], v[172:175], v[188:191], v[116:119]
	v_mfma_f32_16x16x32_bf16 v[112:115], v[180:183], v[188:191], v[112:115]
	v_mfma_f32_16x16x32_bf16 v[100:103], v[172:175], v[198:201], v[100:103]
	v_mfma_f32_16x16x32_bf16 v[96:99], v[180:183], v[198:201], v[96:99]
	v_mfma_f32_16x16x32_bf16 v[84:87], v[172:175], v[206:209], v[84:87]
	v_mfma_f32_16x16x32_bf16 v[80:83], v[180:183], v[206:209], v[80:83]
	v_mfma_f32_16x16x32_bf16 v[68:71], v[172:175], v[214:217], v[68:71]
	v_mfma_f32_16x16x32_bf16 v[64:67], v[180:183], v[214:217], v[64:67]
	s_setprio 0
	s_barrier
	ds_read_b128 v[184:187], v167 offset:49152
	ds_read_b128 v[188:191], v167 offset:50176
	ds_read_b128 v[194:197], v167 offset:51200
	ds_read_b128 v[198:201], v167 offset:52224
	ds_read_b128 v[202:205], v167 offset:53248
	ds_read_b128 v[206:209], v167 offset:54272
	ds_read_b128 v[210:213], v167 offset:55296
	ds_read_b128 v[214:217], v167 offset:56320
	s_add_u32 s28, s26, 0x80
	s_addc_u32 s29, s27, 0
	s_mov_b32 m0, s51
	s_nop 0
	global_load_lds_dwordx4 v151, s[28:29]
	s_add_u32 s26, s26, 0x80080
	s_mov_b32 m0, s52
	s_nop 0
	global_load_lds_dwordx4 v155, s[28:29]
	s_addc_u32 s27, s27, 0
	s_mov_b32 m0, s55
	s_nop 0
	global_load_lds_dwordx4 v151, s[26:27]
	s_mov_b32 m0, s56
	s_nop 0
	global_load_lds_dwordx4 v155, s[26:27]
	s_mov_b32 m0, s53
	s_nop 0
	global_load_lds_dwordx4 v147, s[24:25]
	s_mov_b32 m0, s54
	s_nop 0
	global_load_lds_dwordx4 v153, s[24:25]
	s_waitcnt vmcnt(8) lgkmcnt(0)
	s_setprio 1
	s_barrier
	v_mfma_f32_16x16x32_bf16 v[60:63], v[128:131], v[184:187], v[60:63]
	v_mfma_f32_16x16x32_bf16 v[56:59], v[136:139], v[184:187], v[56:59]
	v_mfma_f32_16x16x32_bf16 v[44:47], v[128:131], v[194:197], v[44:47]
	v_mfma_f32_16x16x32_bf16 v[40:43], v[136:139], v[194:197], v[40:43]
	v_mfma_f32_16x16x32_bf16 v[28:31], v[128:131], v[202:205], v[28:31]
	v_mfma_f32_16x16x32_bf16 v[24:27], v[136:139], v[202:205], v[24:27]
	v_mfma_f32_16x16x32_bf16 v[12:15], v[128:131], v[210:213], v[12:15]
	v_mfma_f32_16x16x32_bf16 v[8:11], v[136:139], v[210:213], v[8:11]
	v_mfma_f32_16x16x32_bf16 v[60:63], v[132:135], v[188:191], v[60:63]
	v_mfma_f32_16x16x32_bf16 v[56:59], v[140:143], v[188:191], v[56:59]
	v_mfma_f32_16x16x32_bf16 v[44:47], v[132:135], v[198:201], v[44:47]
	v_mfma_f32_16x16x32_bf16 v[40:43], v[140:143], v[198:201], v[40:43]
	v_mfma_f32_16x16x32_bf16 v[28:31], v[132:135], v[206:209], v[28:31]
	v_mfma_f32_16x16x32_bf16 v[24:27], v[140:143], v[206:209], v[24:27]
	v_mfma_f32_16x16x32_bf16 v[12:15], v[132:135], v[214:217], v[12:15]
	v_mfma_f32_16x16x32_bf16 v[8:11], v[140:143], v[214:217], v[8:11]
	v_mfma_f32_16x16x32_bf16 v[52:55], v[168:171], v[184:187], v[52:55]
	v_mfma_f32_16x16x32_bf16 v[48:51], v[176:179], v[184:187], v[48:51]
	v_mfma_f32_16x16x32_bf16 v[36:39], v[168:171], v[194:197], v[36:39]
	v_mfma_f32_16x16x32_bf16 v[32:35], v[176:179], v[194:197], v[32:35]
	v_mfma_f32_16x16x32_bf16 v[20:23], v[168:171], v[202:205], v[20:23]
	v_mfma_f32_16x16x32_bf16 v[16:19], v[176:179], v[202:205], v[16:19]
	v_mfma_f32_16x16x32_bf16 v[4:7], v[168:171], v[210:213], v[4:7]
	v_mfma_f32_16x16x32_bf16 v[0:3], v[176:179], v[210:213], v[0:3]
	v_mfma_f32_16x16x32_bf16 v[52:55], v[172:175], v[188:191], v[52:55]
	v_mfma_f32_16x16x32_bf16 v[48:51], v[180:183], v[188:191], v[48:51]
	v_mfma_f32_16x16x32_bf16 v[36:39], v[172:175], v[198:201], v[36:39]
	v_mfma_f32_16x16x32_bf16 v[32:35], v[180:183], v[198:201], v[32:35]
	v_mfma_f32_16x16x32_bf16 v[20:23], v[172:175], v[206:209], v[20:23]
	v_mfma_f32_16x16x32_bf16 v[16:19], v[180:183], v[206:209], v[16:19]
	v_mfma_f32_16x16x32_bf16 v[4:7], v[172:175], v[214:217], v[4:7]
	v_mfma_f32_16x16x32_bf16 v[0:3], v[180:183], v[214:217], v[0:3]
	s_setprio 0
	s_barrier
	s_add_u32 s79, s79, 0x100
	s_addc_u32 s88, s88, 0
	s_add_u32 s89, s89, 0x100
	s_addc_u32 s90, s90, 0
	s_cmp_ge_i32 s92, s85
	s_mov_b32 s24, s92
	s_cbranch_scc0 .LBB0_563
	v_readlane_b32 s96, v254, 47
	v_readlane_b32 s97, v254, 48
	v_readlane_b32 s90, v254, 52
	s_mov_b32 s79, 0xc00000
	s_branch .LBB0_566

; #define PG8_STAGE(bufoff, gbase, voff) do { _Pragma("unroll") for (int _i = 0; _i < 2; ++_i) \
;         asm volatile("s_mov_b32 m0, %0\n\ts_nop 0\n\tglobal_load_lds_dwordx4 %1, %2" :: "s"(ldsb + (unsigned)((bufoff) + _i * 8192)), "v"((voff)[_i]), "s"(gbase) : "m0", "memory"); } while (0)
; #define PG8_LDA(dst, b, h) do { _Pragma("unroll") for (int m = 0; m < 4; ++m) _Pragma("unroll") for (int k = 0; k < 2; ++k) dst[m][k] = *(const PG8_LAS bf16x8*)(lds + PG8_SA(b, h) + aoff + m * 2048 + k * 1024); } while (0)
; #define PG8_WAIT_V(n) asm volatile("s_waitcnt vmcnt(" #n ")" ::: "memory")
; #define PG8_WAIT_L(n) asm volatile("s_waitcnt lgkmcnt(" #n ")" ::: "memory")
; template <class Epi, class Sched, bool ALIGN_EPI = false, bool SP2 = false>
; __device__ __forceinline__ void gemm_phase(PG8_LAS unsigned char* lds, const Gemm g, const Sched& S, const Epi& E, const int wv) {
;     ...
;         for (int t = 0; t < nt; t += 2) {
;             const bool last = (t == nt - 2);
;             const char* a1 = cA + (size_t)(t + 1) * kstep;
;             const char* a2 = last ? nA : cA + (size_t)(t + 2) * kstep; const char* b2 = last ? nB : cB + (size_t)(t + 2) * kstep;
;             const char* a3 = a2 + kstep; const char* b3 = b2 + kstep;
;             if (last && has_next) S.a_ready(nxt);
;             if constexpr (SP2) {
;             PG8_LDB(B0, 0, 0); PG8_LDB(B1, 0, 1); PG8_SCHED; PG8_LDA(At, 0, 0); PG8_STAGE(PG8_SA(1, 1), a1 + hstepA, voffA);
;             PG8_WAIT_V(8); PG8_WAIT_L(0); PG8_BAR; PG8_MMA(0, 0, At, B0); PG8_MMA(0, 1, At, B1); PG8_BAR; PG8_SCHED;
;             PG8_LDA(At, 0, 1); PG8_STAGE(PG8_SB(0, 0), b2, voffB); PG8_STAGE(PG8_SB(0, 1), b2 + hstepB, voffB); PG8_STAGE(PG8_SA(0, 0), a2, voffA);
;             PG8_WAIT_V(8); PG8_WAIT_L(0); PG8_BAR; PG8_MMA(1, 0, At, B0); PG8_MMA(1, 1, At, B1); PG8_BAR; PG8_SCHED;
;             PG8_LDB(B0, 1, 0); PG8_LDB(B1, 1, 1); PG8_SCHED; PG8_LDA(At, 1, 0); PG8_STAGE(PG8_SA(0, 1), a2 + hstepA, voffA);
;             PG8_WAIT_V(8); PG8_WAIT_L(0); PG8_BAR; PG8_MMA(0, 0, At, B0); PG8_MMA(0, 1, At, B1); PG8_BAR; PG8_SCHED;
;             PG8_LDA(At, 1, 1); PG8_STAGE(PG8_SB(1, 0), b3, voffB); PG8_STAGE(PG8_SB(1, 1), b3 + hstepB, voffB); PG8_STAGE(PG8_SA(1, 0), a3, voffA);
;             PG8_WAIT_V(8); PG8_WAIT_L(0); PG8_BAR; PG8_MMA(1, 0, At, B0); PG8_MMA(1, 1, At, B1); PG8_BAR; PG8_SCHED;
.LBB0_756:
	v_add_u32_e32 v141, 0x10000, v139
	ds_read_b128 v[142:145], v141
	ds_read_b128 v[146:149], v141 offset:1024
	ds_read_b128 v[150:153], v141 offset:2048
	ds_read_b128 v[154:157], v141 offset:3072
	v_add_u32_e32 v141, 0x14000, v139
	ds_read_b128 v[158:161], v141
	ds_read_b128 v[162:165], v141 offset:1024
	ds_read_b128 v[166:169], v141 offset:2048
	ds_read_b128 v[170:173], v141 offset:3072
	s_add_i32 s79, s24, 2
	s_cmp_eq_u32 s60, s24
	s_cselect_b32 s28, s18, s62
	s_cselect_b32 s29, s19, s65
	s_cselect_b32 s26, s58, s71
	s_cselect_b32 s27, s56, s77
	s_add_u32 s24, s28, 0x80
	s_addc_u32 s25, s29, 0
	ds_read_b128 v[174:177], v140
	ds_read_b128 v[178:181], v140 offset:1024
	ds_read_b128 v[182:185], v140 offset:2048
	ds_read_b128 v[186:189], v140 offset:3072
	ds_read_b128 v[194:197], v140 offset:4096
	ds_read_b128 v[198:201], v140 offset:5120
	ds_read_b128 v[202:205], v140 offset:6144
	ds_read_b128 v[206:209], v140 offset:7168
	s_add_u32 s88, s62, 0x1ff80
	s_addc_u32 s89, s65, 0
	s_mov_b32 m0, s55
	s_nop 0
	global_load_lds_dwordx4 v128, s[88:89]
	s_mov_b32 m0, s87
	s_nop 0
	global_load_lds_dwordx4 v130, s[88:89]
	s_waitcnt vmcnt(8) lgkmcnt(0)
	s_setprio 1
	s_barrier
	v_mfma_f32_16x16x32_bf16 v[124:127], v[142:145], v[174:177], v[124:127]
	v_mfma_f32_16x16x32_bf16 v[120:123], v[150:153], v[174:177], v[120:123]
	v_mfma_f32_16x16x32_bf16 v[116:119], v[142:145], v[182:185], v[116:119]
	v_mfma_f32_16x16x32_bf16 v[112:115], v[150:153], v[182:185], v[112:115]
	v_mfma_f32_16x16x32_bf16 v[108:111], v[142:145], v[194:197], v[108:111]
	v_mfma_f32_16x16x32_bf16 v[104:107], v[150:153], v[194:197], v[104:107]
	v_mfma_f32_16x16x32_bf16 v[100:103], v[142:145], v[202:205], v[100:103]
	v_mfma_f32_16x16x32_bf16 v[96:99], v[150:153], v[202:205], v[96:99]
	v_mfma_f32_16x16x32_bf16 v[124:127], v[146:149], v[178:181], v[124:127]
	v_mfma_f32_16x16x32_bf16 v[120:123], v[154:157], v[178:181], v[120:123]
	v_mfma_f32_16x16x32_bf16 v[116:119], v[146:149], v[186:189], v[116:119]
	v_mfma_f32_16x16x32_bf16 v[112:115], v[154:157], v[186:189], v[112:115]
	v_mfma_f32_16x16x32_bf16 v[108:111], v[146:149], v[198:201], v[108:111]
	v_mfma_f32_16x16x32_bf16 v[104:107], v[154:157], v[198:201], v[104:107]
	v_mfma_f32_16x16x32_bf16 v[100:103], v[146:149], v[206:209], v[100:103]
	v_mfma_f32_16x16x32_bf16 v[96:99], v[154:157], v[206:209], v[96:99]
	v_mfma_f32_16x16x32_bf16 v[60:63], v[158:161], v[174:177], v[60:63]
	v_mfma_f32_16x16x32_bf16 v[56:59], v[166:169], v[174:177], v[56:59]
	v_mfma_f32_16x16x32_bf16 v[52:55], v[158:161], v[182:185], v[52:55]
	v_mfma_f32_16x16x32_bf16 v[48:51], v[166:169], v[182:185], v[48:51]
	v_mfma_f32_16x16x32_bf16 v[44:47], v[158:161], v[194:197], v[44:47]
	v_mfma_f32_16x16x32_bf16 v[40:43], v[166:169], v[194:197], v[40:43]
	v_mfma_f32_16x16x32_bf16 v[36:39], v[158:161], v[202:205], v[36:39]
	v_mfma_f32_16x16x32_bf16 v[32:35], v[166:169], v[202:205], v[32:35]
	v_mfma_f32_16x16x32_bf16 v[60:63], v[162:165], v[178:181], v[60:63]
	v_mfma_f32_16x16x32_bf16 v[56:59], v[170:173], v[178:181], v[56:59]
	v_mfma_f32_16x16x32_bf16 v[52:55], v[162:165], v[186:189], v[52:55]
	v_mfma_f32_16x16x32_bf16 v[48:51], v[170:173], v[186:189], v[48:51]
	v_mfma_f32_16x16x32_bf16 v[44:47], v[162:165], v[198:201], v[44:47]
	v_mfma_f32_16x16x32_bf16 v[40:43], v[170:173], v[198:201], v[40:43]
	v_mfma_f32_16x16x32_bf16 v[36:39], v[162:165], v[206:209], v[36:39]
	v_mfma_f32_16x16x32_bf16 v[32:35], v[170:173], v[206:209], v[32:35]
	s_setprio 0
	s_barrier
	ds_read_b128 v[174:177], v140 offset:16384
	ds_read_b128 v[178:181], v140 offset:17408
	ds_read_b128 v[182:185], v140 offset:18432
	ds_read_b128 v[186:189], v140 offset:19456
	ds_read_b128 v[194:197], v140 offset:20480
	ds_read_b128 v[198:201], v140 offset:21504
	ds_read_b128 v[202:205], v140 offset:22528
	ds_read_b128 v[206:209], v140 offset:23552
	s_mov_b32 m0, s37
	s_nop 0
	global_load_lds_dwordx4 v129, s[26:27]
	s_add_u32 s88, s26, 0x20000
	s_mov_b32 m0, s42
	s_nop 0
	global_load_lds_dwordx4 v131, s[26:27]
	s_addc_u32 s89, s27, 0
	s_mov_b32 m0, s43
	s_nop 0
	global_load_lds_dwordx4 v129, s[88:89]
	s_mov_b32 m0, s44
	s_nop 0
	global_load_lds_dwordx4 v131, s[88:89]
	s_mov_b32 m0, s36
	s_nop 0
	global_load_lds_dwordx4 v128, s[28:29]
	s_mov_b32 m0, s45
	s_nop 0
	global_load_lds_dwordx4 v130, s[28:29]
	s_waitcnt vmcnt(8) lgkmcnt(0)
	s_setprio 1
	s_barrier
	v_mfma_f32_16x16x32_bf16 v[92:95], v[142:145], v[174:177], v[92:95]
	v_mfma_f32_16x16x32_bf16 v[88:91], v[150:153], v[174:177], v[88:91]
	v_mfma_f32_16x16x32_bf16 v[84:87], v[142:145], v[182:185], v[84:87]
	v_mfma_f32_16x16x32_bf16 v[80:83], v[150:153], v[182:185], v[80:83]
	v_mfma_f32_16x16x32_bf16 v[76:79], v[142:145], v[194:197], v[76:79]
	v_mfma_f32_16x16x32_bf16 v[72:75], v[150:153], v[194:197], v[72:75]
	v_mfma_f32_16x16x32_bf16 v[68:71], v[142:145], v[202:205], v[68:71]
	v_mfma_f32_16x16x32_bf16 v[64:67], v[150:153], v[202:205], v[64:67]
	v_mfma_f32_16x16x32_bf16 v[92:95], v[146:149], v[178:181], v[92:95]
	v_mfma_f32_16x16x32_bf16 v[88:91], v[154:157], v[178:181], v[88:91]
	v_mfma_f32_16x16x32_bf16 v[84:87], v[146:149], v[186:189], v[84:87]
	v_mfma_f32_16x16x32_bf16 v[80:83], v[154:157], v[186:189], v[80:83]
	v_mfma_f32_16x16x32_bf16 v[76:79], v[146:149], v[198:201], v[76:79]
	v_mfma_f32_16x16x32_bf16 v[72:75], v[154:157], v[198:201], v[72:75]
	v_mfma_f32_16x16x32_bf16 v[68:71], v[146:149], v[206:209], v[68:71]
	v_mfma_f32_16x16x32_bf16 v[64:67], v[154:157], v[206:209], v[64:67]
	v_mfma_f32_16x16x32_bf16 v[28:31], v[158:161], v[174:177], v[28:31]
	v_mfma_f32_16x16x32_bf16 v[24:27], v[166:169], v[174:177], v[24:27]
	v_mfma_f32_16x16x32_bf16 v[20:23], v[158:161], v[182:185], v[20:23]
	v_mfma_f32_16x16x32_bf16 v[16:19], v[166:169], v[182:185], v[16:19]
	v_mfma_f32_16x16x32_bf16 v[12:15], v[158:161], v[194:197], v[12:15]
	v_mfma_f32_16x16x32_bf16 v[8:11], v[166:169], v[194:197], v[8:11]
	v_mfma_f32_16x16x32_bf16 v[4:7], v[158:161], v[202:205], v[4:7]
	v_mfma_f32_16x16x32_bf16 v[0:3], v[166:169], v[202:205], v[0:3]
	v_mfma_f32_16x16x32_bf16 v[28:31], v[162:165], v[178:181], v[28:31]
	v_mfma_f32_16x16x32_bf16 v[24:27], v[170:173], v[178:181], v[24:27]
	v_mfma_f32_16x16x32_bf16 v[20:23], v[162:165], v[186:189], v[20:23]
	v_mfma_f32_16x16x32_bf16 v[16:19], v[170:173], v[186:189], v[16:19]
	v_mfma_f32_16x16x32_bf16 v[12:15], v[162:165], v[198:201], v[12:15]
	v_mfma_f32_16x16x32_bf16 v[8:11], v[170:173], v[198:201], v[8:11]
	v_mfma_f32_16x16x32_bf16 v[4:7], v[162:165], v[206:209], v[4:7]
	v_mfma_f32_16x16x32_bf16 v[0:3], v[170:173], v[206:209], v[0:3]
	s_setprio 0
	s_barrier
; #define PG8_STAGE(bufoff, gbase, voff) do { _Pragma("unroll") for (int _i = 0; _i < 2; ++_i) \
;         asm volatile("s_mov_b32 m0, %0\n\ts_nop 0\n\tglobal_load_lds_dwordx4 %1, %2" :: "s"(ldsb + (unsigned)((bufoff) + _i * 8192)), "v"((voff)[_i]), "s"(gbase) : "m0", "memory"); } while (0)
; #define PG8_LDA(dst, b, h) do { _Pragma("unroll") for (int m = 0; m < 4; ++m) _Pragma("unroll") for (int k = 0; k < 2; ++k) dst[m][k] = *(const PG8_LAS bf16x8*)(lds + PG8_SA(b, h) + aoff + m * 2048 + k * 1024); } while (0)
; #define PG8_LDB(dst, b, h) do { _Pragma("unroll") for (int n = 0; n < 2; ++n) _Pragma("unroll") for (int k = 0; k < 2; ++k) dst[n][k] = *(const PG8_LAS bf16x8*)(lds + PG8_SB(b, h) + boff + n * 2048 + k * 1024); } while (0)
; #define PG8_MMA(ai, bj, At, Bt) do { __builtin_amdgcn_s_setprio(1); _Pragma("unroll") for (int m = 0; m < 4; ++m) _Pragma("unroll") for (int n = 0; n < 2; ++n) _Pragma("unroll") for (int k = 0; k < 2; ++k) \
;         acc[ai][bj][m][n] = __builtin_amdgcn_mfma_f32_16x16x32_bf16(Bt[n][k], At[m][k], acc[ai][bj][m][n], 0, 0, 0); __builtin_amdgcn_s_setprio(0); } while (0)
; #define PG8_WAIT_V(n) asm volatile("s_waitcnt vmcnt(" #n ")" ::: "memory")
; #define PG8_WAIT_L(n) asm volatile("s_waitcnt lgkmcnt(" #n ")" ::: "memory")
; #define PG8_BAR __builtin_amdgcn_s_barrier()
; #define PG8_SCHED __builtin_amdgcn_sched_barrier(0)
; template <class Epi, class Sched, bool ALIGN_EPI = false, bool SP2 = false>
; __device__ __forceinline__ void gemm_phase(PG8_LAS unsigned char* lds, const Gemm g, const Sched& S, const Epi& E, const int wv) {
;     ...
;         for (int t = 0; t < nt; t += 2) {
;     ...
;             PG8_LDB(B0, 1, 0); PG8_LDB(B1, 1, 1); PG8_SCHED; PG8_LDA(At, 1, 0); PG8_STAGE(PG8_SA(0, 1), a2 + hstepA, voffA);
;             PG8_WAIT_V(8); PG8_WAIT_L(0); PG8_BAR; PG8_MMA(0, 0, At, B0); PG8_MMA(0, 1, At, B1); PG8_BAR; PG8_SCHED;
;             PG8_LDA(At, 1, 1); PG8_STAGE(PG8_SB(1, 0), b3, voffB); PG8_STAGE(PG8_SB(1, 1), b3 + hstepB, voffB); PG8_STAGE(PG8_SA(1, 0), a3, voffA);
;             PG8_WAIT_V(8); PG8_WAIT_L(0); PG8_BAR; PG8_MMA(1, 0, At, B0); PG8_MMA(1, 1, At, B1); PG8_BAR; PG8_SCHED;
	v_add_u32_e32 v141, 0x18000, v139
	ds_read_b128 v[142:145], v141
	ds_read_b128 v[146:149], v141 offset:1024
	ds_read_b128 v[150:153], v141 offset:2048
	ds_read_b128 v[154:157], v141 offset:3072
	v_add_u32_e32 v141, 0x1c000, v139
	ds_read_b128 v[158:161], v141
	ds_read_b128 v[162:165], v141 offset:1024
	ds_read_b128 v[166:169], v141 offset:2048
	ds_read_b128 v[170:173], v141 offset:3072
	ds_read_b128 v[174:177], v140 offset:32768
	ds_read_b128 v[178:181], v140 offset:33792
	ds_read_b128 v[182:185], v140 offset:34816
	ds_read_b128 v[186:189], v140 offset:35840
	ds_read_b128 v[194:197], v140 offset:36864
	ds_read_b128 v[198:201], v140 offset:37888
	ds_read_b128 v[202:205], v140 offset:38912
	ds_read_b128 v[206:209], v140 offset:39936
	s_add_u32 s28, s28, 0x20000
	s_addc_u32 s29, s29, 0
	s_mov_b32 m0, s46
	s_nop 0
	global_load_lds_dwordx4 v128, s[28:29]
	s_mov_b32 m0, s47
	s_nop 0
	global_load_lds_dwordx4 v130, s[28:29]
	s_waitcnt vmcnt(8) lgkmcnt(0)
	s_setprio 1
	s_barrier
	v_mfma_f32_16x16x32_bf16 v[124:127], v[142:145], v[174:177], v[124:127]
	v_mfma_f32_16x16x32_bf16 v[120:123], v[150:153], v[174:177], v[120:123]
	v_mfma_f32_16x16x32_bf16 v[116:119], v[142:145], v[182:185], v[116:119]
	v_mfma_f32_16x16x32_bf16 v[112:115], v[150:153], v[182:185], v[112:115]
	v_mfma_f32_16x16x32_bf16 v[108:111], v[142:145], v[194:197], v[108:111]
	v_mfma_f32_16x16x32_bf16 v[104:107], v[150:153], v[194:197], v[104:107]
	v_mfma_f32_16x16x32_bf16 v[100:103], v[142:145], v[202:205], v[100:103]
	v_mfma_f32_16x16x32_bf16 v[96:99], v[150:153], v[202:205], v[96:99]
	v_mfma_f32_16x16x32_bf16 v[124:127], v[146:149], v[178:181], v[124:127]
	v_mfma_f32_16x16x32_bf16 v[120:123], v[154:157], v[178:181], v[120:123]
	v_mfma_f32_16x16x32_bf16 v[116:119], v[146:149], v[186:189], v[116:119]
	v_mfma_f32_16x16x32_bf16 v[112:115], v[154:157], v[186:189], v[112:115]
	v_mfma_f32_16x16x32_bf16 v[108:111], v[146:149], v[198:201], v[108:111]
	v_mfma_f32_16x16x32_bf16 v[104:107], v[154:157], v[198:201], v[104:107]
	v_mfma_f32_16x16x32_bf16 v[100:103], v[146:149], v[206:209], v[100:103]
	v_mfma_f32_16x16x32_bf16 v[96:99], v[154:157], v[206:209], v[96:99]
	v_mfma_f32_16x16x32_bf16 v[60:63], v[158:161], v[174:177], v[60:63]
	v_mfma_f32_16x16x32_bf16 v[56:59], v[166:169], v[174:177], v[56:59]
	v_mfma_f32_16x16x32_bf16 v[52:55], v[158:161], v[182:185], v[52:55]
	v_mfma_f32_16x16x32_bf16 v[48:51], v[166:169], v[182:185], v[48:51]
	v_mfma_f32_16x16x32_bf16 v[44:47], v[158:161], v[194:197], v[44:47]
	v_mfma_f32_16x16x32_bf16 v[40:43], v[166:169], v[194:197], v[40:43]
	v_mfma_f32_16x16x32_bf16 v[36:39], v[158:161], v[202:205], v[36:39]
	v_mfma_f32_16x16x32_bf16 v[32:35], v[166:169], v[202:205], v[32:35]
	v_mfma_f32_16x16x32_bf16 v[60:63], v[162:165], v[178:181], v[60:63]
	v_mfma_f32_16x16x32_bf16 v[56:59], v[170:173], v[178:181], v[56:59]
	v_mfma_f32_16x16x32_bf16 v[52:55], v[162:165], v[186:189], v[52:55]
	v_mfma_f32_16x16x32_bf16 v[48:51], v[170:173], v[186:189], v[48:51]
	v_mfma_f32_16x16x32_bf16 v[44:47], v[162:165], v[198:201], v[44:47]
	v_mfma_f32_16x16x32_bf16 v[40:43], v[170:173], v[198:201], v[40:43]
	v_mfma_f32_16x16x32_bf16 v[36:39], v[162:165], v[206:209], v[36:39]
	v_mfma_f32_16x16x32_bf16 v[32:35], v[170:173], v[206:209], v[32:35]
	s_setprio 0
	s_barrier
	ds_read_b128 v[174:177], v140 offset:49152
	ds_read_b128 v[178:181], v140 offset:50176
	ds_read_b128 v[182:185], v140 offset:51200
	ds_read_b128 v[186:189], v140 offset:52224
	ds_read_b128 v[194:197], v140 offset:53248
	ds_read_b128 v[198:201], v140 offset:54272
	ds_read_b128 v[202:205], v140 offset:55296
	ds_read_b128 v[206:209], v140 offset:56320
	s_add_u32 s28, s26, 0x80
	s_addc_u32 s29, s27, 0
	s_mov_b32 m0, s49
	s_nop 0
	global_load_lds_dwordx4 v129, s[28:29]
	s_add_u32 s26, s26, 0x20080
	s_mov_b32 m0, s50
	s_nop 0
	global_load_lds_dwordx4 v131, s[28:29]
	s_addc_u32 s27, s27, 0
	s_mov_b32 m0, s53
	s_nop 0
	global_load_lds_dwordx4 v129, s[26:27]
	s_mov_b32 m0, s54
	s_nop 0
	global_load_lds_dwordx4 v131, s[26:27]
	s_mov_b32 m0, s51
	s_nop 0
	global_load_lds_dwordx4 v128, s[24:25]
	s_mov_b32 m0, s52
	s_nop 0
	global_load_lds_dwordx4 v130, s[24:25]
	s_waitcnt vmcnt(8) lgkmcnt(0)
	s_setprio 1
	s_barrier
	v_mfma_f32_16x16x32_bf16 v[92:95], v[142:145], v[174:177], v[92:95]
	v_mfma_f32_16x16x32_bf16 v[88:91], v[150:153], v[174:177], v[88:91]
	v_mfma_f32_16x16x32_bf16 v[84:87], v[142:145], v[182:185], v[84:87]
	v_mfma_f32_16x16x32_bf16 v[80:83], v[150:153], v[182:185], v[80:83]
	v_mfma_f32_16x16x32_bf16 v[76:79], v[142:145], v[194:197], v[76:79]
	v_mfma_f32_16x16x32_bf16 v[72:75], v[150:153], v[194:197], v[72:75]
	v_mfma_f32_16x16x32_bf16 v[68:71], v[142:145], v[202:205], v[68:71]
	v_mfma_f32_16x16x32_bf16 v[64:67], v[150:153], v[202:205], v[64:67]
	v_mfma_f32_16x16x32_bf16 v[92:95], v[146:149], v[178:181], v[92:95]
	v_mfma_f32_16x16x32_bf16 v[88:91], v[154:157], v[178:181], v[88:91]
	v_mfma_f32_16x16x32_bf16 v[84:87], v[146:149], v[186:189], v[84:87]
	v_mfma_f32_16x16x32_bf16 v[80:83], v[154:157], v[186:189], v[80:83]
	v_mfma_f32_16x16x32_bf16 v[76:79], v[146:149], v[198:201], v[76:79]
	v_mfma_f32_16x16x32_bf16 v[72:75], v[154:157], v[198:201], v[72:75]
	v_mfma_f32_16x16x32_bf16 v[68:71], v[146:149], v[206:209], v[68:71]
	v_mfma_f32_16x16x32_bf16 v[64:67], v[154:157], v[206:209], v[64:67]
	v_mfma_f32_16x16x32_bf16 v[28:31], v[158:161], v[174:177], v[28:31]
	v_mfma_f32_16x16x32_bf16 v[24:27], v[166:169], v[174:177], v[24:27]
	v_mfma_f32_16x16x32_bf16 v[20:23], v[158:161], v[182:185], v[20:23]
	v_mfma_f32_16x16x32_bf16 v[16:19], v[166:169], v[182:185], v[16:19]
	v_mfma_f32_16x16x32_bf16 v[12:15], v[158:161], v[194:197], v[12:15]
	v_mfma_f32_16x16x32_bf16 v[8:11], v[166:169], v[194:197], v[8:11]
	v_mfma_f32_16x16x32_bf16 v[4:7], v[158:161], v[202:205], v[4:7]
	v_mfma_f32_16x16x32_bf16 v[0:3], v[166:169], v[202:205], v[0:3]
	v_mfma_f32_16x16x32_bf16 v[28:31], v[162:165], v[178:181], v[28:31]
	v_mfma_f32_16x16x32_bf16 v[24:27], v[170:173], v[178:181], v[24:27]
	v_mfma_f32_16x16x32_bf16 v[20:23], v[162:165], v[186:189], v[20:23]
	v_mfma_f32_16x16x32_bf16 v[16:19], v[170:173], v[186:189], v[16:19]
	v_mfma_f32_16x16x32_bf16 v[12:15], v[162:165], v[198:201], v[12:15]
	v_mfma_f32_16x16x32_bf16 v[8:11], v[170:173], v[198:201], v[8:11]
	v_mfma_f32_16x16x32_bf16 v[4:7], v[162:165], v[206:209], v[4:7]
	v_mfma_f32_16x16x32_bf16 v[0:3], v[170:173], v[206:209], v[0:3]
	s_setprio 0
	s_barrier
	s_add_u32 s62, s62, 0x100
	s_addc_u32 s65, s65, 0
	s_add_u32 s71, s71, 0x100
	s_addc_u32 s77, s77, 0
	s_cmp_ge_i32 s79, s40
	s_mov_b32 s24, s79
	s_cbranch_scc0 .LBB0_756
	s_mov_b32 s79, 0xc00000
	s_and_b64 vcc, exec, s[14:15]
	s_cbranch_vccz .LBB0_759

; #define PG8_STAGE(bufoff, gbase, voff) do { _Pragma("unroll") for (int _i = 0; _i < 2; ++_i) \
;         asm volatile("s_mov_b32 m0, %0\n\ts_nop 0\n\tglobal_load_lds_dwordx4 %1, %2" :: "s"(ldsb + (unsigned)((bufoff) + _i * 8192)), "v"((voff)[_i]), "s"(gbase) : "m0", "memory"); } while (0)
; #define PG8_LDA(dst, b, h) do { _Pragma("unroll") for (int m = 0; m < 4; ++m) _Pragma("unroll") for (int k = 0; k < 2; ++k) dst[m][k] = *(const PG8_LAS bf16x8*)(lds + PG8_SA(b, h) + aoff + m * 2048 + k * 1024); } while (0)
; #define PG8_WAIT_V(n) asm volatile("s_waitcnt vmcnt(" #n ")" ::: "memory")
; #define PG8_WAIT_L(n) asm volatile("s_waitcnt lgkmcnt(" #n ")" ::: "memory")
; template <class Epi, class Sched, bool ALIGN_EPI = false, bool SP2 = false>
; __device__ __forceinline__ void gemm_phase(PG8_LAS unsigned char* lds, const Gemm g, const Sched& S, const Epi& E, const int wv) {
;     ...
;         for (int t = 0; t < nt; t += 2) {
;             const bool last = (t == nt - 2);
;             const char* a1 = cA + (size_t)(t + 1) * kstep;
;             const char* a2 = last ? nA : cA + (size_t)(t + 2) * kstep; const char* b2 = last ? nB : cB + (size_t)(t + 2) * kstep;
;             const char* a3 = a2 + kstep; const char* b3 = b2 + kstep;
;             if (last && has_next) S.a_ready(nxt);
;             if constexpr (SP2) {
;             PG8_LDB(B0, 0, 0); PG8_LDB(B1, 0, 1); PG8_SCHED; PG8_LDA(At, 0, 0); PG8_STAGE(PG8_SA(1, 1), a1 + hstepA, voffA);
;             PG8_WAIT_V(8); PG8_WAIT_L(0); PG8_BAR; PG8_MMA(0, 0, At, B0); PG8_MMA(0, 1, At, B1); PG8_BAR; PG8_SCHED;
;             PG8_LDA(At, 0, 1); PG8_STAGE(PG8_SB(0, 0), b2, voffB); PG8_STAGE(PG8_SB(0, 1), b2 + hstepB, voffB); PG8_STAGE(PG8_SA(0, 0), a2, voffA);
;             PG8_WAIT_V(8); PG8_WAIT_L(0); PG8_BAR; PG8_MMA(1, 0, At, B0); PG8_MMA(1, 1, At, B1); PG8_BAR; PG8_SCHED;
;             PG8_LDB(B0, 1, 0); PG8_LDB(B1, 1, 1); PG8_SCHED; PG8_LDA(At, 1, 0); PG8_STAGE(PG8_SA(0, 1), a2 + hstepA, voffA);
;             PG8_WAIT_V(8); PG8_WAIT_L(0); PG8_BAR; PG8_MMA(0, 0, At, B0); PG8_MMA(0, 1, At, B1); PG8_BAR; PG8_SCHED;
;             PG8_LDA(At, 1, 1); PG8_STAGE(PG8_SB(1, 0), b3, voffB); PG8_STAGE(PG8_SB(1, 1), b3 + hstepB, voffB); PG8_STAGE(PG8_SA(1, 0), a3, voffA);
;             PG8_WAIT_V(8); PG8_WAIT_L(0); PG8_BAR; PG8_MMA(1, 0, At, B0); PG8_MMA(1, 1, At, B1); PG8_BAR; PG8_SCHED;
.LBB0_810:
	v_add_u32_e32 v128, 0x10000, v136
	ds_read_b128 v[138:141], v128
	ds_read_b128 v[142:145], v128 offset:1024
	ds_read_b128 v[146:149], v128 offset:2048
	ds_read_b128 v[150:153], v128 offset:3072
	v_add_u32_e32 v128, 0x14000, v136
	ds_read_b128 v[154:157], v128
	ds_read_b128 v[158:161], v128 offset:1024
	ds_read_b128 v[162:165], v128 offset:2048
	ds_read_b128 v[166:169], v128 offset:3072
	s_add_i32 s85, s20, 2
	s_cmp_eq_u32 s62, s20
	s_cselect_b32 s24, s14, s77
	s_cselect_b32 s25, s15, s79
	s_cselect_b32 s22, s72, s83
	s_cselect_b32 s23, s71, s84
	s_add_u32 s20, s24, 0x80
	s_addc_u32 s21, s25, 0
	ds_read_b128 v[170:173], v137
	ds_read_b128 v[174:177], v137 offset:1024
	ds_read_b128 v[178:181], v137 offset:2048
	ds_read_b128 v[182:185], v137 offset:3072
	ds_read_b128 v[186:189], v137 offset:4096
	ds_read_b128 v[194:197], v137 offset:5120
	ds_read_b128 v[198:201], v137 offset:6144
	ds_read_b128 v[202:205], v137 offset:7168
	s_add_u32 s86, s77, 0xff80
	s_addc_u32 s87, s79, 0
	s_mov_b32 m0, s51
	s_nop 0
	global_load_lds_dwordx4 v130, s[86:87]
	s_mov_b32 m0, s52
	s_nop 0
	global_load_lds_dwordx4 v132, s[86:87]
	s_waitcnt vmcnt(8) lgkmcnt(0)
	s_setprio 1
	s_barrier
	v_mfma_f32_16x16x32_bf16 v[124:127], v[138:141], v[170:173], v[124:127]
	v_mfma_f32_16x16x32_bf16 v[120:123], v[146:149], v[170:173], v[120:123]
	v_mfma_f32_16x16x32_bf16 v[108:111], v[138:141], v[178:181], v[108:111]
	v_mfma_f32_16x16x32_bf16 v[104:107], v[146:149], v[178:181], v[104:107]
	v_mfma_f32_16x16x32_bf16 v[92:95], v[138:141], v[186:189], v[92:95]
	v_mfma_f32_16x16x32_bf16 v[88:91], v[146:149], v[186:189], v[88:91]
	v_mfma_f32_16x16x32_bf16 v[76:79], v[138:141], v[198:201], v[76:79]
	v_mfma_f32_16x16x32_bf16 v[72:75], v[146:149], v[198:201], v[72:75]
	v_mfma_f32_16x16x32_bf16 v[124:127], v[142:145], v[174:177], v[124:127]
	v_mfma_f32_16x16x32_bf16 v[120:123], v[150:153], v[174:177], v[120:123]
	v_mfma_f32_16x16x32_bf16 v[108:111], v[142:145], v[182:185], v[108:111]
	v_mfma_f32_16x16x32_bf16 v[104:107], v[150:153], v[182:185], v[104:107]
	v_mfma_f32_16x16x32_bf16 v[92:95], v[142:145], v[194:197], v[92:95]
	v_mfma_f32_16x16x32_bf16 v[88:91], v[150:153], v[194:197], v[88:91]
	v_mfma_f32_16x16x32_bf16 v[76:79], v[142:145], v[202:205], v[76:79]
	v_mfma_f32_16x16x32_bf16 v[72:75], v[150:153], v[202:205], v[72:75]
	v_mfma_f32_16x16x32_bf16 v[116:119], v[154:157], v[170:173], v[116:119]
	v_mfma_f32_16x16x32_bf16 v[112:115], v[162:165], v[170:173], v[112:115]
	v_mfma_f32_16x16x32_bf16 v[100:103], v[154:157], v[178:181], v[100:103]
	v_mfma_f32_16x16x32_bf16 v[96:99], v[162:165], v[178:181], v[96:99]
	v_mfma_f32_16x16x32_bf16 v[84:87], v[154:157], v[186:189], v[84:87]
	v_mfma_f32_16x16x32_bf16 v[80:83], v[162:165], v[186:189], v[80:83]
	v_mfma_f32_16x16x32_bf16 v[68:71], v[154:157], v[198:201], v[68:71]
	v_mfma_f32_16x16x32_bf16 v[64:67], v[162:165], v[198:201], v[64:67]
	v_mfma_f32_16x16x32_bf16 v[116:119], v[158:161], v[174:177], v[116:119]
	v_mfma_f32_16x16x32_bf16 v[112:115], v[166:169], v[174:177], v[112:115]
	v_mfma_f32_16x16x32_bf16 v[100:103], v[158:161], v[182:185], v[100:103]
	v_mfma_f32_16x16x32_bf16 v[96:99], v[166:169], v[182:185], v[96:99]
	v_mfma_f32_16x16x32_bf16 v[84:87], v[158:161], v[194:197], v[84:87]
	v_mfma_f32_16x16x32_bf16 v[80:83], v[166:169], v[194:197], v[80:83]
	v_mfma_f32_16x16x32_bf16 v[68:71], v[158:161], v[202:205], v[68:71]
	v_mfma_f32_16x16x32_bf16 v[64:67], v[166:169], v[202:205], v[64:67]
	s_setprio 0
	s_barrier
	ds_read_b128 v[170:173], v137 offset:16384
	ds_read_b128 v[174:177], v137 offset:17408
	ds_read_b128 v[178:181], v137 offset:18432
	ds_read_b128 v[182:185], v137 offset:19456
	ds_read_b128 v[186:189], v137 offset:20480
	ds_read_b128 v[194:197], v137 offset:21504
	ds_read_b128 v[198:201], v137 offset:22528
	ds_read_b128 v[202:205], v137 offset:23552
	s_mov_b32 m0, s33
	s_nop 0
	global_load_lds_dwordx4 v131, s[22:23]
	s_add_u32 s86, s22, 0x10000
	s_mov_b32 m0, s34
	s_nop 0
	global_load_lds_dwordx4 v133, s[22:23]
	s_addc_u32 s87, s23, 0
	s_mov_b32 m0, s35
	s_nop 0
	global_load_lds_dwordx4 v131, s[86:87]
	s_mov_b32 m0, s36
	s_nop 0
	global_load_lds_dwordx4 v133, s[86:87]
	s_mov_b32 m0, s31
	s_nop 0
	global_load_lds_dwordx4 v130, s[24:25]
	s_mov_b32 m0, s37
	s_nop 0
	global_load_lds_dwordx4 v132, s[24:25]
	s_waitcnt vmcnt(8) lgkmcnt(0)
	s_setprio 1
	s_barrier
	v_mfma_f32_16x16x32_bf16 v[60:63], v[138:141], v[170:173], v[60:63]
	v_mfma_f32_16x16x32_bf16 v[56:59], v[146:149], v[170:173], v[56:59]
	v_mfma_f32_16x16x32_bf16 v[44:47], v[138:141], v[178:181], v[44:47]
	v_mfma_f32_16x16x32_bf16 v[40:43], v[146:149], v[178:181], v[40:43]
	v_mfma_f32_16x16x32_bf16 v[28:31], v[138:141], v[186:189], v[28:31]
	v_mfma_f32_16x16x32_bf16 v[24:27], v[146:149], v[186:189], v[24:27]
	v_mfma_f32_16x16x32_bf16 v[12:15], v[138:141], v[198:201], v[12:15]
	v_mfma_f32_16x16x32_bf16 v[8:11], v[146:149], v[198:201], v[8:11]
	v_mfma_f32_16x16x32_bf16 v[60:63], v[142:145], v[174:177], v[60:63]
	v_mfma_f32_16x16x32_bf16 v[56:59], v[150:153], v[174:177], v[56:59]
	v_mfma_f32_16x16x32_bf16 v[44:47], v[142:145], v[182:185], v[44:47]
	v_mfma_f32_16x16x32_bf16 v[40:43], v[150:153], v[182:185], v[40:43]
	v_mfma_f32_16x16x32_bf16 v[28:31], v[142:145], v[194:197], v[28:31]
	v_mfma_f32_16x16x32_bf16 v[24:27], v[150:153], v[194:197], v[24:27]
	v_mfma_f32_16x16x32_bf16 v[12:15], v[142:145], v[202:205], v[12:15]
	v_mfma_f32_16x16x32_bf16 v[8:11], v[150:153], v[202:205], v[8:11]
	v_mfma_f32_16x16x32_bf16 v[52:55], v[154:157], v[170:173], v[52:55]
	v_mfma_f32_16x16x32_bf16 v[48:51], v[162:165], v[170:173], v[48:51]
	v_mfma_f32_16x16x32_bf16 v[36:39], v[154:157], v[178:181], v[36:39]
	v_mfma_f32_16x16x32_bf16 v[32:35], v[162:165], v[178:181], v[32:35]
	v_mfma_f32_16x16x32_bf16 v[20:23], v[154:157], v[186:189], v[20:23]
	v_mfma_f32_16x16x32_bf16 v[16:19], v[162:165], v[186:189], v[16:19]
	v_mfma_f32_16x16x32_bf16 v[4:7], v[154:157], v[198:201], v[4:7]
	v_mfma_f32_16x16x32_bf16 v[0:3], v[162:165], v[198:201], v[0:3]
	v_mfma_f32_16x16x32_bf16 v[52:55], v[158:161], v[174:177], v[52:55]
	v_mfma_f32_16x16x32_bf16 v[48:51], v[166:169], v[174:177], v[48:51]
	v_mfma_f32_16x16x32_bf16 v[36:39], v[158:161], v[182:185], v[36:39]
	v_mfma_f32_16x16x32_bf16 v[32:35], v[166:169], v[182:185], v[32:35]
	v_mfma_f32_16x16x32_bf16 v[20:23], v[158:161], v[194:197], v[20:23]
	v_mfma_f32_16x16x32_bf16 v[16:19], v[166:169], v[194:197], v[16:19]
	v_mfma_f32_16x16x32_bf16 v[4:7], v[158:161], v[202:205], v[4:7]
	v_mfma_f32_16x16x32_bf16 v[0:3], v[166:169], v[202:205], v[0:3]
	s_setprio 0
	s_barrier
; #define PG8_STAGE(bufoff, gbase, voff) do { _Pragma("unroll") for (int _i = 0; _i < 2; ++_i) \
;         asm volatile("s_mov_b32 m0, %0\n\ts_nop 0\n\tglobal_load_lds_dwordx4 %1, %2" :: "s"(ldsb + (unsigned)((bufoff) + _i * 8192)), "v"((voff)[_i]), "s"(gbase) : "m0", "memory"); } while (0)
; #define PG8_LDA(dst, b, h) do { _Pragma("unroll") for (int m = 0; m < 4; ++m) _Pragma("unroll") for (int k = 0; k < 2; ++k) dst[m][k] = *(const PG8_LAS bf16x8*)(lds + PG8_SA(b, h) + aoff + m * 2048 + k * 1024); } while (0)
; #define PG8_LDB(dst, b, h) do { _Pragma("unroll") for (int n = 0; n < 2; ++n) _Pragma("unroll") for (int k = 0; k < 2; ++k) dst[n][k] = *(const PG8_LAS bf16x8*)(lds + PG8_SB(b, h) + boff + n * 2048 + k * 1024); } while (0)
; #define PG8_MMA(ai, bj, At, Bt) do { __builtin_amdgcn_s_setprio(1); _Pragma("unroll") for (int m = 0; m < 4; ++m) _Pragma("unroll") for (int n = 0; n < 2; ++n) _Pragma("unroll") for (int k = 0; k < 2; ++k) \
;         acc[ai][bj][m][n] = __builtin_amdgcn_mfma_f32_16x16x32_bf16(Bt[n][k], At[m][k], acc[ai][bj][m][n], 0, 0, 0); __builtin_amdgcn_s_setprio(0); } while (0)
; #define PG8_WAIT_V(n) asm volatile("s_waitcnt vmcnt(" #n ")" ::: "memory")
; #define PG8_WAIT_L(n) asm volatile("s_waitcnt lgkmcnt(" #n ")" ::: "memory")
; #define PG8_BAR __builtin_amdgcn_s_barrier()
; #define PG8_SCHED __builtin_amdgcn_sched_barrier(0)
; template <class Epi, class Sched, bool ALIGN_EPI = false, bool SP2 = false>
; __device__ __forceinline__ void gemm_phase(PG8_LAS unsigned char* lds, const Gemm g, const Sched& S, const Epi& E, const int wv) {
;     ...
;         for (int t = 0; t < nt; t += 2) {
;     ...
;             PG8_LDB(B0, 1, 0); PG8_LDB(B1, 1, 1); PG8_SCHED; PG8_LDA(At, 1, 0); PG8_STAGE(PG8_SA(0, 1), a2 + hstepA, voffA);
;             PG8_WAIT_V(8); PG8_WAIT_L(0); PG8_BAR; PG8_MMA(0, 0, At, B0); PG8_MMA(0, 1, At, B1); PG8_BAR; PG8_SCHED;
;             PG8_LDA(At, 1, 1); PG8_STAGE(PG8_SB(1, 0), b3, voffB); PG8_STAGE(PG8_SB(1, 1), b3 + hstepB, voffB); PG8_STAGE(PG8_SA(1, 0), a3, voffA);
;             PG8_WAIT_V(8); PG8_WAIT_L(0); PG8_BAR; PG8_MMA(1, 0, At, B0); PG8_MMA(1, 1, At, B1); PG8_BAR; PG8_SCHED;
	v_add_u32_e32 v128, 0x18000, v136
	ds_read_b128 v[138:141], v128
	ds_read_b128 v[142:145], v128 offset:1024
	ds_read_b128 v[146:149], v128 offset:2048
	ds_read_b128 v[150:153], v128 offset:3072
	v_add_u32_e32 v128, 0x1c000, v136
	ds_read_b128 v[154:157], v128
	ds_read_b128 v[158:161], v128 offset:1024
	ds_read_b128 v[162:165], v128 offset:2048
	ds_read_b128 v[166:169], v128 offset:3072
	ds_read_b128 v[170:173], v137 offset:32768
	ds_read_b128 v[174:177], v137 offset:33792
	ds_read_b128 v[178:181], v137 offset:34816
	ds_read_b128 v[182:185], v137 offset:35840
	ds_read_b128 v[186:189], v137 offset:36864
	ds_read_b128 v[194:197], v137 offset:37888
	ds_read_b128 v[198:201], v137 offset:38912
	ds_read_b128 v[202:205], v137 offset:39936
	s_add_u32 s24, s24, 0x10000
	s_addc_u32 s25, s25, 0
	s_mov_b32 m0, s42
	s_nop 0
	global_load_lds_dwordx4 v130, s[24:25]
	s_mov_b32 m0, s43
	s_nop 0
	global_load_lds_dwordx4 v132, s[24:25]
	s_waitcnt vmcnt(8) lgkmcnt(0)
	s_setprio 1
	s_barrier
	v_mfma_f32_16x16x32_bf16 v[124:127], v[138:141], v[170:173], v[124:127]
	v_mfma_f32_16x16x32_bf16 v[120:123], v[146:149], v[170:173], v[120:123]
	v_mfma_f32_16x16x32_bf16 v[108:111], v[138:141], v[178:181], v[108:111]
	v_mfma_f32_16x16x32_bf16 v[104:107], v[146:149], v[178:181], v[104:107]
	v_mfma_f32_16x16x32_bf16 v[92:95], v[138:141], v[186:189], v[92:95]
	v_mfma_f32_16x16x32_bf16 v[88:91], v[146:149], v[186:189], v[88:91]
	v_mfma_f32_16x16x32_bf16 v[76:79], v[138:141], v[198:201], v[76:79]
	v_mfma_f32_16x16x32_bf16 v[72:75], v[146:149], v[198:201], v[72:75]
	v_mfma_f32_16x16x32_bf16 v[124:127], v[142:145], v[174:177], v[124:127]
	v_mfma_f32_16x16x32_bf16 v[120:123], v[150:153], v[174:177], v[120:123]
	v_mfma_f32_16x16x32_bf16 v[108:111], v[142:145], v[182:185], v[108:111]
	v_mfma_f32_16x16x32_bf16 v[104:107], v[150:153], v[182:185], v[104:107]
	v_mfma_f32_16x16x32_bf16 v[92:95], v[142:145], v[194:197], v[92:95]
	v_mfma_f32_16x16x32_bf16 v[88:91], v[150:153], v[194:197], v[88:91]
	v_mfma_f32_16x16x32_bf16 v[76:79], v[142:145], v[202:205], v[76:79]
	v_mfma_f32_16x16x32_bf16 v[72:75], v[150:153], v[202:205], v[72:75]
	v_mfma_f32_16x16x32_bf16 v[116:119], v[154:157], v[170:173], v[116:119]
	v_mfma_f32_16x16x32_bf16 v[112:115], v[162:165], v[170:173], v[112:115]
	v_mfma_f32_16x16x32_bf16 v[100:103], v[154:157], v[178:181], v[100:103]
	v_mfma_f32_16x16x32_bf16 v[96:99], v[162:165], v[178:181], v[96:99]
	v_mfma_f32_16x16x32_bf16 v[84:87], v[154:157], v[186:189], v[84:87]
	v_mfma_f32_16x16x32_bf16 v[80:83], v[162:165], v[186:189], v[80:83]
	v_mfma_f32_16x16x32_bf16 v[68:71], v[154:157], v[198:201], v[68:71]
	v_mfma_f32_16x16x32_bf16 v[64:67], v[162:165], v[198:201], v[64:67]
	v_mfma_f32_16x16x32_bf16 v[116:119], v[158:161], v[174:177], v[116:119]
	v_mfma_f32_16x16x32_bf16 v[112:115], v[166:169], v[174:177], v[112:115]
	v_mfma_f32_16x16x32_bf16 v[100:103], v[158:161], v[182:185], v[100:103]
	v_mfma_f32_16x16x32_bf16 v[96:99], v[166:169], v[182:185], v[96:99]
	v_mfma_f32_16x16x32_bf16 v[84:87], v[158:161], v[194:197], v[84:87]
	v_mfma_f32_16x16x32_bf16 v[80:83], v[166:169], v[194:197], v[80:83]
	v_mfma_f32_16x16x32_bf16 v[68:71], v[158:161], v[202:205], v[68:71]
	v_mfma_f32_16x16x32_bf16 v[64:67], v[166:169], v[202:205], v[64:67]
	s_setprio 0
	s_barrier
	ds_read_b128 v[170:173], v137 offset:49152
	ds_read_b128 v[174:177], v137 offset:50176
	ds_read_b128 v[178:181], v137 offset:51200
	ds_read_b128 v[182:185], v137 offset:52224
	ds_read_b128 v[186:189], v137 offset:53248
	ds_read_b128 v[194:197], v137 offset:54272
	ds_read_b128 v[198:201], v137 offset:55296
	ds_read_b128 v[202:205], v137 offset:56320
	s_add_u32 s24, s22, 0x80
	s_addc_u32 s25, s23, 0
	s_mov_b32 m0, s45
	s_nop 0
	global_load_lds_dwordx4 v131, s[24:25]
	s_add_u32 s22, s22, 0x10080
	s_mov_b32 m0, s46
	s_nop 0
	global_load_lds_dwordx4 v133, s[24:25]
	s_addc_u32 s23, s23, 0
	s_mov_b32 m0, s49
	s_nop 0
	global_load_lds_dwordx4 v131, s[22:23]
	s_mov_b32 m0, s50
	s_nop 0
	global_load_lds_dwordx4 v133, s[22:23]
	s_mov_b32 m0, s47
	s_nop 0
	global_load_lds_dwordx4 v130, s[20:21]
	s_mov_b32 m0, s48
	s_nop 0
	global_load_lds_dwordx4 v132, s[20:21]
	s_waitcnt vmcnt(8) lgkmcnt(0)
	s_setprio 1
	s_barrier
	v_mfma_f32_16x16x32_bf16 v[60:63], v[138:141], v[170:173], v[60:63]
	v_mfma_f32_16x16x32_bf16 v[56:59], v[146:149], v[170:173], v[56:59]
	v_mfma_f32_16x16x32_bf16 v[44:47], v[138:141], v[178:181], v[44:47]
	v_mfma_f32_16x16x32_bf16 v[40:43], v[146:149], v[178:181], v[40:43]
	v_mfma_f32_16x16x32_bf16 v[28:31], v[138:141], v[186:189], v[28:31]
	v_mfma_f32_16x16x32_bf16 v[24:27], v[146:149], v[186:189], v[24:27]
	v_mfma_f32_16x16x32_bf16 v[12:15], v[138:141], v[198:201], v[12:15]
	v_mfma_f32_16x16x32_bf16 v[8:11], v[146:149], v[198:201], v[8:11]
	v_mfma_f32_16x16x32_bf16 v[60:63], v[142:145], v[174:177], v[60:63]
	v_mfma_f32_16x16x32_bf16 v[56:59], v[150:153], v[174:177], v[56:59]
	v_mfma_f32_16x16x32_bf16 v[44:47], v[142:145], v[182:185], v[44:47]
	v_mfma_f32_16x16x32_bf16 v[40:43], v[150:153], v[182:185], v[40:43]
	v_mfma_f32_16x16x32_bf16 v[28:31], v[142:145], v[194:197], v[28:31]
	v_mfma_f32_16x16x32_bf16 v[24:27], v[150:153], v[194:197], v[24:27]
	v_mfma_f32_16x16x32_bf16 v[12:15], v[142:145], v[202:205], v[12:15]
	v_mfma_f32_16x16x32_bf16 v[8:11], v[150:153], v[202:205], v[8:11]
	v_mfma_f32_16x16x32_bf16 v[52:55], v[154:157], v[170:173], v[52:55]
	v_mfma_f32_16x16x32_bf16 v[48:51], v[162:165], v[170:173], v[48:51]
	v_mfma_f32_16x16x32_bf16 v[36:39], v[154:157], v[178:181], v[36:39]
	v_mfma_f32_16x16x32_bf16 v[32:35], v[162:165], v[178:181], v[32:35]
	v_mfma_f32_16x16x32_bf16 v[20:23], v[154:157], v[186:189], v[20:23]
	v_mfma_f32_16x16x32_bf16 v[16:19], v[162:165], v[186:189], v[16:19]
	v_mfma_f32_16x16x32_bf16 v[4:7], v[154:157], v[198:201], v[4:7]
	v_mfma_f32_16x16x32_bf16 v[0:3], v[162:165], v[198:201], v[0:3]
	v_mfma_f32_16x16x32_bf16 v[52:55], v[158:161], v[174:177], v[52:55]
	v_mfma_f32_16x16x32_bf16 v[48:51], v[166:169], v[174:177], v[48:51]
	v_mfma_f32_16x16x32_bf16 v[36:39], v[158:161], v[182:185], v[36:39]
	v_mfma_f32_16x16x32_bf16 v[32:35], v[166:169], v[182:185], v[32:35]
	v_mfma_f32_16x16x32_bf16 v[20:23], v[158:161], v[194:197], v[20:23]
	v_mfma_f32_16x16x32_bf16 v[16:19], v[166:169], v[194:197], v[16:19]
	v_mfma_f32_16x16x32_bf16 v[4:7], v[158:161], v[202:205], v[4:7]
	v_mfma_f32_16x16x32_bf16 v[0:3], v[166:169], v[202:205], v[0:3]
	s_setprio 0
	s_barrier
	s_add_u32 s77, s77, 0x100
	s_addc_u32 s79, s79, 0
	s_add_u32 s83, s83, 0x100
	s_addc_u32 s84, s84, 0
	s_cmp_ge_i32 s85, s65
	s_mov_b32 s20, s85
	s_cbranch_scc0 .LBB0_810
	s_mov_b32 s79, 0xc00000
	s_and_b64 vcc, exec, s[12:13]
	s_cbranch_vccz .LBB0_813

; #define PG8_STAGE(bufoff, gbase, voff) do { _Pragma("unroll") for (int _i = 0; _i < 2; ++_i) \
;         asm volatile("s_mov_b32 m0, %0\n\ts_nop 0\n\tglobal_load_lds_dwordx4 %1, %2" :: "s"(ldsb + (unsigned)((bufoff) + _i * 8192)), "v"((voff)[_i]), "s"(gbase) : "m0", "memory"); } while (0)
; #define PG8_LDA(dst, b, h) do { _Pragma("unroll") for (int m = 0; m < 4; ++m) _Pragma("unroll") for (int k = 0; k < 2; ++k) dst[m][k] = *(const PG8_LAS bf16x8*)(lds + PG8_SA(b, h) + aoff + m * 2048 + k * 1024); } while (0)
; #define PG8_WAIT_V(n) asm volatile("s_waitcnt vmcnt(" #n ")" ::: "memory")
; #define PG8_WAIT_L(n) asm volatile("s_waitcnt lgkmcnt(" #n ")" ::: "memory")
; template <class Epi, class Sched, bool ALIGN_EPI = false, bool SP2 = false>
; __device__ __forceinline__ void gemm_phase(PG8_LAS unsigned char* lds, const Gemm g, const Sched& S, const Epi& E, const int wv) {
;     ...
;         for (int t = 0; t < nt; t += 2) {
;             const bool last = (t == nt - 2);
;             const char* a1 = cA + (size_t)(t + 1) * kstep;
;             const char* a2 = last ? nA : cA + (size_t)(t + 2) * kstep; const char* b2 = last ? nB : cB + (size_t)(t + 2) * kstep;
;             const char* a3 = a2 + kstep; const char* b3 = b2 + kstep;
;             if (last && has_next) S.a_ready(nxt);
;             if constexpr (SP2) {
;             PG8_LDB(B0, 0, 0); PG8_LDB(B1, 0, 1); PG8_SCHED; PG8_LDA(At, 0, 0); PG8_STAGE(PG8_SA(1, 1), a1 + hstepA, voffA);
;             PG8_WAIT_V(8); PG8_WAIT_L(0); PG8_BAR; PG8_MMA(0, 0, At, B0); PG8_MMA(0, 1, At, B1); PG8_BAR; PG8_SCHED;
;             PG8_LDA(At, 0, 1); PG8_STAGE(PG8_SB(0, 0), b2, voffB); PG8_STAGE(PG8_SB(0, 1), b2 + hstepB, voffB); PG8_STAGE(PG8_SA(0, 0), a2, voffA);
;             PG8_WAIT_V(8); PG8_WAIT_L(0); PG8_BAR; PG8_MMA(1, 0, At, B0); PG8_MMA(1, 1, At, B1); PG8_BAR; PG8_SCHED;
;             PG8_LDB(B0, 1, 0); PG8_LDB(B1, 1, 1); PG8_SCHED; PG8_LDA(At, 1, 0); PG8_STAGE(PG8_SA(0, 1), a2 + hstepA, voffA);
;             PG8_WAIT_V(8); PG8_WAIT_L(0); PG8_BAR; PG8_MMA(0, 0, At, B0); PG8_MMA(0, 1, At, B1); PG8_BAR; PG8_SCHED;
;             PG8_LDA(At, 1, 1); PG8_STAGE(PG8_SB(1, 0), b3, voffB); PG8_STAGE(PG8_SB(1, 1), b3 + hstepB, voffB); PG8_STAGE(PG8_SA(1, 0), a3, voffA);
;             PG8_WAIT_V(8); PG8_WAIT_L(0); PG8_BAR; PG8_MMA(1, 0, At, B0); PG8_MMA(1, 1, At, B1); PG8_BAR; PG8_SCHED;
.LBB0_864:
	v_add_u32_e32 v137, 0x10000, v134
	ds_read_b128 v[138:141], v137
	ds_read_b128 v[142:145], v137 offset:1024
	ds_read_b128 v[146:149], v137 offset:2048
	ds_read_b128 v[150:153], v137 offset:3072
	v_add_u32_e32 v137, 0x14000, v134
	ds_read_b128 v[154:157], v137
	ds_read_b128 v[158:161], v137 offset:1024
	ds_read_b128 v[162:165], v137 offset:2048
	ds_read_b128 v[166:169], v137 offset:3072
	s_add_i32 s72, s18, 2
	s_cmp_eq_u32 s58, s18
	s_cselect_b32 s22, s12, s60
	s_cselect_b32 s23, s13, s62
	s_cselect_b32 s20, s57, s65
	s_cselect_b32 s21, s56, s71
	s_add_u32 s18, s22, 0x80
	s_addc_u32 s19, s23, 0
	ds_read_b128 v[170:173], v135
	ds_read_b128 v[174:177], v135 offset:1024
	ds_read_b128 v[178:181], v135 offset:2048
	ds_read_b128 v[182:185], v135 offset:3072
	ds_read_b128 v[186:189], v135 offset:4096
	ds_read_b128 v[194:197], v135 offset:5120
	ds_read_b128 v[198:201], v135 offset:6144
	ds_read_b128 v[202:205], v135 offset:7168
	s_add_u32 s84, s60, 0x1ff80
	s_addc_u32 s85, s62, 0
	s_mov_b32 m0, s45
	s_nop 0
	global_load_lds_dwordx4 v128, s[84:85]
	s_mov_b32 m0, s46
	s_nop 0
	global_load_lds_dwordx4 v130, s[84:85]
	s_waitcnt vmcnt(8) lgkmcnt(0)
	s_setprio 1
	s_barrier
	v_mfma_f32_16x16x32_bf16 v[124:127], v[138:141], v[170:173], v[124:127]
	v_mfma_f32_16x16x32_bf16 v[120:123], v[146:149], v[170:173], v[120:123]
	v_mfma_f32_16x16x32_bf16 v[108:111], v[138:141], v[178:181], v[108:111]
	v_mfma_f32_16x16x32_bf16 v[104:107], v[146:149], v[178:181], v[104:107]
	v_mfma_f32_16x16x32_bf16 v[92:95], v[138:141], v[186:189], v[92:95]
	v_mfma_f32_16x16x32_bf16 v[88:91], v[146:149], v[186:189], v[88:91]
	v_mfma_f32_16x16x32_bf16 v[76:79], v[138:141], v[198:201], v[76:79]
	v_mfma_f32_16x16x32_bf16 v[72:75], v[146:149], v[198:201], v[72:75]
	v_mfma_f32_16x16x32_bf16 v[124:127], v[142:145], v[174:177], v[124:127]
	v_mfma_f32_16x16x32_bf16 v[120:123], v[150:153], v[174:177], v[120:123]
	v_mfma_f32_16x16x32_bf16 v[108:111], v[142:145], v[182:185], v[108:111]
	v_mfma_f32_16x16x32_bf16 v[104:107], v[150:153], v[182:185], v[104:107]
	v_mfma_f32_16x16x32_bf16 v[92:95], v[142:145], v[194:197], v[92:95]
	v_mfma_f32_16x16x32_bf16 v[88:91], v[150:153], v[194:197], v[88:91]
	v_mfma_f32_16x16x32_bf16 v[76:79], v[142:145], v[202:205], v[76:79]
	v_mfma_f32_16x16x32_bf16 v[72:75], v[150:153], v[202:205], v[72:75]
	v_mfma_f32_16x16x32_bf16 v[116:119], v[154:157], v[170:173], v[116:119]
	v_mfma_f32_16x16x32_bf16 v[112:115], v[162:165], v[170:173], v[112:115]
	v_mfma_f32_16x16x32_bf16 v[100:103], v[154:157], v[178:181], v[100:103]
	v_mfma_f32_16x16x32_bf16 v[96:99], v[162:165], v[178:181], v[96:99]
	v_mfma_f32_16x16x32_bf16 v[84:87], v[154:157], v[186:189], v[84:87]
	v_mfma_f32_16x16x32_bf16 v[80:83], v[162:165], v[186:189], v[80:83]
	v_mfma_f32_16x16x32_bf16 v[68:71], v[154:157], v[198:201], v[68:71]
	v_mfma_f32_16x16x32_bf16 v[64:67], v[162:165], v[198:201], v[64:67]
	v_mfma_f32_16x16x32_bf16 v[116:119], v[158:161], v[174:177], v[116:119]
	v_mfma_f32_16x16x32_bf16 v[112:115], v[166:169], v[174:177], v[112:115]
	v_mfma_f32_16x16x32_bf16 v[100:103], v[158:161], v[182:185], v[100:103]
	v_mfma_f32_16x16x32_bf16 v[96:99], v[166:169], v[182:185], v[96:99]
	v_mfma_f32_16x16x32_bf16 v[84:87], v[158:161], v[194:197], v[84:87]
	v_mfma_f32_16x16x32_bf16 v[80:83], v[166:169], v[194:197], v[80:83]
	v_mfma_f32_16x16x32_bf16 v[68:71], v[158:161], v[202:205], v[68:71]
	v_mfma_f32_16x16x32_bf16 v[64:67], v[166:169], v[202:205], v[64:67]
	s_setprio 0
	s_barrier
	ds_read_b128 v[170:173], v135 offset:16384
	ds_read_b128 v[174:177], v135 offset:17408
	ds_read_b128 v[178:181], v135 offset:18432
	ds_read_b128 v[182:185], v135 offset:19456
	ds_read_b128 v[186:189], v135 offset:20480
	ds_read_b128 v[194:197], v135 offset:21504
	ds_read_b128 v[198:201], v135 offset:22528
	ds_read_b128 v[202:205], v135 offset:23552
	s_mov_b32 m0, s28
	s_nop 0
	global_load_lds_dwordx4 v129, s[20:21]
	s_add_u32 s84, s20, 0x20000
	s_mov_b32 m0, s29
	s_nop 0
	global_load_lds_dwordx4 v131, s[20:21]
	s_addc_u32 s85, s21, 0
	s_mov_b32 m0, s30
	s_nop 0
	global_load_lds_dwordx4 v129, s[84:85]
	s_mov_b32 m0, s31
	s_nop 0
	global_load_lds_dwordx4 v131, s[84:85]
	s_mov_b32 m0, s27
	s_nop 0
	global_load_lds_dwordx4 v128, s[22:23]
	s_mov_b32 m0, s33
	s_nop 0
	global_load_lds_dwordx4 v130, s[22:23]
	s_waitcnt vmcnt(8) lgkmcnt(0)
	s_setprio 1
	s_barrier
	v_mfma_f32_16x16x32_bf16 v[60:63], v[138:141], v[170:173], v[60:63]
	v_mfma_f32_16x16x32_bf16 v[56:59], v[146:149], v[170:173], v[56:59]
	v_mfma_f32_16x16x32_bf16 v[44:47], v[138:141], v[178:181], v[44:47]
	v_mfma_f32_16x16x32_bf16 v[40:43], v[146:149], v[178:181], v[40:43]
	v_mfma_f32_16x16x32_bf16 v[28:31], v[138:141], v[186:189], v[28:31]
	v_mfma_f32_16x16x32_bf16 v[24:27], v[146:149], v[186:189], v[24:27]
	v_mfma_f32_16x16x32_bf16 v[12:15], v[138:141], v[198:201], v[12:15]
	v_mfma_f32_16x16x32_bf16 v[8:11], v[146:149], v[198:201], v[8:11]
	v_mfma_f32_16x16x32_bf16 v[60:63], v[142:145], v[174:177], v[60:63]
	v_mfma_f32_16x16x32_bf16 v[56:59], v[150:153], v[174:177], v[56:59]
	v_mfma_f32_16x16x32_bf16 v[44:47], v[142:145], v[182:185], v[44:47]
	v_mfma_f32_16x16x32_bf16 v[40:43], v[150:153], v[182:185], v[40:43]
	v_mfma_f32_16x16x32_bf16 v[28:31], v[142:145], v[194:197], v[28:31]
	v_mfma_f32_16x16x32_bf16 v[24:27], v[150:153], v[194:197], v[24:27]
	v_mfma_f32_16x16x32_bf16 v[12:15], v[142:145], v[202:205], v[12:15]
	v_mfma_f32_16x16x32_bf16 v[8:11], v[150:153], v[202:205], v[8:11]
	v_mfma_f32_16x16x32_bf16 v[52:55], v[154:157], v[170:173], v[52:55]
	v_mfma_f32_16x16x32_bf16 v[48:51], v[162:165], v[170:173], v[48:51]
	v_mfma_f32_16x16x32_bf16 v[36:39], v[154:157], v[178:181], v[36:39]
	v_mfma_f32_16x16x32_bf16 v[32:35], v[162:165], v[178:181], v[32:35]
	v_mfma_f32_16x16x32_bf16 v[20:23], v[154:157], v[186:189], v[20:23]
	v_mfma_f32_16x16x32_bf16 v[16:19], v[162:165], v[186:189], v[16:19]
	v_mfma_f32_16x16x32_bf16 v[4:7], v[154:157], v[198:201], v[4:7]
	v_mfma_f32_16x16x32_bf16 v[0:3], v[162:165], v[198:201], v[0:3]
	v_mfma_f32_16x16x32_bf16 v[52:55], v[158:161], v[174:177], v[52:55]
	v_mfma_f32_16x16x32_bf16 v[48:51], v[166:169], v[174:177], v[48:51]
	v_mfma_f32_16x16x32_bf16 v[36:39], v[158:161], v[182:185], v[36:39]
	v_mfma_f32_16x16x32_bf16 v[32:35], v[166:169], v[182:185], v[32:35]
	v_mfma_f32_16x16x32_bf16 v[20:23], v[158:161], v[194:197], v[20:23]
	v_mfma_f32_16x16x32_bf16 v[16:19], v[166:169], v[194:197], v[16:19]
	v_mfma_f32_16x16x32_bf16 v[4:7], v[158:161], v[202:205], v[4:7]
	v_mfma_f32_16x16x32_bf16 v[0:3], v[166:169], v[202:205], v[0:3]
	s_setprio 0
	s_barrier
; #define PG8_STAGE(bufoff, gbase, voff) do { _Pragma("unroll") for (int _i = 0; _i < 2; ++_i) \
;         asm volatile("s_mov_b32 m0, %0\n\ts_nop 0\n\tglobal_load_lds_dwordx4 %1, %2" :: "s"(ldsb + (unsigned)((bufoff) + _i * 8192)), "v"((voff)[_i]), "s"(gbase) : "m0", "memory"); } while (0)
; #define PG8_LDA(dst, b, h) do { _Pragma("unroll") for (int m = 0; m < 4; ++m) _Pragma("unroll") for (int k = 0; k < 2; ++k) dst[m][k] = *(const PG8_LAS bf16x8*)(lds + PG8_SA(b, h) + aoff + m * 2048 + k * 1024); } while (0)
; #define PG8_LDB(dst, b, h) do { _Pragma("unroll") for (int n = 0; n < 2; ++n) _Pragma("unroll") for (int k = 0; k < 2; ++k) dst[n][k] = *(const PG8_LAS bf16x8*)(lds + PG8_SB(b, h) + boff + n * 2048 + k * 1024); } while (0)
; #define PG8_MMA(ai, bj, At, Bt) do { __builtin_amdgcn_s_setprio(1); _Pragma("unroll") for (int m = 0; m < 4; ++m) _Pragma("unroll") for (int n = 0; n < 2; ++n) _Pragma("unroll") for (int k = 0; k < 2; ++k) \
;         acc[ai][bj][m][n] = __builtin_amdgcn_mfma_f32_16x16x32_bf16(Bt[n][k], At[m][k], acc[ai][bj][m][n], 0, 0, 0); __builtin_amdgcn_s_setprio(0); } while (0)
; #define PG8_WAIT_V(n) asm volatile("s_waitcnt vmcnt(" #n ")" ::: "memory")
; #define PG8_WAIT_L(n) asm volatile("s_waitcnt lgkmcnt(" #n ")" ::: "memory")
; #define PG8_BAR __builtin_amdgcn_s_barrier()
; #define PG8_SCHED __builtin_amdgcn_sched_barrier(0)
; template <class Epi, class Sched, bool ALIGN_EPI = false, bool SP2 = false>
; __device__ __forceinline__ void gemm_phase(PG8_LAS unsigned char* lds, const Gemm g, const Sched& S, const Epi& E, const int wv) {
;     ...
;         for (int t = 0; t < nt; t += 2) {
;     ...
;             PG8_LDB(B0, 1, 0); PG8_LDB(B1, 1, 1); PG8_SCHED; PG8_LDA(At, 1, 0); PG8_STAGE(PG8_SA(0, 1), a2 + hstepA, voffA);
;             PG8_WAIT_V(8); PG8_WAIT_L(0); PG8_BAR; PG8_MMA(0, 0, At, B0); PG8_MMA(0, 1, At, B1); PG8_BAR; PG8_SCHED;
;             PG8_LDA(At, 1, 1); PG8_STAGE(PG8_SB(1, 0), b3, voffB); PG8_STAGE(PG8_SB(1, 1), b3 + hstepB, voffB); PG8_STAGE(PG8_SA(1, 0), a3, voffA);
;             PG8_WAIT_V(8); PG8_WAIT_L(0); PG8_BAR; PG8_MMA(1, 0, At, B0); PG8_MMA(1, 1, At, B1); PG8_BAR; PG8_SCHED;
	v_add_u32_e32 v137, 0x18000, v134
	ds_read_b128 v[138:141], v137
	ds_read_b128 v[142:145], v137 offset:1024
	ds_read_b128 v[146:149], v137 offset:2048
	ds_read_b128 v[150:153], v137 offset:3072
	v_add_u32_e32 v137, 0x1c000, v134
	ds_read_b128 v[154:157], v137
	ds_read_b128 v[158:161], v137 offset:1024
	ds_read_b128 v[162:165], v137 offset:2048
	ds_read_b128 v[166:169], v137 offset:3072
	ds_read_b128 v[170:173], v135 offset:32768
	ds_read_b128 v[174:177], v135 offset:33792
	ds_read_b128 v[178:181], v135 offset:34816
	ds_read_b128 v[182:185], v135 offset:35840
	ds_read_b128 v[186:189], v135 offset:36864
	ds_read_b128 v[194:197], v135 offset:37888
	ds_read_b128 v[198:201], v135 offset:38912
	ds_read_b128 v[202:205], v135 offset:39936
	s_add_u32 s22, s22, 0x20000
	s_addc_u32 s23, s23, 0
	s_mov_b32 m0, s34
	s_nop 0
	global_load_lds_dwordx4 v128, s[22:23]
	s_mov_b32 m0, s35
	s_nop 0
	global_load_lds_dwordx4 v130, s[22:23]
	s_waitcnt vmcnt(8) lgkmcnt(0)
	s_setprio 1
	s_barrier
	v_mfma_f32_16x16x32_bf16 v[124:127], v[138:141], v[170:173], v[124:127]
	v_mfma_f32_16x16x32_bf16 v[120:123], v[146:149], v[170:173], v[120:123]
	v_mfma_f32_16x16x32_bf16 v[108:111], v[138:141], v[178:181], v[108:111]
	v_mfma_f32_16x16x32_bf16 v[104:107], v[146:149], v[178:181], v[104:107]
	v_mfma_f32_16x16x32_bf16 v[92:95], v[138:141], v[186:189], v[92:95]
	v_mfma_f32_16x16x32_bf16 v[88:91], v[146:149], v[186:189], v[88:91]
	v_mfma_f32_16x16x32_bf16 v[76:79], v[138:141], v[198:201], v[76:79]
	v_mfma_f32_16x16x32_bf16 v[72:75], v[146:149], v[198:201], v[72:75]
	v_mfma_f32_16x16x32_bf16 v[124:127], v[142:145], v[174:177], v[124:127]
	v_mfma_f32_16x16x32_bf16 v[120:123], v[150:153], v[174:177], v[120:123]
	v_mfma_f32_16x16x32_bf16 v[108:111], v[142:145], v[182:185], v[108:111]
	v_mfma_f32_16x16x32_bf16 v[104:107], v[150:153], v[182:185], v[104:107]
	v_mfma_f32_16x16x32_bf16 v[92:95], v[142:145], v[194:197], v[92:95]
	v_mfma_f32_16x16x32_bf16 v[88:91], v[150:153], v[194:197], v[88:91]
	v_mfma_f32_16x16x32_bf16 v[76:79], v[142:145], v[202:205], v[76:79]
	v_mfma_f32_16x16x32_bf16 v[72:75], v[150:153], v[202:205], v[72:75]
	v_mfma_f32_16x16x32_bf16 v[116:119], v[154:157], v[170:173], v[116:119]
	v_mfma_f32_16x16x32_bf16 v[112:115], v[162:165], v[170:173], v[112:115]
	v_mfma_f32_16x16x32_bf16 v[100:103], v[154:157], v[178:181], v[100:103]
	v_mfma_f32_16x16x32_bf16 v[96:99], v[162:165], v[178:181], v[96:99]
	v_mfma_f32_16x16x32_bf16 v[84:87], v[154:157], v[186:189], v[84:87]
	v_mfma_f32_16x16x32_bf16 v[80:83], v[162:165], v[186:189], v[80:83]
	v_mfma_f32_16x16x32_bf16 v[68:71], v[154:157], v[198:201], v[68:71]
	v_mfma_f32_16x16x32_bf16 v[64:67], v[162:165], v[198:201], v[64:67]
	v_mfma_f32_16x16x32_bf16 v[116:119], v[158:161], v[174:177], v[116:119]
	v_mfma_f32_16x16x32_bf16 v[112:115], v[166:169], v[174:177], v[112:115]
	v_mfma_f32_16x16x32_bf16 v[100:103], v[158:161], v[182:185], v[100:103]
	v_mfma_f32_16x16x32_bf16 v[96:99], v[166:169], v[182:185], v[96:99]
	v_mfma_f32_16x16x32_bf16 v[84:87], v[158:161], v[194:197], v[84:87]
	v_mfma_f32_16x16x32_bf16 v[80:83], v[166:169], v[194:197], v[80:83]
	v_mfma_f32_16x16x32_bf16 v[68:71], v[158:161], v[202:205], v[68:71]
	v_mfma_f32_16x16x32_bf16 v[64:67], v[166:169], v[202:205], v[64:67]
	s_setprio 0
	s_barrier
	ds_read_b128 v[170:173], v135 offset:49152
	ds_read_b128 v[174:177], v135 offset:50176
	ds_read_b128 v[178:181], v135 offset:51200
	ds_read_b128 v[182:185], v135 offset:52224
	ds_read_b128 v[186:189], v135 offset:53248
	ds_read_b128 v[194:197], v135 offset:54272
	ds_read_b128 v[198:201], v135 offset:55296
	ds_read_b128 v[202:205], v135 offset:56320
	s_add_u32 s22, s20, 0x80
	s_addc_u32 s23, s21, 0
	s_mov_b32 m0, s36
	s_nop 0
	global_load_lds_dwordx4 v129, s[22:23]
	s_add_u32 s20, s20, 0x20080
	s_mov_b32 m0, s37
	s_nop 0
	global_load_lds_dwordx4 v131, s[22:23]
	s_addc_u32 s21, s21, 0
	s_mov_b32 m0, s43
	s_nop 0
	global_load_lds_dwordx4 v129, s[20:21]
	s_mov_b32 m0, s44
	s_nop 0
	global_load_lds_dwordx4 v131, s[20:21]
	s_mov_b32 m0, s40
	s_nop 0
	global_load_lds_dwordx4 v128, s[18:19]
	s_mov_b32 m0, s42
	s_nop 0
	global_load_lds_dwordx4 v130, s[18:19]
	s_waitcnt vmcnt(8) lgkmcnt(0)
	s_setprio 1
	s_barrier
	v_mfma_f32_16x16x32_bf16 v[60:63], v[138:141], v[170:173], v[60:63]
	v_mfma_f32_16x16x32_bf16 v[56:59], v[146:149], v[170:173], v[56:59]
	v_mfma_f32_16x16x32_bf16 v[44:47], v[138:141], v[178:181], v[44:47]
	v_mfma_f32_16x16x32_bf16 v[40:43], v[146:149], v[178:181], v[40:43]
	v_mfma_f32_16x16x32_bf16 v[28:31], v[138:141], v[186:189], v[28:31]
	v_mfma_f32_16x16x32_bf16 v[24:27], v[146:149], v[186:189], v[24:27]
	v_mfma_f32_16x16x32_bf16 v[12:15], v[138:141], v[198:201], v[12:15]
	v_mfma_f32_16x16x32_bf16 v[8:11], v[146:149], v[198:201], v[8:11]
	v_mfma_f32_16x16x32_bf16 v[60:63], v[142:145], v[174:177], v[60:63]
	v_mfma_f32_16x16x32_bf16 v[56:59], v[150:153], v[174:177], v[56:59]
	v_mfma_f32_16x16x32_bf16 v[44:47], v[142:145], v[182:185], v[44:47]
	v_mfma_f32_16x16x32_bf16 v[40:43], v[150:153], v[182:185], v[40:43]
	v_mfma_f32_16x16x32_bf16 v[28:31], v[142:145], v[194:197], v[28:31]
	v_mfma_f32_16x16x32_bf16 v[24:27], v[150:153], v[194:197], v[24:27]
	v_mfma_f32_16x16x32_bf16 v[12:15], v[142:145], v[202:205], v[12:15]
	v_mfma_f32_16x16x32_bf16 v[8:11], v[150:153], v[202:205], v[8:11]
	v_mfma_f32_16x16x32_bf16 v[52:55], v[154:157], v[170:173], v[52:55]
	v_mfma_f32_16x16x32_bf16 v[48:51], v[162:165], v[170:173], v[48:51]
	v_mfma_f32_16x16x32_bf16 v[36:39], v[154:157], v[178:181], v[36:39]
	v_mfma_f32_16x16x32_bf16 v[32:35], v[162:165], v[178:181], v[32:35]
	v_mfma_f32_16x16x32_bf16 v[20:23], v[154:157], v[186:189], v[20:23]
	v_mfma_f32_16x16x32_bf16 v[16:19], v[162:165], v[186:189], v[16:19]
	v_mfma_f32_16x16x32_bf16 v[4:7], v[154:157], v[198:201], v[4:7]
	v_mfma_f32_16x16x32_bf16 v[0:3], v[162:165], v[198:201], v[0:3]
	v_mfma_f32_16x16x32_bf16 v[52:55], v[158:161], v[174:177], v[52:55]
	v_mfma_f32_16x16x32_bf16 v[48:51], v[166:169], v[174:177], v[48:51]
	v_mfma_f32_16x16x32_bf16 v[36:39], v[158:161], v[182:185], v[36:39]
	v_mfma_f32_16x16x32_bf16 v[32:35], v[166:169], v[182:185], v[32:35]
	v_mfma_f32_16x16x32_bf16 v[20:23], v[158:161], v[194:197], v[20:23]
	v_mfma_f32_16x16x32_bf16 v[16:19], v[166:169], v[194:197], v[16:19]
	v_mfma_f32_16x16x32_bf16 v[4:7], v[158:161], v[202:205], v[4:7]
	v_mfma_f32_16x16x32_bf16 v[0:3], v[166:169], v[202:205], v[0:3]
	s_setprio 0
	s_barrier
	s_add_u32 s60, s60, 0x100
	s_addc_u32 s62, s62, 0
	s_add_u32 s65, s65, 0x100
	s_addc_u32 s71, s71, 0
	s_cmp_ge_i32 s72, s55
	s_mov_b32 s18, s72
	s_cbranch_scc0 .LBB0_864
	s_and_b64 vcc, exec, s[10:11]
	s_cbranch_vccz .LBB0_867

; #define PG8_STAGE(bufoff, gbase, voff) do { _Pragma("unroll") for (int _i = 0; _i < 2; ++_i) \
;         asm volatile("s_mov_b32 m0, %0\n\ts_nop 0\n\tglobal_load_lds_dwordx4 %1, %2" :: "s"(ldsb + (unsigned)((bufoff) + _i * 8192)), "v"((voff)[_i]), "s"(gbase) : "m0", "memory"); } while (0)
; #define PG8_LDA(dst, b, h) do { _Pragma("unroll") for (int m = 0; m < 4; ++m) _Pragma("unroll") for (int k = 0; k < 2; ++k) dst[m][k] = *(const PG8_LAS bf16x8*)(lds + PG8_SA(b, h) + aoff + m * 2048 + k * 1024); } while (0)
; #define PG8_LDB(dst, b, h) do { _Pragma("unroll") for (int n = 0; n < 2; ++n) _Pragma("unroll") for (int k = 0; k < 2; ++k) dst[n][k] = *(const PG8_LAS bf16x8*)(lds + PG8_SB(b, h) + boff + n * 2048 + k * 1024); } while (0)
; #define PG8_MMA(ai, bj, At, Bt) do { __builtin_amdgcn_s_setprio(1); _Pragma("unroll") for (int m = 0; m < 4; ++m) _Pragma("unroll") for (int n = 0; n < 2; ++n) _Pragma("unroll") for (int k = 0; k < 2; ++k) \
;         acc[ai][bj][m][n] = __builtin_amdgcn_mfma_f32_16x16x32_bf16(Bt[n][k], At[m][k], acc[ai][bj][m][n], 0, 0, 0); __builtin_amdgcn_s_setprio(0); } while (0)
; #define PG8_WAIT_V(n) asm volatile("s_waitcnt vmcnt(" #n ")" ::: "memory")
; #define PG8_WAIT_L(n) asm volatile("s_waitcnt lgkmcnt(" #n ")" ::: "memory")
; #define PG8_BAR __builtin_amdgcn_s_barrier()
; #define PG8_SCHED __builtin_amdgcn_sched_barrier(0)
; template <class Epi, class Sched, bool ALIGN_EPI = false, bool SP2 = false>
; __device__ __forceinline__ void gemm_phase(PG8_LAS unsigned char* lds, const Gemm g, const Sched& S, const Epi& E, const int wv) {
;     ...
;             PG8_LDB(B0, 0, 0); PG8_LDB(B1, 0, 1); PG8_SCHED; PG8_LDA(At, 0, 0); PG8_STAGE(PG8_SA(1, 1), a1 + hstepA, voffA);
;             PG8_WAIT_V(8); PG8_WAIT_L(0); PG8_BAR; PG8_MMA(0, 0, At, B0); PG8_MMA(0, 1, At, B1); PG8_BAR; PG8_SCHED;
;             PG8_LDA(At, 0, 1); PG8_STAGE(PG8_SB(0, 0), b2, voffB); PG8_STAGE(PG8_SB(0, 1), b2 + hstepB, voffB); PG8_STAGE(PG8_SA(0, 0), a2, voffA);
;             PG8_WAIT_V(8); PG8_WAIT_L(0); PG8_BAR; PG8_MMA(1, 0, At, B0); PG8_MMA(1, 1, At, B1); PG8_BAR; PG8_SCHED;
.LBB0_1031:
	v_add_u32_e32 v124, 0x10000, v220
	v_add_u32_e32 v156, 0x14000, v220
	ds_read_b128 v[108:111], v124
	ds_read_b128 v[116:119], v124 offset:1024
	ds_read_b128 v[120:123], v124 offset:2048
	ds_read_b128 v[124:127], v124 offset:3072
	ds_read_b128 v[144:147], v156
	ds_read_b128 v[148:151], v156 offset:1024
	ds_read_b128 v[152:155], v156 offset:2048
	ds_read_b128 v[156:159], v156 offset:3072
	s_add_i32 s12, s34, 2
	s_cmp_eq_u32 s11, s34
	s_cselect_b32 s42, s26, vcc_lo
	s_cselect_b32 s43, s27, vcc_hi
	s_cselect_b32 s36, s28, s79
	s_cselect_b32 s37, s29, s62
	s_add_u32 s34, s42, 0x80
	s_addc_u32 s35, s43, 0
	ds_read_b128 v[160:163], v221
	ds_read_b128 v[164:167], v221 offset:1024
	ds_read_b128 v[168:171], v221 offset:2048
	ds_read_b128 v[176:179], v221 offset:3072
	ds_read_b128 v[180:183], v221 offset:4096
	ds_read_b128 v[184:187], v221 offset:5120
	ds_read_b128 v[188:191], v221 offset:6144
	ds_read_b128 v[194:197], v221 offset:7168
	s_mov_b32 m0, s88
	s_nop 0
	global_load_lds_dwordx4 v208, s[30:31]
	s_mov_b32 m0, s93
	s_nop 0
	global_load_lds_dwordx4 v210, s[30:31]
	s_waitcnt vmcnt(8) lgkmcnt(0)
	s_setprio 1
	s_barrier
	v_mfma_f32_16x16x32_bf16 v[140:143], v[108:111], v[160:163], v[140:143]
	v_mfma_f32_16x16x32_bf16 v[136:139], v[120:123], v[160:163], v[136:139]
	v_mfma_f32_16x16x32_bf16 v[112:115], v[108:111], v[168:171], v[112:115]
	v_mfma_f32_16x16x32_bf16 v[104:107], v[120:123], v[168:171], v[104:107]
	v_mfma_f32_16x16x32_bf16 v[92:95], v[108:111], v[180:183], v[92:95]
	v_mfma_f32_16x16x32_bf16 v[88:91], v[120:123], v[180:183], v[88:91]
	v_mfma_f32_16x16x32_bf16 v[76:79], v[108:111], v[188:191], v[76:79]
	v_mfma_f32_16x16x32_bf16 v[72:75], v[120:123], v[188:191], v[72:75]
	v_mfma_f32_16x16x32_bf16 v[140:143], v[116:119], v[164:167], v[140:143]
	v_mfma_f32_16x16x32_bf16 v[136:139], v[124:127], v[164:167], v[136:139]
	v_mfma_f32_16x16x32_bf16 v[112:115], v[116:119], v[176:179], v[112:115]
	v_mfma_f32_16x16x32_bf16 v[104:107], v[124:127], v[176:179], v[104:107]
	v_mfma_f32_16x16x32_bf16 v[92:95], v[116:119], v[184:187], v[92:95]
	v_mfma_f32_16x16x32_bf16 v[88:91], v[124:127], v[184:187], v[88:91]
	v_mfma_f32_16x16x32_bf16 v[76:79], v[116:119], v[194:197], v[76:79]
	v_mfma_f32_16x16x32_bf16 v[72:75], v[124:127], v[194:197], v[72:75]
	v_mfma_f32_16x16x32_bf16 v[132:135], v[144:147], v[160:163], v[132:135]
	v_mfma_f32_16x16x32_bf16 v[128:131], v[152:155], v[160:163], v[128:131]
	v_mfma_f32_16x16x32_bf16 v[100:103], v[144:147], v[168:171], v[100:103]
	v_mfma_f32_16x16x32_bf16 v[96:99], v[152:155], v[168:171], v[96:99]
	v_mfma_f32_16x16x32_bf16 v[84:87], v[144:147], v[180:183], v[84:87]
	v_mfma_f32_16x16x32_bf16 v[80:83], v[152:155], v[180:183], v[80:83]
	v_mfma_f32_16x16x32_bf16 v[68:71], v[144:147], v[188:191], v[68:71]
	v_mfma_f32_16x16x32_bf16 v[64:67], v[152:155], v[188:191], v[64:67]
	v_mfma_f32_16x16x32_bf16 v[132:135], v[148:151], v[164:167], v[132:135]
	v_mfma_f32_16x16x32_bf16 v[128:131], v[156:159], v[164:167], v[128:131]
	v_mfma_f32_16x16x32_bf16 v[100:103], v[148:151], v[176:179], v[100:103]
	v_mfma_f32_16x16x32_bf16 v[96:99], v[156:159], v[176:179], v[96:99]
	v_mfma_f32_16x16x32_bf16 v[84:87], v[148:151], v[184:187], v[84:87]
	v_mfma_f32_16x16x32_bf16 v[80:83], v[156:159], v[184:187], v[80:83]
	v_mfma_f32_16x16x32_bf16 v[68:71], v[148:151], v[194:197], v[68:71]
	v_mfma_f32_16x16x32_bf16 v[64:67], v[156:159], v[194:197], v[64:67]
	s_setprio 0
	s_barrier
	ds_read_b128 v[160:163], v221 offset:16384
	ds_read_b128 v[164:167], v221 offset:17408
	ds_read_b128 v[168:171], v221 offset:18432
	ds_read_b128 v[176:179], v221 offset:19456
	ds_read_b128 v[180:183], v221 offset:20480
	ds_read_b128 v[184:187], v221 offset:21504
	ds_read_b128 v[188:191], v221 offset:22528
	ds_read_b128 v[194:197], v221 offset:23552
	s_mov_b32 m0, s48
	s_nop 0
	global_load_lds_dwordx4 v209, s[36:37]
	s_add_u32 s44, s36, 0x80000
	s_mov_b32 m0, s49
	s_nop 0
	global_load_lds_dwordx4 v211, s[36:37]
	s_addc_u32 s45, s37, 0
	s_mov_b32 m0, s50
	s_nop 0
	global_load_lds_dwordx4 v209, s[44:45]
	s_mov_b32 m0, s51
	s_nop 0
	global_load_lds_dwordx4 v211, s[44:45]
	s_mov_b32 m0, s47
	s_nop 0
	global_load_lds_dwordx4 v208, s[42:43]
	s_mov_b32 m0, s52
	s_nop 0
	global_load_lds_dwordx4 v210, s[42:43]
	s_waitcnt vmcnt(8) lgkmcnt(0)
	s_setprio 1
	s_barrier
	v_mfma_f32_16x16x32_bf16 v[60:63], v[108:111], v[160:163], v[60:63]
	v_mfma_f32_16x16x32_bf16 v[56:59], v[120:123], v[160:163], v[56:59]
	v_mfma_f32_16x16x32_bf16 v[44:47], v[108:111], v[168:171], v[44:47]
	v_mfma_f32_16x16x32_bf16 v[40:43], v[120:123], v[168:171], v[40:43]
	v_mfma_f32_16x16x32_bf16 v[28:31], v[108:111], v[180:183], v[28:31]
	v_mfma_f32_16x16x32_bf16 v[24:27], v[120:123], v[180:183], v[24:27]
	v_mfma_f32_16x16x32_bf16 v[12:15], v[108:111], v[188:191], v[12:15]
	v_mfma_f32_16x16x32_bf16 v[8:11], v[120:123], v[188:191], v[8:11]
	v_mfma_f32_16x16x32_bf16 v[60:63], v[116:119], v[164:167], v[60:63]
	v_mfma_f32_16x16x32_bf16 v[56:59], v[124:127], v[164:167], v[56:59]
	v_mfma_f32_16x16x32_bf16 v[44:47], v[116:119], v[176:179], v[44:47]
	v_mfma_f32_16x16x32_bf16 v[40:43], v[124:127], v[176:179], v[40:43]
	v_mfma_f32_16x16x32_bf16 v[28:31], v[116:119], v[184:187], v[28:31]
	v_mfma_f32_16x16x32_bf16 v[24:27], v[124:127], v[184:187], v[24:27]
	v_mfma_f32_16x16x32_bf16 v[12:15], v[116:119], v[194:197], v[12:15]
	v_mfma_f32_16x16x32_bf16 v[8:11], v[124:127], v[194:197], v[8:11]
	v_mfma_f32_16x16x32_bf16 v[52:55], v[144:147], v[160:163], v[52:55]
	v_mfma_f32_16x16x32_bf16 v[48:51], v[152:155], v[160:163], v[48:51]
	v_mfma_f32_16x16x32_bf16 v[36:39], v[144:147], v[168:171], v[36:39]
	v_mfma_f32_16x16x32_bf16 v[32:35], v[152:155], v[168:171], v[32:35]
	v_mfma_f32_16x16x32_bf16 v[20:23], v[144:147], v[180:183], v[20:23]
	v_mfma_f32_16x16x32_bf16 v[16:19], v[152:155], v[180:183], v[16:19]
	v_mfma_f32_16x16x32_bf16 v[4:7], v[144:147], v[188:191], v[4:7]
	v_mfma_f32_16x16x32_bf16 v[0:3], v[152:155], v[188:191], v[0:3]
	v_mfma_f32_16x16x32_bf16 v[52:55], v[148:151], v[164:167], v[52:55]
	v_mfma_f32_16x16x32_bf16 v[48:51], v[156:159], v[164:167], v[48:51]
	v_mfma_f32_16x16x32_bf16 v[36:39], v[148:151], v[176:179], v[36:39]
	v_mfma_f32_16x16x32_bf16 v[32:35], v[156:159], v[176:179], v[32:35]
	v_mfma_f32_16x16x32_bf16 v[20:23], v[148:151], v[184:187], v[20:23]
	v_mfma_f32_16x16x32_bf16 v[16:19], v[156:159], v[184:187], v[16:19]
	v_mfma_f32_16x16x32_bf16 v[4:7], v[148:151], v[194:197], v[4:7]
	v_mfma_f32_16x16x32_bf16 v[0:3], v[156:159], v[194:197], v[0:3]
	s_setprio 0
	s_barrier
; #define PG8_STAGE(bufoff, gbase, voff) do { _Pragma("unroll") for (int _i = 0; _i < 2; ++_i) \
;         asm volatile("s_mov_b32 m0, %0\n\ts_nop 0\n\tglobal_load_lds_dwordx4 %1, %2" :: "s"(ldsb + (unsigned)((bufoff) + _i * 8192)), "v"((voff)[_i]), "s"(gbase) : "m0", "memory"); } while (0)
; #define PG8_LDA(dst, b, h) do { _Pragma("unroll") for (int m = 0; m < 4; ++m) _Pragma("unroll") for (int k = 0; k < 2; ++k) dst[m][k] = *(const PG8_LAS bf16x8*)(lds + PG8_SA(b, h) + aoff + m * 2048 + k * 1024); } while (0)
; #define PG8_LDB(dst, b, h) do { _Pragma("unroll") for (int n = 0; n < 2; ++n) _Pragma("unroll") for (int k = 0; k < 2; ++k) dst[n][k] = *(const PG8_LAS bf16x8*)(lds + PG8_SB(b, h) + boff + n * 2048 + k * 1024); } while (0)
; #define PG8_MMA(ai, bj, At, Bt) do { __builtin_amdgcn_s_setprio(1); _Pragma("unroll") for (int m = 0; m < 4; ++m) _Pragma("unroll") for (int n = 0; n < 2; ++n) _Pragma("unroll") for (int k = 0; k < 2; ++k) \
;         acc[ai][bj][m][n] = __builtin_amdgcn_mfma_f32_16x16x32_bf16(Bt[n][k], At[m][k], acc[ai][bj][m][n], 0, 0, 0); __builtin_amdgcn_s_setprio(0); } while (0)
; #define PG8_WAIT_V(n) asm volatile("s_waitcnt vmcnt(" #n ")" ::: "memory")
; #define PG8_WAIT_L(n) asm volatile("s_waitcnt lgkmcnt(" #n ")" ::: "memory")
; #define PG8_BAR __builtin_amdgcn_s_barrier()
; template <class Epi, class Sched, bool ALIGN_EPI = false, bool SP2 = false>
; __device__ __forceinline__ void gemm_phase(PG8_LAS unsigned char* lds, const Gemm g, const Sched& S, const Epi& E, const int wv) {
;     ...
;         for (int t = 0; t < nt; t += 2) {
;             const bool last = (t == nt - 2);
;             const char* a1 = cA + (size_t)(t + 1) * kstep;
;             const char* a2 = last ? nA : cA + (size_t)(t + 2) * kstep; const char* b2 = last ? nB : cB + (size_t)(t + 2) * kstep;
;             const char* a3 = a2 + kstep; const char* b3 = b2 + kstep;
;     ...
;             PG8_LDB(B0, 1, 0); PG8_LDB(B1, 1, 1); PG8_SCHED; PG8_LDA(At, 1, 0); PG8_STAGE(PG8_SA(0, 1), a2 + hstepA, voffA);
;             PG8_WAIT_V(8); PG8_WAIT_L(0); PG8_BAR; PG8_MMA(0, 0, At, B0); PG8_MMA(0, 1, At, B1); PG8_BAR; PG8_SCHED;
;             PG8_LDA(At, 1, 1); PG8_STAGE(PG8_SB(1, 0), b3, voffB); PG8_STAGE(PG8_SB(1, 1), b3 + hstepB, voffB); PG8_STAGE(PG8_SA(1, 0), a3, voffA);
;             PG8_WAIT_V(8); PG8_WAIT_L(0); PG8_BAR; PG8_MMA(1, 0, At, B0); PG8_MMA(1, 1, At, B1); PG8_BAR; PG8_SCHED;
	v_add_u32_e32 v124, 0x18000, v220
	v_add_u32_e32 v156, 0x1c000, v220
	ds_read_b128 v[108:111], v124
	ds_read_b128 v[116:119], v124 offset:1024
	ds_read_b128 v[120:123], v124 offset:2048
	ds_read_b128 v[124:127], v124 offset:3072
	ds_read_b128 v[144:147], v156
	ds_read_b128 v[148:151], v156 offset:1024
	ds_read_b128 v[152:155], v156 offset:2048
	ds_read_b128 v[156:159], v156 offset:3072
	ds_read_b128 v[160:163], v221 offset:32768
	ds_read_b128 v[164:167], v221 offset:33792
	ds_read_b128 v[168:171], v221 offset:34816
	ds_read_b128 v[176:179], v221 offset:35840
	ds_read_b128 v[180:183], v221 offset:36864
	ds_read_b128 v[184:187], v221 offset:37888
	ds_read_b128 v[188:191], v221 offset:38912
	ds_read_b128 v[194:197], v221 offset:39936
	s_add_u32 s42, s42, 0x84000
	s_addc_u32 s43, s43, 0
	s_mov_b32 m0, s53
	s_nop 0
	global_load_lds_dwordx4 v208, s[42:43]
	s_mov_b32 m0, s54
	s_nop 0
	global_load_lds_dwordx4 v210, s[42:43]
	s_waitcnt vmcnt(8) lgkmcnt(0)
	s_setprio 1
	s_barrier
	v_mfma_f32_16x16x32_bf16 v[140:143], v[108:111], v[160:163], v[140:143]
	v_mfma_f32_16x16x32_bf16 v[136:139], v[120:123], v[160:163], v[136:139]
	v_mfma_f32_16x16x32_bf16 v[112:115], v[108:111], v[168:171], v[112:115]
	v_mfma_f32_16x16x32_bf16 v[104:107], v[120:123], v[168:171], v[104:107]
	v_mfma_f32_16x16x32_bf16 v[92:95], v[108:111], v[180:183], v[92:95]
	v_mfma_f32_16x16x32_bf16 v[88:91], v[120:123], v[180:183], v[88:91]
	v_mfma_f32_16x16x32_bf16 v[76:79], v[108:111], v[188:191], v[76:79]
	v_mfma_f32_16x16x32_bf16 v[72:75], v[120:123], v[188:191], v[72:75]
	v_mfma_f32_16x16x32_bf16 v[140:143], v[116:119], v[164:167], v[140:143]
	v_mfma_f32_16x16x32_bf16 v[136:139], v[124:127], v[164:167], v[136:139]
	v_mfma_f32_16x16x32_bf16 v[112:115], v[116:119], v[176:179], v[112:115]
	v_mfma_f32_16x16x32_bf16 v[104:107], v[124:127], v[176:179], v[104:107]
	v_mfma_f32_16x16x32_bf16 v[92:95], v[116:119], v[184:187], v[92:95]
	v_mfma_f32_16x16x32_bf16 v[88:91], v[124:127], v[184:187], v[88:91]
	v_mfma_f32_16x16x32_bf16 v[76:79], v[116:119], v[194:197], v[76:79]
	v_mfma_f32_16x16x32_bf16 v[72:75], v[124:127], v[194:197], v[72:75]
	v_mfma_f32_16x16x32_bf16 v[132:135], v[144:147], v[160:163], v[132:135]
	v_mfma_f32_16x16x32_bf16 v[128:131], v[152:155], v[160:163], v[128:131]
	v_mfma_f32_16x16x32_bf16 v[100:103], v[144:147], v[168:171], v[100:103]
	v_mfma_f32_16x16x32_bf16 v[96:99], v[152:155], v[168:171], v[96:99]
	v_mfma_f32_16x16x32_bf16 v[84:87], v[144:147], v[180:183], v[84:87]
	v_mfma_f32_16x16x32_bf16 v[80:83], v[152:155], v[180:183], v[80:83]
	v_mfma_f32_16x16x32_bf16 v[68:71], v[144:147], v[188:191], v[68:71]
	v_mfma_f32_16x16x32_bf16 v[64:67], v[152:155], v[188:191], v[64:67]
	v_mfma_f32_16x16x32_bf16 v[132:135], v[148:151], v[164:167], v[132:135]
	v_mfma_f32_16x16x32_bf16 v[128:131], v[156:159], v[164:167], v[128:131]
	v_mfma_f32_16x16x32_bf16 v[100:103], v[148:151], v[176:179], v[100:103]
	v_mfma_f32_16x16x32_bf16 v[96:99], v[156:159], v[176:179], v[96:99]
	v_mfma_f32_16x16x32_bf16 v[84:87], v[148:151], v[184:187], v[84:87]
	v_mfma_f32_16x16x32_bf16 v[80:83], v[156:159], v[184:187], v[80:83]
	v_mfma_f32_16x16x32_bf16 v[68:71], v[148:151], v[194:197], v[68:71]
	v_mfma_f32_16x16x32_bf16 v[64:67], v[156:159], v[194:197], v[64:67]
	s_setprio 0
	s_barrier
	ds_read_b128 v[160:163], v221 offset:49152
	ds_read_b128 v[164:167], v221 offset:50176
	ds_read_b128 v[168:171], v221 offset:51200
	ds_read_b128 v[176:179], v221 offset:52224
	ds_read_b128 v[180:183], v221 offset:53248
	ds_read_b128 v[184:187], v221 offset:54272
	ds_read_b128 v[188:191], v221 offset:55296
	ds_read_b128 v[194:197], v221 offset:56320
	s_add_u32 s42, s36, 0x80
	s_addc_u32 s43, s37, 0
	s_mov_b32 m0, s84
	s_nop 0
	global_load_lds_dwordx4 v209, s[42:43]
	s_add_u32 s36, s36, 0x80080
	s_mov_b32 m0, s71
	s_nop 0
	global_load_lds_dwordx4 v211, s[42:43]
	s_addc_u32 s37, s37, 0
	s_mov_b32 m0, s92
	s_nop 0
	global_load_lds_dwordx4 v209, s[36:37]
	s_mov_b32 m0, s58
	s_nop 0
	global_load_lds_dwordx4 v211, s[36:37]
	s_mov_b32 m0, s87
	s_nop 0
	global_load_lds_dwordx4 v208, s[34:35]
	s_mov_b32 m0, s89
	s_nop 0
	global_load_lds_dwordx4 v210, s[34:35]
	s_waitcnt vmcnt(8) lgkmcnt(0)
	s_setprio 1
	s_barrier
	v_mfma_f32_16x16x32_bf16 v[60:63], v[108:111], v[160:163], v[60:63]
	v_mfma_f32_16x16x32_bf16 v[56:59], v[120:123], v[160:163], v[56:59]
	v_mfma_f32_16x16x32_bf16 v[44:47], v[108:111], v[168:171], v[44:47]
	v_mfma_f32_16x16x32_bf16 v[40:43], v[120:123], v[168:171], v[40:43]
	v_mfma_f32_16x16x32_bf16 v[28:31], v[108:111], v[180:183], v[28:31]
	v_mfma_f32_16x16x32_bf16 v[24:27], v[120:123], v[180:183], v[24:27]
	v_mfma_f32_16x16x32_bf16 v[12:15], v[108:111], v[188:191], v[12:15]
	v_mfma_f32_16x16x32_bf16 v[8:11], v[120:123], v[188:191], v[8:11]
	v_mfma_f32_16x16x32_bf16 v[60:63], v[116:119], v[164:167], v[60:63]
	v_mfma_f32_16x16x32_bf16 v[56:59], v[124:127], v[164:167], v[56:59]
	v_mfma_f32_16x16x32_bf16 v[44:47], v[116:119], v[176:179], v[44:47]
	v_mfma_f32_16x16x32_bf16 v[40:43], v[124:127], v[176:179], v[40:43]
	v_mfma_f32_16x16x32_bf16 v[28:31], v[116:119], v[184:187], v[28:31]
	v_mfma_f32_16x16x32_bf16 v[24:27], v[124:127], v[184:187], v[24:27]
	v_mfma_f32_16x16x32_bf16 v[12:15], v[116:119], v[194:197], v[12:15]
	v_mfma_f32_16x16x32_bf16 v[8:11], v[124:127], v[194:197], v[8:11]
	v_mfma_f32_16x16x32_bf16 v[52:55], v[144:147], v[160:163], v[52:55]
	v_mfma_f32_16x16x32_bf16 v[48:51], v[152:155], v[160:163], v[48:51]
	v_mfma_f32_16x16x32_bf16 v[36:39], v[144:147], v[168:171], v[36:39]
	v_mfma_f32_16x16x32_bf16 v[32:35], v[152:155], v[168:171], v[32:35]
	v_mfma_f32_16x16x32_bf16 v[20:23], v[144:147], v[180:183], v[20:23]
	v_mfma_f32_16x16x32_bf16 v[16:19], v[152:155], v[180:183], v[16:19]
	v_mfma_f32_16x16x32_bf16 v[4:7], v[144:147], v[188:191], v[4:7]
	v_mfma_f32_16x16x32_bf16 v[0:3], v[152:155], v[188:191], v[0:3]
	v_mfma_f32_16x16x32_bf16 v[52:55], v[148:151], v[164:167], v[52:55]
	v_mfma_f32_16x16x32_bf16 v[48:51], v[156:159], v[164:167], v[48:51]
	v_mfma_f32_16x16x32_bf16 v[36:39], v[148:151], v[176:179], v[36:39]
	v_mfma_f32_16x16x32_bf16 v[32:35], v[156:159], v[176:179], v[32:35]
	v_mfma_f32_16x16x32_bf16 v[20:23], v[148:151], v[184:187], v[20:23]
	v_mfma_f32_16x16x32_bf16 v[16:19], v[156:159], v[184:187], v[16:19]
	v_mfma_f32_16x16x32_bf16 v[4:7], v[148:151], v[194:197], v[4:7]
	v_mfma_f32_16x16x32_bf16 v[0:3], v[156:159], v[194:197], v[0:3]
	s_setprio 0
	s_barrier
	s_add_u32 vcc_lo, vcc_lo, 0x100
	s_addc_u32 vcc_hi, vcc_hi, 0
	s_add_u32 s79, s79, 0x100
	s_addc_u32 s62, s62, 0
	s_add_u32 s30, s30, 0x100
	s_addc_u32 s31, s31, 0
	s_cmp_ge_i32 s12, s40
	s_mov_b32 s34, s12
	s_cbranch_scc0 .LBB0_1031
	s_mov_b32 s79, 0xc00000
	s_and_b64 vcc, exec, s[22:23]
	s_cbranch_vccz .LBB0_1034

; #define PG8_STAGE(bufoff, gbase, voff) do { _Pragma("unroll") for (int _i = 0; _i < 2; ++_i) \
;         asm volatile("s_mov_b32 m0, %0\n\ts_nop 0\n\tglobal_load_lds_dwordx4 %1, %2" :: "s"(ldsb + (unsigned)((bufoff) + _i * 8192)), "v"((voff)[_i]), "s"(gbase) : "m0", "memory"); } while (0)
; #define PG8_LDA(dst, b, h) do { _Pragma("unroll") for (int m = 0; m < 4; ++m) _Pragma("unroll") for (int k = 0; k < 2; ++k) dst[m][k] = *(const PG8_LAS bf16x8*)(lds + PG8_SA(b, h) + aoff + m * 2048 + k * 1024); } while (0)
; #define PG8_LDB(dst, b, h) do { _Pragma("unroll") for (int n = 0; n < 2; ++n) _Pragma("unroll") for (int k = 0; k < 2; ++k) dst[n][k] = *(const PG8_LAS bf16x8*)(lds + PG8_SB(b, h) + boff + n * 2048 + k * 1024); } while (0)
; #define PG8_MMA(ai, bj, At, Bt) do { __builtin_amdgcn_s_setprio(1); _Pragma("unroll") for (int m = 0; m < 4; ++m) _Pragma("unroll") for (int n = 0; n < 2; ++n) _Pragma("unroll") for (int k = 0; k < 2; ++k) \
;         acc[ai][bj][m][n] = __builtin_amdgcn_mfma_f32_16x16x32_bf16(Bt[n][k], At[m][k], acc[ai][bj][m][n], 0, 0, 0); __builtin_amdgcn_s_setprio(0); } while (0)
; #define PG8_WAIT_V(n) asm volatile("s_waitcnt vmcnt(" #n ")" ::: "memory")
; #define PG8_WAIT_L(n) asm volatile("s_waitcnt lgkmcnt(" #n ")" ::: "memory")
; #define PG8_BAR __builtin_amdgcn_s_barrier()
; #define PG8_SCHED __builtin_amdgcn_sched_barrier(0)
; template <class Epi, class Sched, bool ALIGN_EPI = false, bool SP2 = false>
; __device__ __forceinline__ void gemm_phase(PG8_LAS unsigned char* lds, const Gemm g, const Sched& S, const Epi& E, const int wv) {
;     ...
;             PG8_LDB(B0, 0, 0); PG8_LDB(B1, 0, 1); PG8_SCHED; PG8_LDA(At, 0, 0); PG8_STAGE(PG8_SA(1, 1), a1 + hstepA, voffA);
;             PG8_WAIT_V(8); PG8_WAIT_L(0); PG8_BAR; PG8_MMA(0, 0, At, B0); PG8_MMA(0, 1, At, B1); PG8_BAR; PG8_SCHED;
;             PG8_LDA(At, 0, 1); PG8_STAGE(PG8_SB(0, 0), b2, voffB); PG8_STAGE(PG8_SB(0, 1), b2 + hstepB, voffB); PG8_STAGE(PG8_SA(0, 0), a2, voffA);
;             PG8_WAIT_V(8); PG8_WAIT_L(0); PG8_BAR; PG8_MMA(1, 0, At, B0); PG8_MMA(1, 1, At, B1); PG8_BAR; PG8_SCHED;
.LBB0_1175:
	v_add_u32_e32 v92, 0x10000, v160
	v_add_u32_e32 v144, 0x14000, v160
	ds_read_b128 v[80:83], v92
	ds_read_b128 v[84:87], v92 offset:1024
	ds_read_b128 v[88:91], v92 offset:2048
	ds_read_b128 v[92:95], v92 offset:3072
	ds_read_b128 v[164:167], v144
	ds_read_b128 v[168:171], v144 offset:1024
	ds_read_b128 v[172:175], v144 offset:2048
	ds_read_b128 v[176:179], v144 offset:3072
	s_add_i32 s88, s22, 2
	s_cmp_eq_u32 s62, s22
	s_cselect_b32 s26, s16, s79
	s_cselect_b32 s27, s17, s85
	s_cselect_b32 s24, s84, s86
	s_cselect_b32 s25, s83, s87
	s_add_u32 s22, s26, 0x80
	s_addc_u32 s23, s27, 0
	ds_read_b128 v[180:183], v161
	ds_read_b128 v[184:187], v161 offset:1024
	ds_read_b128 v[188:191], v161 offset:2048
	ds_read_b128 v[194:197], v161 offset:3072
	ds_read_b128 v[198:201], v161 offset:4096
	ds_read_b128 v[202:205], v161 offset:5120
	ds_read_b128 v[206:209], v161 offset:6144
	ds_read_b128 v[210:213], v161 offset:7168
	s_add_u32 s92, s79, 0x83f80
	s_addc_u32 s93, s85, 0
	s_mov_b32 m0, s54
	s_nop 0
	global_load_lds_dwordx4 v147, s[92:93]
	s_mov_b32 m0, s55
	s_nop 0
	global_load_lds_dwordx4 v151, s[92:93]
	s_waitcnt vmcnt(8) lgkmcnt(0)
	s_setprio 1
	s_barrier
	v_mfma_f32_16x16x32_bf16 v[140:143], v[80:83], v[180:183], v[140:143]
	v_mfma_f32_16x16x32_bf16 v[136:139], v[88:91], v[180:183], v[136:139]
	v_mfma_f32_16x16x32_bf16 v[124:127], v[80:83], v[188:191], v[124:127]
	v_mfma_f32_16x16x32_bf16 v[120:123], v[88:91], v[188:191], v[120:123]
	v_mfma_f32_16x16x32_bf16 v[108:111], v[80:83], v[198:201], v[108:111]
	v_mfma_f32_16x16x32_bf16 v[104:107], v[88:91], v[198:201], v[104:107]
	v_mfma_f32_16x16x32_bf16 v[76:79], v[80:83], v[206:209], v[76:79]
	v_mfma_f32_16x16x32_bf16 v[72:75], v[88:91], v[206:209], v[72:75]
	v_mfma_f32_16x16x32_bf16 v[140:143], v[84:87], v[184:187], v[140:143]
	v_mfma_f32_16x16x32_bf16 v[136:139], v[92:95], v[184:187], v[136:139]
	v_mfma_f32_16x16x32_bf16 v[124:127], v[84:87], v[194:197], v[124:127]
	v_mfma_f32_16x16x32_bf16 v[120:123], v[92:95], v[194:197], v[120:123]
	v_mfma_f32_16x16x32_bf16 v[108:111], v[84:87], v[202:205], v[108:111]
	v_mfma_f32_16x16x32_bf16 v[104:107], v[92:95], v[202:205], v[104:107]
	v_mfma_f32_16x16x32_bf16 v[76:79], v[84:87], v[210:213], v[76:79]
	v_mfma_f32_16x16x32_bf16 v[72:75], v[92:95], v[210:213], v[72:75]
	v_mfma_f32_16x16x32_bf16 v[132:135], v[164:167], v[180:183], v[132:135]
	v_mfma_f32_16x16x32_bf16 v[128:131], v[172:175], v[180:183], v[128:131]
	v_mfma_f32_16x16x32_bf16 v[116:119], v[164:167], v[188:191], v[116:119]
	v_mfma_f32_16x16x32_bf16 v[112:115], v[172:175], v[188:191], v[112:115]
	v_mfma_f32_16x16x32_bf16 v[100:103], v[164:167], v[198:201], v[100:103]
	v_mfma_f32_16x16x32_bf16 v[96:99], v[172:175], v[198:201], v[96:99]
	v_mfma_f32_16x16x32_bf16 v[68:71], v[164:167], v[206:209], v[68:71]
	v_mfma_f32_16x16x32_bf16 v[64:67], v[172:175], v[206:209], v[64:67]
	v_mfma_f32_16x16x32_bf16 v[132:135], v[168:171], v[184:187], v[132:135]
	v_mfma_f32_16x16x32_bf16 v[128:131], v[176:179], v[184:187], v[128:131]
	v_mfma_f32_16x16x32_bf16 v[116:119], v[168:171], v[194:197], v[116:119]
	v_mfma_f32_16x16x32_bf16 v[112:115], v[176:179], v[194:197], v[112:115]
	v_mfma_f32_16x16x32_bf16 v[100:103], v[168:171], v[202:205], v[100:103]
	v_mfma_f32_16x16x32_bf16 v[96:99], v[176:179], v[202:205], v[96:99]
	v_mfma_f32_16x16x32_bf16 v[68:71], v[168:171], v[210:213], v[68:71]
	v_mfma_f32_16x16x32_bf16 v[64:67], v[176:179], v[210:213], v[64:67]
	s_setprio 0
	s_barrier
	ds_read_b128 v[180:183], v161 offset:16384
	ds_read_b128 v[184:187], v161 offset:17408
	ds_read_b128 v[188:191], v161 offset:18432
	ds_read_b128 v[194:197], v161 offset:19456
	ds_read_b128 v[198:201], v161 offset:20480
	ds_read_b128 v[202:205], v161 offset:21504
	ds_read_b128 v[206:209], v161 offset:22528
	ds_read_b128 v[210:213], v161 offset:23552
	s_mov_b32 m0, s33
	s_nop 0
	global_load_lds_dwordx4 v149, s[24:25]
	s_add_u32 s92, s24, 0x80000
	s_mov_b32 m0, s34
	s_nop 0
	global_load_lds_dwordx4 v153, s[24:25]
	s_addc_u32 s93, s25, 0
	s_mov_b32 m0, s35
	s_nop 0
	global_load_lds_dwordx4 v149, s[92:93]
	s_mov_b32 m0, s36
	s_nop 0
	global_load_lds_dwordx4 v153, s[92:93]
	s_mov_b32 m0, s31
	s_nop 0
	global_load_lds_dwordx4 v147, s[26:27]
	s_mov_b32 m0, s37
	s_nop 0
	global_load_lds_dwordx4 v151, s[26:27]
	s_waitcnt vmcnt(8) lgkmcnt(0)
	s_setprio 1
	s_barrier
	v_mfma_f32_16x16x32_bf16 v[60:63], v[80:83], v[180:183], v[60:63]
	v_mfma_f32_16x16x32_bf16 v[56:59], v[88:91], v[180:183], v[56:59]
	v_mfma_f32_16x16x32_bf16 v[44:47], v[80:83], v[188:191], v[44:47]
	v_mfma_f32_16x16x32_bf16 v[40:43], v[88:91], v[188:191], v[40:43]
	v_mfma_f32_16x16x32_bf16 v[28:31], v[80:83], v[198:201], v[28:31]
	v_mfma_f32_16x16x32_bf16 v[24:27], v[88:91], v[198:201], v[24:27]
	v_mfma_f32_16x16x32_bf16 v[12:15], v[80:83], v[206:209], v[12:15]
	v_mfma_f32_16x16x32_bf16 v[8:11], v[88:91], v[206:209], v[8:11]
	v_mfma_f32_16x16x32_bf16 v[60:63], v[84:87], v[184:187], v[60:63]
	v_mfma_f32_16x16x32_bf16 v[56:59], v[92:95], v[184:187], v[56:59]
	v_mfma_f32_16x16x32_bf16 v[44:47], v[84:87], v[194:197], v[44:47]
	v_mfma_f32_16x16x32_bf16 v[40:43], v[92:95], v[194:197], v[40:43]
	v_mfma_f32_16x16x32_bf16 v[28:31], v[84:87], v[202:205], v[28:31]
	v_mfma_f32_16x16x32_bf16 v[24:27], v[92:95], v[202:205], v[24:27]
	v_mfma_f32_16x16x32_bf16 v[12:15], v[84:87], v[210:213], v[12:15]
	v_mfma_f32_16x16x32_bf16 v[8:11], v[92:95], v[210:213], v[8:11]
	v_mfma_f32_16x16x32_bf16 v[52:55], v[164:167], v[180:183], v[52:55]
	v_mfma_f32_16x16x32_bf16 v[48:51], v[172:175], v[180:183], v[48:51]
	v_mfma_f32_16x16x32_bf16 v[36:39], v[164:167], v[188:191], v[36:39]
	v_mfma_f32_16x16x32_bf16 v[32:35], v[172:175], v[188:191], v[32:35]
	v_mfma_f32_16x16x32_bf16 v[20:23], v[164:167], v[198:201], v[20:23]
	v_mfma_f32_16x16x32_bf16 v[16:19], v[172:175], v[198:201], v[16:19]
	v_mfma_f32_16x16x32_bf16 v[4:7], v[164:167], v[206:209], v[4:7]
	v_mfma_f32_16x16x32_bf16 v[0:3], v[172:175], v[206:209], v[0:3]
	v_mfma_f32_16x16x32_bf16 v[52:55], v[168:171], v[184:187], v[52:55]
	v_mfma_f32_16x16x32_bf16 v[48:51], v[176:179], v[184:187], v[48:51]
	v_mfma_f32_16x16x32_bf16 v[36:39], v[168:171], v[194:197], v[36:39]
	v_mfma_f32_16x16x32_bf16 v[32:35], v[176:179], v[194:197], v[32:35]
	v_mfma_f32_16x16x32_bf16 v[20:23], v[168:171], v[202:205], v[20:23]
	v_mfma_f32_16x16x32_bf16 v[16:19], v[176:179], v[202:205], v[16:19]
	v_mfma_f32_16x16x32_bf16 v[4:7], v[168:171], v[210:213], v[4:7]
	v_mfma_f32_16x16x32_bf16 v[0:3], v[176:179], v[210:213], v[0:3]
	s_setprio 0
	s_barrier
; #define PG8_STAGE(bufoff, gbase, voff) do { _Pragma("unroll") for (int _i = 0; _i < 2; ++_i) \
;         asm volatile("s_mov_b32 m0, %0\n\ts_nop 0\n\tglobal_load_lds_dwordx4 %1, %2" :: "s"(ldsb + (unsigned)((bufoff) + _i * 8192)), "v"((voff)[_i]), "s"(gbase) : "m0", "memory"); } while (0)
; #define PG8_LDA(dst, b, h) do { _Pragma("unroll") for (int m = 0; m < 4; ++m) _Pragma("unroll") for (int k = 0; k < 2; ++k) dst[m][k] = *(const PG8_LAS bf16x8*)(lds + PG8_SA(b, h) + aoff + m * 2048 + k * 1024); } while (0)
; #define PG8_LDB(dst, b, h) do { _Pragma("unroll") for (int n = 0; n < 2; ++n) _Pragma("unroll") for (int k = 0; k < 2; ++k) dst[n][k] = *(const PG8_LAS bf16x8*)(lds + PG8_SB(b, h) + boff + n * 2048 + k * 1024); } while (0)
; #define PG8_MMA(ai, bj, At, Bt) do { __builtin_amdgcn_s_setprio(1); _Pragma("unroll") for (int m = 0; m < 4; ++m) _Pragma("unroll") for (int n = 0; n < 2; ++n) _Pragma("unroll") for (int k = 0; k < 2; ++k) \
;         acc[ai][bj][m][n] = __builtin_amdgcn_mfma_f32_16x16x32_bf16(Bt[n][k], At[m][k], acc[ai][bj][m][n], 0, 0, 0); __builtin_amdgcn_s_setprio(0); } while (0)
; #define PG8_WAIT_V(n) asm volatile("s_waitcnt vmcnt(" #n ")" ::: "memory")
; #define PG8_WAIT_L(n) asm volatile("s_waitcnt lgkmcnt(" #n ")" ::: "memory")
; #define PG8_BAR __builtin_amdgcn_s_barrier()
; template <class Epi, class Sched, bool ALIGN_EPI = false, bool SP2 = false>
; __device__ __forceinline__ void gemm_phase(PG8_LAS unsigned char* lds, const Gemm g, const Sched& S, const Epi& E, const int wv) {
;     ...
;         for (int t = 0; t < nt; t += 2) {
;             const bool last = (t == nt - 2);
;             const char* a1 = cA + (size_t)(t + 1) * kstep;
;             const char* a2 = last ? nA : cA + (size_t)(t + 2) * kstep; const char* b2 = last ? nB : cB + (size_t)(t + 2) * kstep;
;             const char* a3 = a2 + kstep; const char* b3 = b2 + kstep;
;     ...
;             PG8_LDB(B0, 1, 0); PG8_LDB(B1, 1, 1); PG8_SCHED; PG8_LDA(At, 1, 0); PG8_STAGE(PG8_SA(0, 1), a2 + hstepA, voffA);
;             PG8_WAIT_V(8); PG8_WAIT_L(0); PG8_BAR; PG8_MMA(0, 0, At, B0); PG8_MMA(0, 1, At, B1); PG8_BAR; PG8_SCHED;
;             PG8_LDA(At, 1, 1); PG8_STAGE(PG8_SB(1, 0), b3, voffB); PG8_STAGE(PG8_SB(1, 1), b3 + hstepB, voffB); PG8_STAGE(PG8_SA(1, 0), a3, voffA);
;             PG8_WAIT_V(8); PG8_WAIT_L(0); PG8_BAR; PG8_MMA(1, 0, At, B0); PG8_MMA(1, 1, At, B1); PG8_BAR; PG8_SCHED;
	v_add_u32_e32 v92, 0x18000, v160
	v_add_u32_e32 v144, 0x1c000, v160
	ds_read_b128 v[80:83], v92
	ds_read_b128 v[84:87], v92 offset:1024
	ds_read_b128 v[88:91], v92 offset:2048
	ds_read_b128 v[92:95], v92 offset:3072
	ds_read_b128 v[164:167], v144
	ds_read_b128 v[168:171], v144 offset:1024
	ds_read_b128 v[172:175], v144 offset:2048
	ds_read_b128 v[176:179], v144 offset:3072
	ds_read_b128 v[180:183], v161 offset:32768
	ds_read_b128 v[184:187], v161 offset:33792
	ds_read_b128 v[188:191], v161 offset:34816
	ds_read_b128 v[194:197], v161 offset:35840
	ds_read_b128 v[198:201], v161 offset:36864
	ds_read_b128 v[202:205], v161 offset:37888
	ds_read_b128 v[206:209], v161 offset:38912
	ds_read_b128 v[210:213], v161 offset:39936
	s_add_u32 s26, s26, 0x84000
	s_addc_u32 s27, s27, 0
	s_mov_b32 m0, s42
	s_nop 0
	global_load_lds_dwordx4 v147, s[26:27]
	s_mov_b32 m0, s43
	s_nop 0
	global_load_lds_dwordx4 v151, s[26:27]
	s_waitcnt vmcnt(8) lgkmcnt(0)
	s_setprio 1
	s_barrier
	v_mfma_f32_16x16x32_bf16 v[140:143], v[80:83], v[180:183], v[140:143]
	v_mfma_f32_16x16x32_bf16 v[136:139], v[88:91], v[180:183], v[136:139]
	v_mfma_f32_16x16x32_bf16 v[124:127], v[80:83], v[188:191], v[124:127]
	v_mfma_f32_16x16x32_bf16 v[120:123], v[88:91], v[188:191], v[120:123]
	v_mfma_f32_16x16x32_bf16 v[108:111], v[80:83], v[198:201], v[108:111]
	v_mfma_f32_16x16x32_bf16 v[104:107], v[88:91], v[198:201], v[104:107]
	v_mfma_f32_16x16x32_bf16 v[76:79], v[80:83], v[206:209], v[76:79]
	v_mfma_f32_16x16x32_bf16 v[72:75], v[88:91], v[206:209], v[72:75]
	v_mfma_f32_16x16x32_bf16 v[140:143], v[84:87], v[184:187], v[140:143]
	v_mfma_f32_16x16x32_bf16 v[136:139], v[92:95], v[184:187], v[136:139]
	v_mfma_f32_16x16x32_bf16 v[124:127], v[84:87], v[194:197], v[124:127]
	v_mfma_f32_16x16x32_bf16 v[120:123], v[92:95], v[194:197], v[120:123]
	v_mfma_f32_16x16x32_bf16 v[108:111], v[84:87], v[202:205], v[108:111]
	v_mfma_f32_16x16x32_bf16 v[104:107], v[92:95], v[202:205], v[104:107]
	v_mfma_f32_16x16x32_bf16 v[76:79], v[84:87], v[210:213], v[76:79]
	v_mfma_f32_16x16x32_bf16 v[72:75], v[92:95], v[210:213], v[72:75]
	v_mfma_f32_16x16x32_bf16 v[132:135], v[164:167], v[180:183], v[132:135]
	v_mfma_f32_16x16x32_bf16 v[128:131], v[172:175], v[180:183], v[128:131]
	v_mfma_f32_16x16x32_bf16 v[116:119], v[164:167], v[188:191], v[116:119]
	v_mfma_f32_16x16x32_bf16 v[112:115], v[172:175], v[188:191], v[112:115]
	v_mfma_f32_16x16x32_bf16 v[100:103], v[164:167], v[198:201], v[100:103]
	v_mfma_f32_16x16x32_bf16 v[96:99], v[172:175], v[198:201], v[96:99]
	v_mfma_f32_16x16x32_bf16 v[68:71], v[164:167], v[206:209], v[68:71]
	v_mfma_f32_16x16x32_bf16 v[64:67], v[172:175], v[206:209], v[64:67]
	v_mfma_f32_16x16x32_bf16 v[132:135], v[168:171], v[184:187], v[132:135]
	v_mfma_f32_16x16x32_bf16 v[128:131], v[176:179], v[184:187], v[128:131]
	v_mfma_f32_16x16x32_bf16 v[116:119], v[168:171], v[194:197], v[116:119]
	v_mfma_f32_16x16x32_bf16 v[112:115], v[176:179], v[194:197], v[112:115]
	v_mfma_f32_16x16x32_bf16 v[100:103], v[168:171], v[202:205], v[100:103]
	v_mfma_f32_16x16x32_bf16 v[96:99], v[176:179], v[202:205], v[96:99]
	v_mfma_f32_16x16x32_bf16 v[68:71], v[168:171], v[210:213], v[68:71]
	v_mfma_f32_16x16x32_bf16 v[64:67], v[176:179], v[210:213], v[64:67]
	s_setprio 0
	s_barrier
	ds_read_b128 v[180:183], v161 offset:49152
	ds_read_b128 v[184:187], v161 offset:50176
	ds_read_b128 v[188:191], v161 offset:51200
	ds_read_b128 v[194:197], v161 offset:52224
	ds_read_b128 v[198:201], v161 offset:53248
	ds_read_b128 v[202:205], v161 offset:54272
	ds_read_b128 v[206:209], v161 offset:55296
	ds_read_b128 v[210:213], v161 offset:56320
	s_add_u32 s26, s24, 0x80
	s_addc_u32 s27, s25, 0
	s_mov_b32 m0, s48
	s_nop 0
	global_load_lds_dwordx4 v149, s[26:27]
	s_add_u32 s24, s24, 0x80080
	s_mov_b32 m0, s49
	s_nop 0
	global_load_lds_dwordx4 v153, s[26:27]
	s_addc_u32 s25, s25, 0
	s_mov_b32 m0, s52
	s_nop 0
	global_load_lds_dwordx4 v149, s[24:25]
	s_mov_b32 m0, s53
	s_nop 0
	global_load_lds_dwordx4 v153, s[24:25]
	s_mov_b32 m0, s50
	s_nop 0
	global_load_lds_dwordx4 v147, s[22:23]
	s_mov_b32 m0, s51
	s_nop 0
	global_load_lds_dwordx4 v151, s[22:23]
	s_waitcnt vmcnt(8) lgkmcnt(0)
	s_setprio 1
	s_barrier
	v_mfma_f32_16x16x32_bf16 v[60:63], v[80:83], v[180:183], v[60:63]
	v_mfma_f32_16x16x32_bf16 v[56:59], v[88:91], v[180:183], v[56:59]
	v_mfma_f32_16x16x32_bf16 v[44:47], v[80:83], v[188:191], v[44:47]
	v_mfma_f32_16x16x32_bf16 v[40:43], v[88:91], v[188:191], v[40:43]
	v_mfma_f32_16x16x32_bf16 v[28:31], v[80:83], v[198:201], v[28:31]
	v_mfma_f32_16x16x32_bf16 v[24:27], v[88:91], v[198:201], v[24:27]
	v_mfma_f32_16x16x32_bf16 v[12:15], v[80:83], v[206:209], v[12:15]
	v_mfma_f32_16x16x32_bf16 v[8:11], v[88:91], v[206:209], v[8:11]
	v_mfma_f32_16x16x32_bf16 v[60:63], v[84:87], v[184:187], v[60:63]
	v_mfma_f32_16x16x32_bf16 v[56:59], v[92:95], v[184:187], v[56:59]
	v_mfma_f32_16x16x32_bf16 v[44:47], v[84:87], v[194:197], v[44:47]
	v_mfma_f32_16x16x32_bf16 v[40:43], v[92:95], v[194:197], v[40:43]
	v_mfma_f32_16x16x32_bf16 v[28:31], v[84:87], v[202:205], v[28:31]
	v_mfma_f32_16x16x32_bf16 v[24:27], v[92:95], v[202:205], v[24:27]
	v_mfma_f32_16x16x32_bf16 v[12:15], v[84:87], v[210:213], v[12:15]
	v_mfma_f32_16x16x32_bf16 v[8:11], v[92:95], v[210:213], v[8:11]
	v_mfma_f32_16x16x32_bf16 v[52:55], v[164:167], v[180:183], v[52:55]
	v_mfma_f32_16x16x32_bf16 v[48:51], v[172:175], v[180:183], v[48:51]
	v_mfma_f32_16x16x32_bf16 v[36:39], v[164:167], v[188:191], v[36:39]
	v_mfma_f32_16x16x32_bf16 v[32:35], v[172:175], v[188:191], v[32:35]
	v_mfma_f32_16x16x32_bf16 v[20:23], v[164:167], v[198:201], v[20:23]
	v_mfma_f32_16x16x32_bf16 v[16:19], v[172:175], v[198:201], v[16:19]
	v_mfma_f32_16x16x32_bf16 v[4:7], v[164:167], v[206:209], v[4:7]
	v_mfma_f32_16x16x32_bf16 v[0:3], v[172:175], v[206:209], v[0:3]
	v_mfma_f32_16x16x32_bf16 v[52:55], v[168:171], v[184:187], v[52:55]
	v_mfma_f32_16x16x32_bf16 v[48:51], v[176:179], v[184:187], v[48:51]
	v_mfma_f32_16x16x32_bf16 v[36:39], v[168:171], v[194:197], v[36:39]
	v_mfma_f32_16x16x32_bf16 v[32:35], v[176:179], v[194:197], v[32:35]
	v_mfma_f32_16x16x32_bf16 v[20:23], v[168:171], v[202:205], v[20:23]
	v_mfma_f32_16x16x32_bf16 v[16:19], v[176:179], v[202:205], v[16:19]
	v_mfma_f32_16x16x32_bf16 v[4:7], v[168:171], v[210:213], v[4:7]
	v_mfma_f32_16x16x32_bf16 v[0:3], v[176:179], v[210:213], v[0:3]
	s_setprio 0
	s_barrier
	s_add_u32 s79, s79, 0x100
	s_addc_u32 s85, s85, 0
	s_add_u32 s86, s86, 0x100
	s_addc_u32 s87, s87, 0
	s_cmp_ge_i32 s88, s40
	s_mov_b32 s22, s88
	s_cbranch_scc0 .LBB0_1175
	v_readlane_b32 s92, v254, 49
	v_readlane_b32 s93, v254, 50
	s_mov_b32 s79, 0xc00000
	s_and_b64 vcc, exec, s[14:15]
	s_cbranch_vccz .LBB0_1178

; #define PG8_STAGE(bufoff, gbase, voff) do { _Pragma("unroll") for (int _i = 0; _i < 2; ++_i) \
;         asm volatile("s_mov_b32 m0, %0\n\ts_nop 0\n\tglobal_load_lds_dwordx4 %1, %2" :: "s"(ldsb + (unsigned)((bufoff) + _i * 8192)), "v"((voff)[_i]), "s"(gbase) : "m0", "memory"); } while (0)
; #define PG8_LDA(dst, b, h) do { _Pragma("unroll") for (int m = 0; m < 4; ++m) _Pragma("unroll") for (int k = 0; k < 2; ++k) dst[m][k] = *(const PG8_LAS bf16x8*)(lds + PG8_SA(b, h) + aoff + m * 2048 + k * 1024); } while (0)
; #define PG8_LDB(dst, b, h) do { _Pragma("unroll") for (int n = 0; n < 2; ++n) _Pragma("unroll") for (int k = 0; k < 2; ++k) dst[n][k] = *(const PG8_LAS bf16x8*)(lds + PG8_SB(b, h) + boff + n * 2048 + k * 1024); } while (0)
; #define PG8_MMA(ai, bj, At, Bt) do { __builtin_amdgcn_s_setprio(1); _Pragma("unroll") for (int m = 0; m < 4; ++m) _Pragma("unroll") for (int n = 0; n < 2; ++n) _Pragma("unroll") for (int k = 0; k < 2; ++k) \
;         acc[ai][bj][m][n] = __builtin_amdgcn_mfma_f32_16x16x32_bf16(Bt[n][k], At[m][k], acc[ai][bj][m][n], 0, 0, 0); __builtin_amdgcn_s_setprio(0); } while (0)
; #define PG8_WAIT_V(n) asm volatile("s_waitcnt vmcnt(" #n ")" ::: "memory")
; #define PG8_WAIT_L(n) asm volatile("s_waitcnt lgkmcnt(" #n ")" ::: "memory")
; #define PG8_BAR __builtin_amdgcn_s_barrier()
; #define PG8_SCHED __builtin_amdgcn_sched_barrier(0)
; template <class Epi, class Sched, bool ALIGN_EPI = false, bool SP2 = false>
; __device__ __forceinline__ void gemm_phase(PG8_LAS unsigned char* lds, const Gemm g, const Sched& S, const Epi& E, const int wv) {
;     ...
;             PG8_LDB(B0, 0, 0); PG8_LDB(B1, 0, 1); PG8_SCHED; PG8_LDA(At, 0, 0); PG8_STAGE(PG8_SA(1, 1), a1 + hstepA, voffA);
;             PG8_WAIT_V(8); PG8_WAIT_L(0); PG8_BAR; PG8_MMA(0, 0, At, B0); PG8_MMA(0, 1, At, B1); PG8_BAR; PG8_SCHED;
;             PG8_LDA(At, 0, 1); PG8_STAGE(PG8_SB(0, 0), b2, voffB); PG8_STAGE(PG8_SB(0, 1), b2 + hstepB, voffB); PG8_STAGE(PG8_SA(0, 0), a2, voffA);
;             PG8_WAIT_V(8); PG8_WAIT_L(0); PG8_BAR; PG8_MMA(1, 0, At, B0); PG8_MMA(1, 1, At, B1); PG8_BAR; PG8_SCHED;
.LBB0_1244:
	v_add_u32_e32 v140, 0x10000, v196
	v_add_u32_e32 v156, 0x14000, v196
	ds_read_b128 v[128:131], v140
	ds_read_b128 v[132:135], v140 offset:1024
	ds_read_b128 v[136:139], v140 offset:2048
	ds_read_b128 v[140:143], v140 offset:3072
	ds_read_b128 v[144:147], v156
	ds_read_b128 v[148:151], v156 offset:1024
	ds_read_b128 v[152:155], v156 offset:2048
	ds_read_b128 v[156:159], v156 offset:3072
	s_add_i32 s85, s20, 2
	s_cmp_eq_u32 s62, s20
	s_cselect_b32 s24, s14, s77
	s_cselect_b32 s25, s15, s79
	s_cselect_b32 s22, s72, s83
	s_cselect_b32 s23, s71, s84
	s_add_u32 s20, s24, 0x80
	s_addc_u32 s21, s25, 0
	ds_read_b128 v[160:163], v197
	ds_read_b128 v[164:167], v197 offset:1024
	ds_read_b128 v[168:171], v197 offset:2048
	ds_read_b128 v[172:175], v197 offset:3072
	ds_read_b128 v[176:179], v197 offset:4096
	ds_read_b128 v[198:201], v197 offset:5120
	ds_read_b128 v[202:205], v197 offset:6144
	ds_read_b128 v[206:209], v197 offset:7168
	s_add_u32 s86, s77, 0x15ff80
	s_addc_u32 s87, s79, 0
	s_mov_b32 m0, s50
	s_nop 0
	global_load_lds_dwordx4 v182, s[86:87]
	s_mov_b32 m0, s52
	s_nop 0
	global_load_lds_dwordx4 v184, s[86:87]
	s_waitcnt vmcnt(8) lgkmcnt(0)
	s_setprio 1
	s_barrier
	v_mfma_f32_16x16x32_bf16 v[124:127], v[128:131], v[160:163], v[124:127]
	v_mfma_f32_16x16x32_bf16 v[120:123], v[136:139], v[160:163], v[120:123]
	v_mfma_f32_16x16x32_bf16 v[108:111], v[128:131], v[168:171], v[108:111]
	v_mfma_f32_16x16x32_bf16 v[104:107], v[136:139], v[168:171], v[104:107]
	v_mfma_f32_16x16x32_bf16 v[92:95], v[128:131], v[176:179], v[92:95]
	v_mfma_f32_16x16x32_bf16 v[88:91], v[136:139], v[176:179], v[88:91]
	v_mfma_f32_16x16x32_bf16 v[76:79], v[128:131], v[202:205], v[76:79]
	v_mfma_f32_16x16x32_bf16 v[72:75], v[136:139], v[202:205], v[72:75]
	v_mfma_f32_16x16x32_bf16 v[124:127], v[132:135], v[164:167], v[124:127]
	v_mfma_f32_16x16x32_bf16 v[120:123], v[140:143], v[164:167], v[120:123]
	v_mfma_f32_16x16x32_bf16 v[108:111], v[132:135], v[172:175], v[108:111]
	v_mfma_f32_16x16x32_bf16 v[104:107], v[140:143], v[172:175], v[104:107]
	v_mfma_f32_16x16x32_bf16 v[92:95], v[132:135], v[198:201], v[92:95]
	v_mfma_f32_16x16x32_bf16 v[88:91], v[140:143], v[198:201], v[88:91]
	v_mfma_f32_16x16x32_bf16 v[76:79], v[132:135], v[206:209], v[76:79]
	v_mfma_f32_16x16x32_bf16 v[72:75], v[140:143], v[206:209], v[72:75]
	v_mfma_f32_16x16x32_bf16 v[116:119], v[144:147], v[160:163], v[116:119]
	v_mfma_f32_16x16x32_bf16 v[112:115], v[152:155], v[160:163], v[112:115]
	v_mfma_f32_16x16x32_bf16 v[100:103], v[144:147], v[168:171], v[100:103]
	v_mfma_f32_16x16x32_bf16 v[96:99], v[152:155], v[168:171], v[96:99]
	v_mfma_f32_16x16x32_bf16 v[84:87], v[144:147], v[176:179], v[84:87]
	v_mfma_f32_16x16x32_bf16 v[80:83], v[152:155], v[176:179], v[80:83]
	v_mfma_f32_16x16x32_bf16 v[68:71], v[144:147], v[202:205], v[68:71]
	v_mfma_f32_16x16x32_bf16 v[64:67], v[152:155], v[202:205], v[64:67]
	v_mfma_f32_16x16x32_bf16 v[116:119], v[148:151], v[164:167], v[116:119]
	v_mfma_f32_16x16x32_bf16 v[112:115], v[156:159], v[164:167], v[112:115]
	v_mfma_f32_16x16x32_bf16 v[100:103], v[148:151], v[172:175], v[100:103]
	v_mfma_f32_16x16x32_bf16 v[96:99], v[156:159], v[172:175], v[96:99]
	v_mfma_f32_16x16x32_bf16 v[84:87], v[148:151], v[198:201], v[84:87]
	v_mfma_f32_16x16x32_bf16 v[80:83], v[156:159], v[198:201], v[80:83]
	v_mfma_f32_16x16x32_bf16 v[68:71], v[148:151], v[206:209], v[68:71]
	v_mfma_f32_16x16x32_bf16 v[64:67], v[156:159], v[206:209], v[64:67]
	s_setprio 0
	s_barrier
	ds_read_b128 v[160:163], v197 offset:16384
	ds_read_b128 v[164:167], v197 offset:17408
	ds_read_b128 v[168:171], v197 offset:18432
	ds_read_b128 v[172:175], v197 offset:19456
	ds_read_b128 v[176:179], v197 offset:20480
	ds_read_b128 v[198:201], v197 offset:21504
	ds_read_b128 v[202:205], v197 offset:22528
	ds_read_b128 v[206:209], v197 offset:23552
	s_mov_b32 m0, s29
	s_nop 0
	global_load_lds_dwordx4 v183, s[22:23]
	s_add_u32 s86, s22, 0x160000
	s_mov_b32 m0, s30
	s_nop 0
	global_load_lds_dwordx4 v185, s[22:23]
	s_addc_u32 s87, s23, 0
	s_mov_b32 m0, s31
	s_nop 0
	global_load_lds_dwordx4 v183, s[86:87]
	s_mov_b32 m0, s33
	s_nop 0
	global_load_lds_dwordx4 v185, s[86:87]
	s_mov_b32 m0, s28
	s_nop 0
	global_load_lds_dwordx4 v182, s[24:25]
	s_mov_b32 m0, s34
	s_nop 0
	global_load_lds_dwordx4 v184, s[24:25]
	s_waitcnt vmcnt(8) lgkmcnt(0)
	s_setprio 1
	s_barrier
	v_mfma_f32_16x16x32_bf16 v[60:63], v[128:131], v[160:163], v[60:63]
	v_mfma_f32_16x16x32_bf16 v[56:59], v[136:139], v[160:163], v[56:59]
	v_mfma_f32_16x16x32_bf16 v[44:47], v[128:131], v[168:171], v[44:47]
	v_mfma_f32_16x16x32_bf16 v[40:43], v[136:139], v[168:171], v[40:43]
	v_mfma_f32_16x16x32_bf16 v[28:31], v[128:131], v[176:179], v[28:31]
	v_mfma_f32_16x16x32_bf16 v[24:27], v[136:139], v[176:179], v[24:27]
	v_mfma_f32_16x16x32_bf16 v[12:15], v[128:131], v[202:205], v[12:15]
	v_mfma_f32_16x16x32_bf16 v[8:11], v[136:139], v[202:205], v[8:11]
	v_mfma_f32_16x16x32_bf16 v[60:63], v[132:135], v[164:167], v[60:63]
	v_mfma_f32_16x16x32_bf16 v[56:59], v[140:143], v[164:167], v[56:59]
	v_mfma_f32_16x16x32_bf16 v[44:47], v[132:135], v[172:175], v[44:47]
	v_mfma_f32_16x16x32_bf16 v[40:43], v[140:143], v[172:175], v[40:43]
	v_mfma_f32_16x16x32_bf16 v[28:31], v[132:135], v[198:201], v[28:31]
	v_mfma_f32_16x16x32_bf16 v[24:27], v[140:143], v[198:201], v[24:27]
	v_mfma_f32_16x16x32_bf16 v[12:15], v[132:135], v[206:209], v[12:15]
	v_mfma_f32_16x16x32_bf16 v[8:11], v[140:143], v[206:209], v[8:11]
	v_mfma_f32_16x16x32_bf16 v[52:55], v[144:147], v[160:163], v[52:55]
	v_mfma_f32_16x16x32_bf16 v[48:51], v[152:155], v[160:163], v[48:51]
	v_mfma_f32_16x16x32_bf16 v[36:39], v[144:147], v[168:171], v[36:39]
	v_mfma_f32_16x16x32_bf16 v[32:35], v[152:155], v[168:171], v[32:35]
	v_mfma_f32_16x16x32_bf16 v[20:23], v[144:147], v[176:179], v[20:23]
	v_mfma_f32_16x16x32_bf16 v[16:19], v[152:155], v[176:179], v[16:19]
	v_mfma_f32_16x16x32_bf16 v[4:7], v[144:147], v[202:205], v[4:7]
	v_mfma_f32_16x16x32_bf16 v[0:3], v[152:155], v[202:205], v[0:3]
	v_mfma_f32_16x16x32_bf16 v[52:55], v[148:151], v[164:167], v[52:55]
	v_mfma_f32_16x16x32_bf16 v[48:51], v[156:159], v[164:167], v[48:51]
	v_mfma_f32_16x16x32_bf16 v[36:39], v[148:151], v[172:175], v[36:39]
	v_mfma_f32_16x16x32_bf16 v[32:35], v[156:159], v[172:175], v[32:35]
	v_mfma_f32_16x16x32_bf16 v[20:23], v[148:151], v[198:201], v[20:23]
	v_mfma_f32_16x16x32_bf16 v[16:19], v[156:159], v[198:201], v[16:19]
	v_mfma_f32_16x16x32_bf16 v[4:7], v[148:151], v[206:209], v[4:7]
	v_mfma_f32_16x16x32_bf16 v[0:3], v[156:159], v[206:209], v[0:3]
	s_setprio 0
	s_barrier
; #define PG8_STAGE(bufoff, gbase, voff) do { _Pragma("unroll") for (int _i = 0; _i < 2; ++_i) \
;         asm volatile("s_mov_b32 m0, %0\n\ts_nop 0\n\tglobal_load_lds_dwordx4 %1, %2" :: "s"(ldsb + (unsigned)((bufoff) + _i * 8192)), "v"((voff)[_i]), "s"(gbase) : "m0", "memory"); } while (0)
; #define PG8_LDA(dst, b, h) do { _Pragma("unroll") for (int m = 0; m < 4; ++m) _Pragma("unroll") for (int k = 0; k < 2; ++k) dst[m][k] = *(const PG8_LAS bf16x8*)(lds + PG8_SA(b, h) + aoff + m * 2048 + k * 1024); } while (0)
; #define PG8_LDB(dst, b, h) do { _Pragma("unroll") for (int n = 0; n < 2; ++n) _Pragma("unroll") for (int k = 0; k < 2; ++k) dst[n][k] = *(const PG8_LAS bf16x8*)(lds + PG8_SB(b, h) + boff + n * 2048 + k * 1024); } while (0)
; #define PG8_MMA(ai, bj, At, Bt) do { __builtin_amdgcn_s_setprio(1); _Pragma("unroll") for (int m = 0; m < 4; ++m) _Pragma("unroll") for (int n = 0; n < 2; ++n) _Pragma("unroll") for (int k = 0; k < 2; ++k) \
;         acc[ai][bj][m][n] = __builtin_amdgcn_mfma_f32_16x16x32_bf16(Bt[n][k], At[m][k], acc[ai][bj][m][n], 0, 0, 0); __builtin_amdgcn_s_setprio(0); } while (0)
; #define PG8_WAIT_V(n) asm volatile("s_waitcnt vmcnt(" #n ")" ::: "memory")
; #define PG8_WAIT_L(n) asm volatile("s_waitcnt lgkmcnt(" #n ")" ::: "memory")
; #define PG8_BAR __builtin_amdgcn_s_barrier()
; template <class Epi, class Sched, bool ALIGN_EPI = false, bool SP2 = false>
; __device__ __forceinline__ void gemm_phase(PG8_LAS unsigned char* lds, const Gemm g, const Sched& S, const Epi& E, const int wv) {
;     ...
;         for (int t = 0; t < nt; t += 2) {
;             const bool last = (t == nt - 2);
;             const char* a1 = cA + (size_t)(t + 1) * kstep;
;             const char* a2 = last ? nA : cA + (size_t)(t + 2) * kstep; const char* b2 = last ? nB : cB + (size_t)(t + 2) * kstep;
;             const char* a3 = a2 + kstep; const char* b3 = b2 + kstep;
;     ...
;             PG8_LDB(B0, 1, 0); PG8_LDB(B1, 1, 1); PG8_SCHED; PG8_LDA(At, 1, 0); PG8_STAGE(PG8_SA(0, 1), a2 + hstepA, voffA);
;             PG8_WAIT_V(8); PG8_WAIT_L(0); PG8_BAR; PG8_MMA(0, 0, At, B0); PG8_MMA(0, 1, At, B1); PG8_BAR; PG8_SCHED;
;             PG8_LDA(At, 1, 1); PG8_STAGE(PG8_SB(1, 0), b3, voffB); PG8_STAGE(PG8_SB(1, 1), b3 + hstepB, voffB); PG8_STAGE(PG8_SA(1, 0), a3, voffA);
;             PG8_WAIT_V(8); PG8_WAIT_L(0); PG8_BAR; PG8_MMA(1, 0, At, B0); PG8_MMA(1, 1, At, B1); PG8_BAR; PG8_SCHED;
	v_add_u32_e32 v140, 0x18000, v196
	v_add_u32_e32 v156, 0x1c000, v196
	ds_read_b128 v[128:131], v140
	ds_read_b128 v[132:135], v140 offset:1024
	ds_read_b128 v[136:139], v140 offset:2048
	ds_read_b128 v[140:143], v140 offset:3072
	ds_read_b128 v[144:147], v156
	ds_read_b128 v[148:151], v156 offset:1024
	ds_read_b128 v[152:155], v156 offset:2048
	ds_read_b128 v[156:159], v156 offset:3072
	ds_read_b128 v[160:163], v197 offset:32768
	ds_read_b128 v[164:167], v197 offset:33792
	ds_read_b128 v[168:171], v197 offset:34816
	ds_read_b128 v[172:175], v197 offset:35840
	ds_read_b128 v[176:179], v197 offset:36864
	ds_read_b128 v[198:201], v197 offset:37888
	ds_read_b128 v[202:205], v197 offset:38912
	ds_read_b128 v[206:209], v197 offset:39936
	s_add_u32 s24, s24, 0x160000
	s_addc_u32 s25, s25, 0
	s_mov_b32 m0, s35
	s_nop 0
	global_load_lds_dwordx4 v182, s[24:25]
	s_mov_b32 m0, s36
	s_nop 0
	global_load_lds_dwordx4 v184, s[24:25]
	s_waitcnt vmcnt(8) lgkmcnt(0)
	s_setprio 1
	s_barrier
	v_mfma_f32_16x16x32_bf16 v[124:127], v[128:131], v[160:163], v[124:127]
	v_mfma_f32_16x16x32_bf16 v[120:123], v[136:139], v[160:163], v[120:123]
	v_mfma_f32_16x16x32_bf16 v[108:111], v[128:131], v[168:171], v[108:111]
	v_mfma_f32_16x16x32_bf16 v[104:107], v[136:139], v[168:171], v[104:107]
	v_mfma_f32_16x16x32_bf16 v[92:95], v[128:131], v[176:179], v[92:95]
	v_mfma_f32_16x16x32_bf16 v[88:91], v[136:139], v[176:179], v[88:91]
	v_mfma_f32_16x16x32_bf16 v[76:79], v[128:131], v[202:205], v[76:79]
	v_mfma_f32_16x16x32_bf16 v[72:75], v[136:139], v[202:205], v[72:75]
	v_mfma_f32_16x16x32_bf16 v[124:127], v[132:135], v[164:167], v[124:127]
	v_mfma_f32_16x16x32_bf16 v[120:123], v[140:143], v[164:167], v[120:123]
	v_mfma_f32_16x16x32_bf16 v[108:111], v[132:135], v[172:175], v[108:111]
	v_mfma_f32_16x16x32_bf16 v[104:107], v[140:143], v[172:175], v[104:107]
	v_mfma_f32_16x16x32_bf16 v[92:95], v[132:135], v[198:201], v[92:95]
	v_mfma_f32_16x16x32_bf16 v[88:91], v[140:143], v[198:201], v[88:91]
	v_mfma_f32_16x16x32_bf16 v[76:79], v[132:135], v[206:209], v[76:79]
	v_mfma_f32_16x16x32_bf16 v[72:75], v[140:143], v[206:209], v[72:75]
	v_mfma_f32_16x16x32_bf16 v[116:119], v[144:147], v[160:163], v[116:119]
	v_mfma_f32_16x16x32_bf16 v[112:115], v[152:155], v[160:163], v[112:115]
	v_mfma_f32_16x16x32_bf16 v[100:103], v[144:147], v[168:171], v[100:103]
	v_mfma_f32_16x16x32_bf16 v[96:99], v[152:155], v[168:171], v[96:99]
	v_mfma_f32_16x16x32_bf16 v[84:87], v[144:147], v[176:179], v[84:87]
	v_mfma_f32_16x16x32_bf16 v[80:83], v[152:155], v[176:179], v[80:83]
	v_mfma_f32_16x16x32_bf16 v[68:71], v[144:147], v[202:205], v[68:71]
	v_mfma_f32_16x16x32_bf16 v[64:67], v[152:155], v[202:205], v[64:67]
	v_mfma_f32_16x16x32_bf16 v[116:119], v[148:151], v[164:167], v[116:119]
	v_mfma_f32_16x16x32_bf16 v[112:115], v[156:159], v[164:167], v[112:115]
	v_mfma_f32_16x16x32_bf16 v[100:103], v[148:151], v[172:175], v[100:103]
	v_mfma_f32_16x16x32_bf16 v[96:99], v[156:159], v[172:175], v[96:99]
	v_mfma_f32_16x16x32_bf16 v[84:87], v[148:151], v[198:201], v[84:87]
	v_mfma_f32_16x16x32_bf16 v[80:83], v[156:159], v[198:201], v[80:83]
	v_mfma_f32_16x16x32_bf16 v[68:71], v[148:151], v[206:209], v[68:71]
	v_mfma_f32_16x16x32_bf16 v[64:67], v[156:159], v[206:209], v[64:67]
	s_setprio 0
	s_barrier
	ds_read_b128 v[160:163], v197 offset:49152
	ds_read_b128 v[164:167], v197 offset:50176
	ds_read_b128 v[168:171], v197 offset:51200
	ds_read_b128 v[172:175], v197 offset:52224
	ds_read_b128 v[176:179], v197 offset:53248
	ds_read_b128 v[198:201], v197 offset:54272
	ds_read_b128 v[202:205], v197 offset:55296
	ds_read_b128 v[206:209], v197 offset:56320
	s_add_u32 s24, s22, 0x80
	s_addc_u32 s25, s23, 0
	s_mov_b32 m0, s44
	s_nop 0
	global_load_lds_dwordx4 v183, s[24:25]
	s_add_u32 s22, s22, 0x160080
	s_mov_b32 m0, s45
	s_nop 0
	global_load_lds_dwordx4 v185, s[24:25]
	s_addc_u32 s23, s23, 0
	s_mov_b32 m0, s48
	s_nop 0
	global_load_lds_dwordx4 v183, s[22:23]
	s_mov_b32 m0, s49
	s_nop 0
	global_load_lds_dwordx4 v185, s[22:23]
	s_mov_b32 m0, s46
	s_nop 0
	global_load_lds_dwordx4 v182, s[20:21]
	s_mov_b32 m0, s47
	s_nop 0
	global_load_lds_dwordx4 v184, s[20:21]
	s_waitcnt vmcnt(8) lgkmcnt(0)
	s_setprio 1
	s_barrier
	v_mfma_f32_16x16x32_bf16 v[60:63], v[128:131], v[160:163], v[60:63]
	v_mfma_f32_16x16x32_bf16 v[56:59], v[136:139], v[160:163], v[56:59]
	v_mfma_f32_16x16x32_bf16 v[44:47], v[128:131], v[168:171], v[44:47]
	v_mfma_f32_16x16x32_bf16 v[40:43], v[136:139], v[168:171], v[40:43]
	v_mfma_f32_16x16x32_bf16 v[28:31], v[128:131], v[176:179], v[28:31]
	v_mfma_f32_16x16x32_bf16 v[24:27], v[136:139], v[176:179], v[24:27]
	v_mfma_f32_16x16x32_bf16 v[12:15], v[128:131], v[202:205], v[12:15]
	v_mfma_f32_16x16x32_bf16 v[8:11], v[136:139], v[202:205], v[8:11]
	v_mfma_f32_16x16x32_bf16 v[60:63], v[132:135], v[164:167], v[60:63]
	v_mfma_f32_16x16x32_bf16 v[56:59], v[140:143], v[164:167], v[56:59]
	v_mfma_f32_16x16x32_bf16 v[44:47], v[132:135], v[172:175], v[44:47]
	v_mfma_f32_16x16x32_bf16 v[40:43], v[140:143], v[172:175], v[40:43]
	v_mfma_f32_16x16x32_bf16 v[28:31], v[132:135], v[198:201], v[28:31]
	v_mfma_f32_16x16x32_bf16 v[24:27], v[140:143], v[198:201], v[24:27]
	v_mfma_f32_16x16x32_bf16 v[12:15], v[132:135], v[206:209], v[12:15]
	v_mfma_f32_16x16x32_bf16 v[8:11], v[140:143], v[206:209], v[8:11]
	v_mfma_f32_16x16x32_bf16 v[52:55], v[144:147], v[160:163], v[52:55]
	v_mfma_f32_16x16x32_bf16 v[48:51], v[152:155], v[160:163], v[48:51]
	v_mfma_f32_16x16x32_bf16 v[36:39], v[144:147], v[168:171], v[36:39]
	v_mfma_f32_16x16x32_bf16 v[32:35], v[152:155], v[168:171], v[32:35]
	v_mfma_f32_16x16x32_bf16 v[20:23], v[144:147], v[176:179], v[20:23]
	v_mfma_f32_16x16x32_bf16 v[16:19], v[152:155], v[176:179], v[16:19]
	v_mfma_f32_16x16x32_bf16 v[4:7], v[144:147], v[202:205], v[4:7]
	v_mfma_f32_16x16x32_bf16 v[0:3], v[152:155], v[202:205], v[0:3]
	v_mfma_f32_16x16x32_bf16 v[52:55], v[148:151], v[164:167], v[52:55]
	v_mfma_f32_16x16x32_bf16 v[48:51], v[156:159], v[164:167], v[48:51]
	v_mfma_f32_16x16x32_bf16 v[36:39], v[148:151], v[172:175], v[36:39]
	v_mfma_f32_16x16x32_bf16 v[32:35], v[156:159], v[172:175], v[32:35]
	v_mfma_f32_16x16x32_bf16 v[20:23], v[148:151], v[198:201], v[20:23]
	v_mfma_f32_16x16x32_bf16 v[16:19], v[156:159], v[198:201], v[16:19]
	v_mfma_f32_16x16x32_bf16 v[4:7], v[148:151], v[206:209], v[4:7]
	v_mfma_f32_16x16x32_bf16 v[0:3], v[156:159], v[206:209], v[0:3]
	s_setprio 0
	s_barrier
	s_add_u32 s77, s77, 0x100
	s_addc_u32 s79, s79, 0
	s_add_u32 s83, s83, 0x100
	s_addc_u32 s84, s84, 0
	s_cmp_ge_i32 s85, s65
	s_mov_b32 s20, s85
	s_cbranch_scc0 .LBB0_1244
	s_mov_b32 s79, 0xc00000
	s_and_b64 vcc, exec, s[12:13]
	s_cbranch_vccz .LBB0_1247

; #define PG8_STAGE(bufoff, gbase, voff) do { _Pragma("unroll") for (int _i = 0; _i < 2; ++_i) \
;         asm volatile("s_mov_b32 m0, %0\n\ts_nop 0\n\tglobal_load_lds_dwordx4 %1, %2" :: "s"(ldsb + (unsigned)((bufoff) + _i * 8192)), "v"((voff)[_i]), "s"(gbase) : "m0", "memory"); } while (0)
; #define PG8_LDA(dst, b, h) do { _Pragma("unroll") for (int m = 0; m < 4; ++m) _Pragma("unroll") for (int k = 0; k < 2; ++k) dst[m][k] = *(const PG8_LAS bf16x8*)(lds + PG8_SA(b, h) + aoff + m * 2048 + k * 1024); } while (0)
; #define PG8_LDB(dst, b, h) do { _Pragma("unroll") for (int n = 0; n < 2; ++n) _Pragma("unroll") for (int k = 0; k < 2; ++k) dst[n][k] = *(const PG8_LAS bf16x8*)(lds + PG8_SB(b, h) + boff + n * 2048 + k * 1024); } while (0)
; #define PG8_MMA(ai, bj, At, Bt) do { __builtin_amdgcn_s_setprio(1); _Pragma("unroll") for (int m = 0; m < 4; ++m) _Pragma("unroll") for (int n = 0; n < 2; ++n) _Pragma("unroll") for (int k = 0; k < 2; ++k) \
;         acc[ai][bj][m][n] = __builtin_amdgcn_mfma_f32_16x16x32_bf16(Bt[n][k], At[m][k], acc[ai][bj][m][n], 0, 0, 0); __builtin_amdgcn_s_setprio(0); } while (0)
; #define PG8_WAIT_V(n) asm volatile("s_waitcnt vmcnt(" #n ")" ::: "memory")
; #define PG8_WAIT_L(n) asm volatile("s_waitcnt lgkmcnt(" #n ")" ::: "memory")
; #define PG8_BAR __builtin_amdgcn_s_barrier()
; #define PG8_SCHED __builtin_amdgcn_sched_barrier(0)
; template <class Epi, class Sched, bool ALIGN_EPI = false, bool SP2 = false>
; __device__ __forceinline__ void gemm_phase(PG8_LAS unsigned char* lds, const Gemm g, const Sched& S, const Epi& E, const int wv) {
;     ...
;             PG8_LDB(B0, 0, 0); PG8_LDB(B1, 0, 1); PG8_SCHED; PG8_LDA(At, 0, 0); PG8_STAGE(PG8_SA(1, 1), a1 + hstepA, voffA);
;             PG8_WAIT_V(8); PG8_WAIT_L(0); PG8_BAR; PG8_MMA(0, 0, At, B0); PG8_MMA(0, 1, At, B1); PG8_BAR; PG8_SCHED;
;             PG8_LDA(At, 0, 1); PG8_STAGE(PG8_SB(0, 0), b2, voffB); PG8_STAGE(PG8_SB(0, 1), b2 + hstepB, voffB); PG8_STAGE(PG8_SA(0, 0), a2, voffA);
;             PG8_WAIT_V(8); PG8_WAIT_L(0); PG8_BAR; PG8_MMA(1, 0, At, B0); PG8_MMA(1, 1, At, B1); PG8_BAR; PG8_SCHED;
.LBB0_1336:
	v_add_u32_e32 v140, 0x10000, v220
	v_add_u32_e32 v159, 0x14000, v220
	ds_read_b128 v[128:131], v140
	ds_read_b128 v[132:135], v140 offset:1024
	ds_read_b128 v[136:139], v140 offset:2048
	ds_read_b128 v[140:143], v140 offset:3072
	ds_read_b128 v[144:147], v159
	ds_read_b128 v[148:151], v159 offset:1024
	ds_read_b128 v[152:155], v159 offset:2048
	ds_read_b128 v[160:163], v159 offset:3072
	s_add_i32 vcc_hi, s34, 2
	s_cmp_eq_u32 s25, s34
	s_cselect_b32 s42, s26, s85
	s_cselect_b32 s43, s27, vcc_lo
	s_cselect_b32 s36, s28, s79
	s_cselect_b32 s37, s29, s62
	s_add_u32 s34, s42, 0x80
	s_addc_u32 s35, s43, 0
	ds_read_b128 v[164:167], v221
	ds_read_b128 v[168:171], v221 offset:1024
	ds_read_b128 v[172:175], v221 offset:2048
	ds_read_b128 v[176:179], v221 offset:3072
	ds_read_b128 v[180:183], v221 offset:4096
	ds_read_b128 v[184:187], v221 offset:5120
	ds_read_b128 v[188:191], v221 offset:6144
	ds_read_b128 v[194:197], v221 offset:7168
	s_mov_b32 m0, s71
	s_nop 0
	global_load_lds_dwordx4 v208, s[30:31]
	s_mov_b32 m0, s88
	s_nop 0
	global_load_lds_dwordx4 v210, s[30:31]
	s_waitcnt vmcnt(8) lgkmcnt(0)
	s_setprio 1
	s_barrier
	v_mfma_f32_16x16x32_bf16 v[124:127], v[128:131], v[164:167], v[124:127]
	v_mfma_f32_16x16x32_bf16 v[120:123], v[136:139], v[164:167], v[120:123]
	v_mfma_f32_16x16x32_bf16 v[108:111], v[128:131], v[172:175], v[108:111]
	v_mfma_f32_16x16x32_bf16 v[104:107], v[136:139], v[172:175], v[104:107]
	v_mfma_f32_16x16x32_bf16 v[92:95], v[128:131], v[180:183], v[92:95]
	v_mfma_f32_16x16x32_bf16 v[88:91], v[136:139], v[180:183], v[88:91]
	v_mfma_f32_16x16x32_bf16 v[76:79], v[128:131], v[188:191], v[76:79]
	v_mfma_f32_16x16x32_bf16 v[72:75], v[136:139], v[188:191], v[72:75]
	v_mfma_f32_16x16x32_bf16 v[124:127], v[132:135], v[168:171], v[124:127]
	v_mfma_f32_16x16x32_bf16 v[120:123], v[140:143], v[168:171], v[120:123]
	v_mfma_f32_16x16x32_bf16 v[108:111], v[132:135], v[176:179], v[108:111]
	v_mfma_f32_16x16x32_bf16 v[104:107], v[140:143], v[176:179], v[104:107]
	v_mfma_f32_16x16x32_bf16 v[92:95], v[132:135], v[184:187], v[92:95]
	v_mfma_f32_16x16x32_bf16 v[88:91], v[140:143], v[184:187], v[88:91]
	v_mfma_f32_16x16x32_bf16 v[76:79], v[132:135], v[194:197], v[76:79]
	v_mfma_f32_16x16x32_bf16 v[72:75], v[140:143], v[194:197], v[72:75]
	v_mfma_f32_16x16x32_bf16 v[116:119], v[144:147], v[164:167], v[116:119]
	v_mfma_f32_16x16x32_bf16 v[112:115], v[152:155], v[164:167], v[112:115]
	v_mfma_f32_16x16x32_bf16 v[100:103], v[144:147], v[172:175], v[100:103]
	v_mfma_f32_16x16x32_bf16 v[96:99], v[152:155], v[172:175], v[96:99]
	v_mfma_f32_16x16x32_bf16 v[84:87], v[144:147], v[180:183], v[84:87]
	v_mfma_f32_16x16x32_bf16 v[80:83], v[152:155], v[180:183], v[80:83]
	v_mfma_f32_16x16x32_bf16 v[68:71], v[144:147], v[188:191], v[68:71]
	v_mfma_f32_16x16x32_bf16 v[64:67], v[152:155], v[188:191], v[64:67]
	v_mfma_f32_16x16x32_bf16 v[116:119], v[148:151], v[168:171], v[116:119]
	v_mfma_f32_16x16x32_bf16 v[112:115], v[160:163], v[168:171], v[112:115]
	v_mfma_f32_16x16x32_bf16 v[100:103], v[148:151], v[176:179], v[100:103]
	v_mfma_f32_16x16x32_bf16 v[96:99], v[160:163], v[176:179], v[96:99]
	v_mfma_f32_16x16x32_bf16 v[84:87], v[148:151], v[184:187], v[84:87]
	v_mfma_f32_16x16x32_bf16 v[80:83], v[160:163], v[184:187], v[80:83]
	v_mfma_f32_16x16x32_bf16 v[68:71], v[148:151], v[194:197], v[68:71]
	v_mfma_f32_16x16x32_bf16 v[64:67], v[160:163], v[194:197], v[64:67]
	s_setprio 0
	s_barrier
	ds_read_b128 v[164:167], v221 offset:16384
	ds_read_b128 v[168:171], v221 offset:17408
	ds_read_b128 v[172:175], v221 offset:18432
	ds_read_b128 v[176:179], v221 offset:19456
	ds_read_b128 v[180:183], v221 offset:20480
	ds_read_b128 v[184:187], v221 offset:21504
	ds_read_b128 v[188:191], v221 offset:22528
	ds_read_b128 v[194:197], v221 offset:23552
	s_mov_b32 m0, s47
	s_nop 0
	global_load_lds_dwordx4 v209, s[36:37]
	s_add_u32 s10, s36, 0x160000
	s_mov_b32 m0, s48
	s_nop 0
	global_load_lds_dwordx4 v211, s[36:37]
	s_addc_u32 s11, s37, 0
	s_mov_b32 m0, s49
	s_nop 0
	global_load_lds_dwordx4 v209, s[10:11]
	s_mov_b32 m0, s50
	s_nop 0
	global_load_lds_dwordx4 v211, s[10:11]
	s_mov_b32 m0, s46
	s_nop 0
	global_load_lds_dwordx4 v208, s[42:43]
	s_mov_b32 m0, s51
	s_nop 0
	global_load_lds_dwordx4 v210, s[42:43]
	s_waitcnt vmcnt(8) lgkmcnt(0)
	s_setprio 1
	s_barrier
	v_mfma_f32_16x16x32_bf16 v[60:63], v[128:131], v[164:167], v[60:63]
	v_mfma_f32_16x16x32_bf16 v[56:59], v[136:139], v[164:167], v[56:59]
	v_mfma_f32_16x16x32_bf16 v[44:47], v[128:131], v[172:175], v[44:47]
	v_mfma_f32_16x16x32_bf16 v[40:43], v[136:139], v[172:175], v[40:43]
	v_mfma_f32_16x16x32_bf16 v[28:31], v[128:131], v[180:183], v[28:31]
	v_mfma_f32_16x16x32_bf16 v[24:27], v[136:139], v[180:183], v[24:27]
	v_mfma_f32_16x16x32_bf16 v[12:15], v[128:131], v[188:191], v[12:15]
	v_mfma_f32_16x16x32_bf16 v[8:11], v[136:139], v[188:191], v[8:11]
	v_mfma_f32_16x16x32_bf16 v[60:63], v[132:135], v[168:171], v[60:63]
	v_mfma_f32_16x16x32_bf16 v[56:59], v[140:143], v[168:171], v[56:59]
	v_mfma_f32_16x16x32_bf16 v[44:47], v[132:135], v[176:179], v[44:47]
	v_mfma_f32_16x16x32_bf16 v[40:43], v[140:143], v[176:179], v[40:43]
	v_mfma_f32_16x16x32_bf16 v[28:31], v[132:135], v[184:187], v[28:31]
	v_mfma_f32_16x16x32_bf16 v[24:27], v[140:143], v[184:187], v[24:27]
	v_mfma_f32_16x16x32_bf16 v[12:15], v[132:135], v[194:197], v[12:15]
	v_mfma_f32_16x16x32_bf16 v[8:11], v[140:143], v[194:197], v[8:11]
	v_mfma_f32_16x16x32_bf16 v[52:55], v[144:147], v[164:167], v[52:55]
	v_mfma_f32_16x16x32_bf16 v[48:51], v[152:155], v[164:167], v[48:51]
	v_mfma_f32_16x16x32_bf16 v[36:39], v[144:147], v[172:175], v[36:39]
	v_mfma_f32_16x16x32_bf16 v[32:35], v[152:155], v[172:175], v[32:35]
	v_mfma_f32_16x16x32_bf16 v[20:23], v[144:147], v[180:183], v[20:23]
	v_mfma_f32_16x16x32_bf16 v[16:19], v[152:155], v[180:183], v[16:19]
	v_mfma_f32_16x16x32_bf16 v[4:7], v[144:147], v[188:191], v[4:7]
	v_mfma_f32_16x16x32_bf16 v[0:3], v[152:155], v[188:191], v[0:3]
	v_mfma_f32_16x16x32_bf16 v[52:55], v[148:151], v[168:171], v[52:55]
	v_mfma_f32_16x16x32_bf16 v[48:51], v[160:163], v[168:171], v[48:51]
	v_mfma_f32_16x16x32_bf16 v[36:39], v[148:151], v[176:179], v[36:39]
	v_mfma_f32_16x16x32_bf16 v[32:35], v[160:163], v[176:179], v[32:35]
	v_mfma_f32_16x16x32_bf16 v[20:23], v[148:151], v[184:187], v[20:23]
	v_mfma_f32_16x16x32_bf16 v[16:19], v[160:163], v[184:187], v[16:19]
	v_mfma_f32_16x16x32_bf16 v[4:7], v[148:151], v[194:197], v[4:7]
	v_mfma_f32_16x16x32_bf16 v[0:3], v[160:163], v[194:197], v[0:3]
	s_setprio 0
	s_barrier
; #define PG8_STAGE(bufoff, gbase, voff) do { _Pragma("unroll") for (int _i = 0; _i < 2; ++_i) \
;         asm volatile("s_mov_b32 m0, %0\n\ts_nop 0\n\tglobal_load_lds_dwordx4 %1, %2" :: "s"(ldsb + (unsigned)((bufoff) + _i * 8192)), "v"((voff)[_i]), "s"(gbase) : "m0", "memory"); } while (0)
; #define PG8_LDA(dst, b, h) do { _Pragma("unroll") for (int m = 0; m < 4; ++m) _Pragma("unroll") for (int k = 0; k < 2; ++k) dst[m][k] = *(const PG8_LAS bf16x8*)(lds + PG8_SA(b, h) + aoff + m * 2048 + k * 1024); } while (0)
; #define PG8_LDB(dst, b, h) do { _Pragma("unroll") for (int n = 0; n < 2; ++n) _Pragma("unroll") for (int k = 0; k < 2; ++k) dst[n][k] = *(const PG8_LAS bf16x8*)(lds + PG8_SB(b, h) + boff + n * 2048 + k * 1024); } while (0)
; #define PG8_MMA(ai, bj, At, Bt) do { __builtin_amdgcn_s_setprio(1); _Pragma("unroll") for (int m = 0; m < 4; ++m) _Pragma("unroll") for (int n = 0; n < 2; ++n) _Pragma("unroll") for (int k = 0; k < 2; ++k) \
;         acc[ai][bj][m][n] = __builtin_amdgcn_mfma_f32_16x16x32_bf16(Bt[n][k], At[m][k], acc[ai][bj][m][n], 0, 0, 0); __builtin_amdgcn_s_setprio(0); } while (0)
; #define PG8_WAIT_V(n) asm volatile("s_waitcnt vmcnt(" #n ")" ::: "memory")
; #define PG8_WAIT_L(n) asm volatile("s_waitcnt lgkmcnt(" #n ")" ::: "memory")
; #define PG8_BAR __builtin_amdgcn_s_barrier()
; template <class Epi, class Sched, bool ALIGN_EPI = false, bool SP2 = false>
; __device__ __forceinline__ void gemm_phase(PG8_LAS unsigned char* lds, const Gemm g, const Sched& S, const Epi& E, const int wv) {
;     ...
;         for (int t = 0; t < nt; t += 2) {
;             const bool last = (t == nt - 2);
;             const char* a1 = cA + (size_t)(t + 1) * kstep;
;             const char* a2 = last ? nA : cA + (size_t)(t + 2) * kstep; const char* b2 = last ? nB : cB + (size_t)(t + 2) * kstep;
;             const char* a3 = a2 + kstep; const char* b3 = b2 + kstep;
;     ...
;             PG8_LDB(B0, 1, 0); PG8_LDB(B1, 1, 1); PG8_SCHED; PG8_LDA(At, 1, 0); PG8_STAGE(PG8_SA(0, 1), a2 + hstepA, voffA);
;             PG8_WAIT_V(8); PG8_WAIT_L(0); PG8_BAR; PG8_MMA(0, 0, At, B0); PG8_MMA(0, 1, At, B1); PG8_BAR; PG8_SCHED;
;             PG8_LDA(At, 1, 1); PG8_STAGE(PG8_SB(1, 0), b3, voffB); PG8_STAGE(PG8_SB(1, 1), b3 + hstepB, voffB); PG8_STAGE(PG8_SA(1, 0), a3, voffA);
;             PG8_WAIT_V(8); PG8_WAIT_L(0); PG8_BAR; PG8_MMA(1, 0, At, B0); PG8_MMA(1, 1, At, B1); PG8_BAR; PG8_SCHED;
	v_add_u32_e32 v140, 0x18000, v220
	v_add_u32_e32 v159, 0x1c000, v220
	ds_read_b128 v[128:131], v140
	ds_read_b128 v[132:135], v140 offset:1024
	ds_read_b128 v[136:139], v140 offset:2048
	ds_read_b128 v[140:143], v140 offset:3072
	ds_read_b128 v[144:147], v159
	ds_read_b128 v[148:151], v159 offset:1024
	ds_read_b128 v[152:155], v159 offset:2048
	ds_read_b128 v[160:163], v159 offset:3072
	ds_read_b128 v[164:167], v221 offset:32768
	ds_read_b128 v[168:171], v221 offset:33792
	ds_read_b128 v[172:175], v221 offset:34816
	ds_read_b128 v[176:179], v221 offset:35840
	ds_read_b128 v[180:183], v221 offset:36864
	ds_read_b128 v[184:187], v221 offset:37888
	ds_read_b128 v[188:191], v221 offset:38912
	ds_read_b128 v[194:197], v221 offset:39936
	s_add_u32 s10, s42, 0x160000
	s_addc_u32 s11, s43, 0
	s_mov_b32 m0, s52
	s_nop 0
	global_load_lds_dwordx4 v208, s[10:11]
	s_mov_b32 m0, s53
	s_nop 0
	global_load_lds_dwordx4 v210, s[10:11]
	s_waitcnt vmcnt(8) lgkmcnt(0)
	s_setprio 1
	s_barrier
	v_mfma_f32_16x16x32_bf16 v[124:127], v[128:131], v[164:167], v[124:127]
	v_mfma_f32_16x16x32_bf16 v[120:123], v[136:139], v[164:167], v[120:123]
	v_mfma_f32_16x16x32_bf16 v[108:111], v[128:131], v[172:175], v[108:111]
	v_mfma_f32_16x16x32_bf16 v[104:107], v[136:139], v[172:175], v[104:107]
	v_mfma_f32_16x16x32_bf16 v[92:95], v[128:131], v[180:183], v[92:95]
	v_mfma_f32_16x16x32_bf16 v[88:91], v[136:139], v[180:183], v[88:91]
	v_mfma_f32_16x16x32_bf16 v[76:79], v[128:131], v[188:191], v[76:79]
	v_mfma_f32_16x16x32_bf16 v[72:75], v[136:139], v[188:191], v[72:75]
	v_mfma_f32_16x16x32_bf16 v[124:127], v[132:135], v[168:171], v[124:127]
	v_mfma_f32_16x16x32_bf16 v[120:123], v[140:143], v[168:171], v[120:123]
	v_mfma_f32_16x16x32_bf16 v[108:111], v[132:135], v[176:179], v[108:111]
	v_mfma_f32_16x16x32_bf16 v[104:107], v[140:143], v[176:179], v[104:107]
	v_mfma_f32_16x16x32_bf16 v[92:95], v[132:135], v[184:187], v[92:95]
	v_mfma_f32_16x16x32_bf16 v[88:91], v[140:143], v[184:187], v[88:91]
	v_mfma_f32_16x16x32_bf16 v[76:79], v[132:135], v[194:197], v[76:79]
	v_mfma_f32_16x16x32_bf16 v[72:75], v[140:143], v[194:197], v[72:75]
	v_mfma_f32_16x16x32_bf16 v[116:119], v[144:147], v[164:167], v[116:119]
	v_mfma_f32_16x16x32_bf16 v[112:115], v[152:155], v[164:167], v[112:115]
	v_mfma_f32_16x16x32_bf16 v[100:103], v[144:147], v[172:175], v[100:103]
	v_mfma_f32_16x16x32_bf16 v[96:99], v[152:155], v[172:175], v[96:99]
	v_mfma_f32_16x16x32_bf16 v[84:87], v[144:147], v[180:183], v[84:87]
	v_mfma_f32_16x16x32_bf16 v[80:83], v[152:155], v[180:183], v[80:83]
	v_mfma_f32_16x16x32_bf16 v[68:71], v[144:147], v[188:191], v[68:71]
	v_mfma_f32_16x16x32_bf16 v[64:67], v[152:155], v[188:191], v[64:67]
	v_mfma_f32_16x16x32_bf16 v[116:119], v[148:151], v[168:171], v[116:119]
	v_mfma_f32_16x16x32_bf16 v[112:115], v[160:163], v[168:171], v[112:115]
	v_mfma_f32_16x16x32_bf16 v[100:103], v[148:151], v[176:179], v[100:103]
	v_mfma_f32_16x16x32_bf16 v[96:99], v[160:163], v[176:179], v[96:99]
	v_mfma_f32_16x16x32_bf16 v[84:87], v[148:151], v[184:187], v[84:87]
	v_mfma_f32_16x16x32_bf16 v[80:83], v[160:163], v[184:187], v[80:83]
	v_mfma_f32_16x16x32_bf16 v[68:71], v[148:151], v[194:197], v[68:71]
	v_mfma_f32_16x16x32_bf16 v[64:67], v[160:163], v[194:197], v[64:67]
	s_setprio 0
	s_barrier
	ds_read_b128 v[164:167], v221 offset:49152
	ds_read_b128 v[168:171], v221 offset:50176
	ds_read_b128 v[172:175], v221 offset:51200
	ds_read_b128 v[176:179], v221 offset:52224
	ds_read_b128 v[180:183], v221 offset:53248
	ds_read_b128 v[184:187], v221 offset:54272
	ds_read_b128 v[188:191], v221 offset:55296
	ds_read_b128 v[194:197], v221 offset:56320
	s_add_u32 s10, s36, 0x80
	s_addc_u32 s11, s37, 0
	s_mov_b32 m0, s87
	s_nop 0
	global_load_lds_dwordx4 v209, s[10:11]
	s_mov_b32 m0, s83
	s_nop 0
	global_load_lds_dwordx4 v211, s[10:11]
	s_add_u32 s10, s36, 0x160080
	s_addc_u32 s11, s37, 0
	s_mov_b32 m0, s92
	s_nop 0
	global_load_lds_dwordx4 v209, s[10:11]
	s_mov_b32 m0, s93
	s_nop 0
	global_load_lds_dwordx4 v211, s[10:11]
	s_mov_b32 m0, s60
	s_nop 0
	global_load_lds_dwordx4 v208, s[34:35]
	s_mov_b32 m0, s89
	s_nop 0
	global_load_lds_dwordx4 v210, s[34:35]
	s_waitcnt vmcnt(8) lgkmcnt(0)
	s_setprio 1
	s_barrier
	v_mfma_f32_16x16x32_bf16 v[60:63], v[128:131], v[164:167], v[60:63]
	v_mfma_f32_16x16x32_bf16 v[56:59], v[136:139], v[164:167], v[56:59]
	v_mfma_f32_16x16x32_bf16 v[44:47], v[128:131], v[172:175], v[44:47]
	v_mfma_f32_16x16x32_bf16 v[40:43], v[136:139], v[172:175], v[40:43]
	v_mfma_f32_16x16x32_bf16 v[28:31], v[128:131], v[180:183], v[28:31]
	v_mfma_f32_16x16x32_bf16 v[24:27], v[136:139], v[180:183], v[24:27]
	v_mfma_f32_16x16x32_bf16 v[12:15], v[128:131], v[188:191], v[12:15]
	v_mfma_f32_16x16x32_bf16 v[8:11], v[136:139], v[188:191], v[8:11]
	v_mfma_f32_16x16x32_bf16 v[60:63], v[132:135], v[168:171], v[60:63]
	v_mfma_f32_16x16x32_bf16 v[56:59], v[140:143], v[168:171], v[56:59]
	v_mfma_f32_16x16x32_bf16 v[44:47], v[132:135], v[176:179], v[44:47]
	v_mfma_f32_16x16x32_bf16 v[40:43], v[140:143], v[176:179], v[40:43]
	v_mfma_f32_16x16x32_bf16 v[28:31], v[132:135], v[184:187], v[28:31]
	v_mfma_f32_16x16x32_bf16 v[24:27], v[140:143], v[184:187], v[24:27]
	v_mfma_f32_16x16x32_bf16 v[12:15], v[132:135], v[194:197], v[12:15]
	v_mfma_f32_16x16x32_bf16 v[8:11], v[140:143], v[194:197], v[8:11]
	v_mfma_f32_16x16x32_bf16 v[52:55], v[144:147], v[164:167], v[52:55]
	v_mfma_f32_16x16x32_bf16 v[48:51], v[152:155], v[164:167], v[48:51]
	v_mfma_f32_16x16x32_bf16 v[36:39], v[144:147], v[172:175], v[36:39]
	v_mfma_f32_16x16x32_bf16 v[32:35], v[152:155], v[172:175], v[32:35]
	v_mfma_f32_16x16x32_bf16 v[20:23], v[144:147], v[180:183], v[20:23]
	v_mfma_f32_16x16x32_bf16 v[16:19], v[152:155], v[180:183], v[16:19]
	v_mfma_f32_16x16x32_bf16 v[4:7], v[144:147], v[188:191], v[4:7]
	v_mfma_f32_16x16x32_bf16 v[0:3], v[152:155], v[188:191], v[0:3]
	v_mfma_f32_16x16x32_bf16 v[52:55], v[148:151], v[168:171], v[52:55]
	v_mfma_f32_16x16x32_bf16 v[48:51], v[160:163], v[168:171], v[48:51]
	v_mfma_f32_16x16x32_bf16 v[36:39], v[148:151], v[176:179], v[36:39]
	v_mfma_f32_16x16x32_bf16 v[32:35], v[160:163], v[176:179], v[32:35]
	v_mfma_f32_16x16x32_bf16 v[20:23], v[148:151], v[184:187], v[20:23]
	v_mfma_f32_16x16x32_bf16 v[16:19], v[160:163], v[184:187], v[16:19]
	v_mfma_f32_16x16x32_bf16 v[4:7], v[148:151], v[194:197], v[4:7]
	v_mfma_f32_16x16x32_bf16 v[0:3], v[160:163], v[194:197], v[0:3]
	s_setprio 0
	s_barrier
	s_add_u32 s85, s85, 0x100
	s_addc_u32 vcc_lo, vcc_lo, 0
	s_add_u32 s79, s79, 0x100
	s_addc_u32 s62, s62, 0
	s_add_u32 s30, s30, 0x100
	s_addc_u32 s31, s31, 0
	s_cmp_ge_i32 vcc_hi, s40
	s_mov_b32 s34, vcc_hi
	s_cbranch_scc0 .LBB0_1336
	s_mov_b32 s79, 0xc00000
	s_and_b64 vcc, exec, s[20:21]
	s_cbranch_vccz .LBB0_1339
